# gated-delta forward substitution with packed f32 FMAs (two rows per v_pk_fma_f32, same per-row operation order), L stored as row pairs in LDS
# speedup vs baseline: 1.0033x; 1.0003x over previous
.LBB0_312:
	s_or_b64 exec, exec, s[66:67]
	v_lshrrev_b32_e32 v241, 1, v26
	v_and_b32_e32 v242, 1, v26
	v_lshlrev_b32_e32 v241, 9, v241
	v_lshl_add_u32 v241, v242, 2, v241
	v_lshl_add_u32 v16, v25, 1, v241
	ds_write_b32 v16, v27 offset:52224

.LBB0_318:
	s_or_b64 exec, exec, s[66:67]
	v_lshrrev_b32_e32 v241, 1, v29
	v_and_b32_e32 v242, 1, v29
	v_lshlrev_b32_e32 v241, 9, v241
	v_lshl_add_u32 v241, v242, 2, v241
	v_lshl_add_u32 v17, v25, 1, v241
	ds_write_b32 v17, v16 offset:52224

.LBB0_324:
	s_or_b64 exec, exec, s[66:67]
	v_lshrrev_b32_e32 v241, 1, v28
	v_and_b32_e32 v242, 1, v28
	v_lshlrev_b32_e32 v241, 9, v241
	v_lshl_add_u32 v241, v242, 2, v241
	v_lshl_add_u32 v17, v25, 1, v241
	ds_write_b32 v17, v16 offset:52224

.LBB0_330:
	s_or_b64 exec, exec, s[66:67]
	v_lshrrev_b32_e32 v241, 1, v27
	v_and_b32_e32 v242, 1, v27
	v_lshlrev_b32_e32 v241, 9, v241
	v_lshl_add_u32 v241, v242, 2, v241
	v_lshl_add_u32 v17, v25, 1, v241
	ds_write_b32 v17, v16 offset:52224

.LBB0_336:
	s_or_b64 exec, exec, s[66:67]
	v_lshrrev_b32_e32 v241, 1, v26
	v_and_b32_e32 v242, 1, v26
	v_lshlrev_b32_e32 v241, 9, v241
	v_lshl_add_u32 v241, v242, 2, v241
	v_lshl_add_u32 v16, v25, 1, v241
	ds_write_b32 v16, v44 offset:52352

.LBB0_352:
	s_or_b64 exec, exec, s[66:67]
	v_lshrrev_b32_e32 v241, 1, v29
	v_and_b32_e32 v242, 1, v29
	v_lshlrev_b32_e32 v241, 9, v241
	v_lshl_add_u32 v241, v242, 2, v241
	v_lshl_add_u32 v17, v25, 1, v241
	ds_write_b32 v17, v16 offset:52352
	s_or_b64 exec, exec, s[12:13]
	s_and_saveexec_b64 s[0:1], vcc
	s_xor_b64 s[12:13], exec, s[0:1]
	s_cbranch_execz .LBB0_340

.LBB0_356:
	s_or_b64 exec, exec, s[66:67]
	v_lshrrev_b32_e32 v241, 1, v28
	v_and_b32_e32 v242, 1, v28
	v_lshlrev_b32_e32 v241, 9, v241
	v_lshl_add_u32 v241, v242, 2, v241
	v_lshl_add_u32 v17, v25, 1, v241
	ds_write_b32 v17, v16 offset:52352
	s_or_b64 exec, exec, s[12:13]
	s_and_saveexec_b64 s[0:1], vcc
	s_xor_b64 s[12:13], exec, s[0:1]
	s_cbranch_execz .LBB0_342

.LBB0_360:
	s_or_b64 exec, exec, s[66:67]
	v_lshrrev_b32_e32 v241, 1, v27
	v_and_b32_e32 v242, 1, v27
	v_lshlrev_b32_e32 v241, 9, v241
	v_lshl_add_u32 v241, v242, 2, v241
	v_lshl_add_u32 v17, v25, 1, v241
	ds_write_b32 v17, v16 offset:52352

.LBB0_372:
	s_or_b64 exec, exec, s[66:67]
	v_lshrrev_b32_e32 v241, 1, v26
	v_and_b32_e32 v242, 1, v26
	v_lshlrev_b32_e32 v241, 9, v241
	v_lshl_add_u32 v241, v242, 2, v241
	v_lshl_add_u32 v16, v25, 1, v241
	ds_write_b32 v16, v44 offset:52480
	s_or_b64 exec, exec, s[12:13]
	s_and_saveexec_b64 s[0:1], vcc
	s_xor_b64 s[12:13], exec, s[0:1]
	s_cbranch_execz .LBB0_364

.LBB0_376:
	s_or_b64 exec, exec, s[66:67]
	v_lshrrev_b32_e32 v241, 1, v29
	v_and_b32_e32 v242, 1, v29
	v_lshlrev_b32_e32 v241, 9, v241
	v_lshl_add_u32 v241, v242, 2, v241
	v_lshl_add_u32 v17, v25, 1, v241
	ds_write_b32 v17, v16 offset:52480
	s_or_b64 exec, exec, s[12:13]
	s_and_saveexec_b64 s[0:1], vcc
	s_xor_b64 s[12:13], exec, s[0:1]
	s_cbranch_execz .LBB0_366

.LBB0_380:
	s_or_b64 exec, exec, s[66:67]
	v_lshrrev_b32_e32 v241, 1, v28
	v_and_b32_e32 v242, 1, v28
	v_lshlrev_b32_e32 v241, 9, v241
	v_lshl_add_u32 v241, v242, 2, v241
	v_lshl_add_u32 v17, v25, 1, v241
	ds_write_b32 v17, v16 offset:52480
	s_or_b64 exec, exec, s[12:13]
	s_and_saveexec_b64 s[0:1], vcc
	s_xor_b64 s[12:13], exec, s[0:1]
	s_cbranch_execz .LBB0_368

.LBB0_384:
	s_or_b64 exec, exec, s[66:67]
	v_lshrrev_b32_e32 v241, 1, v27
	v_and_b32_e32 v242, 1, v27
	v_lshlrev_b32_e32 v241, 9, v241
	v_lshl_add_u32 v241, v242, 2, v241
	v_lshl_add_u32 v17, v25, 1, v241
	ds_write_b32 v17, v16 offset:52480

.LBB0_396:
	s_or_b64 exec, exec, s[66:67]
	v_lshrrev_b32_e32 v241, 1, v26
	v_and_b32_e32 v242, 1, v26
	v_lshlrev_b32_e32 v241, 9, v241
	v_lshl_add_u32 v241, v242, 2, v241
	v_lshl_add_u32 v0, v25, 1, v241
	ds_write_b32 v0, v5 offset:52608
	s_or_b64 exec, exec, s[12:13]
	s_and_saveexec_b64 s[0:1], vcc
	s_xor_b64 s[12:13], exec, s[0:1]
	s_cbranch_execz .LBB0_388

.LBB0_400:
	s_or_b64 exec, exec, s[66:67]
	v_lshrrev_b32_e32 v241, 1, v29
	v_and_b32_e32 v242, 1, v29
	v_lshlrev_b32_e32 v241, 9, v241
	v_lshl_add_u32 v241, v242, 2, v241
	v_lshl_add_u32 v1, v25, 1, v241
	ds_write_b32 v1, v0 offset:52608
	s_or_b64 exec, exec, s[12:13]
	s_and_saveexec_b64 s[0:1], vcc
	s_xor_b64 s[12:13], exec, s[0:1]
	s_cbranch_execz .LBB0_390

.LBB0_404:
	s_or_b64 exec, exec, s[66:67]
	v_lshrrev_b32_e32 v241, 1, v28
	v_and_b32_e32 v242, 1, v28
	v_lshlrev_b32_e32 v241, 9, v241
	v_lshl_add_u32 v241, v242, 2, v241
	v_lshl_add_u32 v1, v25, 1, v241
	ds_write_b32 v1, v0 offset:52608
	s_or_b64 exec, exec, s[12:13]
	s_and_saveexec_b64 s[0:1], vcc
	s_xor_b64 s[0:1], exec, s[0:1]
	s_cbranch_execz .LBB0_392

.LBB0_408:
	s_or_b64 exec, exec, s[6:7]
	v_lshrrev_b32_e32 v241, 1, v27
	v_and_b32_e32 v242, 1, v27
	v_lshlrev_b32_e32 v241, 9, v241
	v_lshl_add_u32 v241, v242, 2, v241
	v_lshl_add_u32 v1, v25, 1, v241
	ds_write_b32 v1, v0 offset:52608

.LBB0_416:
	s_andn2_saveexec_b64 s[6:7], s[6:7]
	s_cbranch_execz .LBB0_284
	v_cmp_gt_i32_e64 s[0:1], s96, v77
	v_add_u32_e32 v39, 0xffffff80, v77
	v_cmp_lt_i32_e32 vcc, s93, v77
	v_cndmask_b32_e64 v0, v65, v74, s[0:1]
	v_cndmask_b32_e64 v1, v39, v77, s[0:1]
	v_lshl_add_u32 v0, v1, 1, v0
	v_cndmask_b32_e64 v1, v75, v76, s[0:1]
	s_nop 0
	v_add_u32_e32 v11, 0, v1
	v_add_u32_e32 v10, 0, v0
	ds_read_b128 v[24:27], v11 offset:0
	ds_read_b128 v[28:31], v11 offset:16
	ds_read_u16 v0, v10 offset:0
	ds_read_u16 v1, v10 offset:272
	ds_read_u16 v2, v10 offset:544
	ds_read_u16 v3, v10 offset:816
	ds_read_u16 v4, v10 offset:1088
	ds_read_u16 v5, v10 offset:1360
	ds_read_u16 v6, v10 offset:1632
	ds_read_u16 v7, v10 offset:1904
	ds_read_b128 v[40:43], v11 offset:32
	ds_read_b128 v[44:47], v11 offset:48
	ds_read_u16 v80, v10 offset:2176
	ds_read_u16 v81, v10 offset:2448
	ds_read_u16 v82, v10 offset:2720
	ds_read_u16 v83, v10 offset:2992
	ds_read_u16 v84, v10 offset:3264
	ds_read_u16 v85, v10 offset:3536
	ds_read_u16 v86, v10 offset:3808
	ds_read_u16 v87, v10 offset:4080
	s_waitcnt lgkmcnt(10)
	v_lshlrev_b32_e32 v0, 16, v0
	v_lshlrev_b32_e32 v1, 16, v1
	v_lshlrev_b32_e32 v2, 16, v2
	v_lshlrev_b32_e32 v3, 16, v3
	v_lshlrev_b32_e32 v4, 16, v4
	v_lshlrev_b32_e32 v5, 16, v5
	v_lshlrev_b32_e32 v6, 16, v6
	v_lshlrev_b32_e32 v7, 16, v7
	v_pk_mul_f32 v[100:101], v[24:25], v[0:1]
	v_pk_mul_f32 v[102:103], v[26:27], v[2:3]
	v_pk_mul_f32 v[104:105], v[28:29], v[4:5]
	v_pk_mul_f32 v[106:107], v[30:31], v[6:7]
	ds_read_b128 v[24:27], v11 offset:64
	ds_read_b128 v[28:31], v11 offset:80
	ds_read_u16 v0, v10 offset:4352
	ds_read_u16 v1, v10 offset:4624
	ds_read_u16 v2, v10 offset:4896
	ds_read_u16 v3, v10 offset:5168
	ds_read_u16 v4, v10 offset:5440
	ds_read_u16 v5, v10 offset:5712
	ds_read_u16 v6, v10 offset:5984
	ds_read_u16 v7, v10 offset:6256
	s_waitcnt lgkmcnt(10)
	v_lshlrev_b32_e32 v80, 16, v80
	v_lshlrev_b32_e32 v81, 16, v81
	v_lshlrev_b32_e32 v82, 16, v82
	v_lshlrev_b32_e32 v83, 16, v83
	v_lshlrev_b32_e32 v84, 16, v84
	v_lshlrev_b32_e32 v85, 16, v85
	v_lshlrev_b32_e32 v86, 16, v86
	v_lshlrev_b32_e32 v87, 16, v87
	v_pk_mul_f32 v[108:109], v[40:41], v[80:81]
	v_pk_mul_f32 v[110:111], v[42:43], v[82:83]
	v_pk_mul_f32 v[112:113], v[44:45], v[84:85]
	v_pk_mul_f32 v[114:115], v[46:47], v[86:87]
	ds_read_b128 v[40:43], v11 offset:96
	ds_read_b128 v[44:47], v11 offset:112
	ds_read_u16 v80, v10 offset:6528
	ds_read_u16 v81, v10 offset:6800
	ds_read_u16 v82, v10 offset:7072
	ds_read_u16 v83, v10 offset:7344
	ds_read_u16 v84, v10 offset:7616
	ds_read_u16 v85, v10 offset:7888
	ds_read_u16 v86, v10 offset:8160
	ds_read_u16 v87, v10 offset:8432
	s_waitcnt lgkmcnt(10)
	v_lshlrev_b32_e32 v0, 16, v0
	v_lshlrev_b32_e32 v1, 16, v1
	v_lshlrev_b32_e32 v2, 16, v2
	v_lshlrev_b32_e32 v3, 16, v3
	v_lshlrev_b32_e32 v4, 16, v4
	v_lshlrev_b32_e32 v5, 16, v5
	v_lshlrev_b32_e32 v6, 16, v6
	v_lshlrev_b32_e32 v7, 16, v7
	v_pk_mul_f32 v[116:117], v[24:25], v[0:1]
	v_pk_mul_f32 v[118:119], v[26:27], v[2:3]
	v_pk_mul_f32 v[120:121], v[28:29], v[4:5]
	v_pk_mul_f32 v[122:123], v[30:31], v[6:7]
	ds_read_b128 v[24:27], v11 offset:128
	ds_read_b128 v[28:31], v11 offset:144
	ds_read_u16 v0, v10 offset:8704
	ds_read_u16 v1, v10 offset:8976
	ds_read_u16 v2, v10 offset:9248
	ds_read_u16 v3, v10 offset:9520
	ds_read_u16 v4, v10 offset:9792
	ds_read_u16 v5, v10 offset:10064
	ds_read_u16 v6, v10 offset:10336
	ds_read_u16 v7, v10 offset:10608
	s_waitcnt lgkmcnt(10)
	v_lshlrev_b32_e32 v80, 16, v80
	v_lshlrev_b32_e32 v81, 16, v81
	v_lshlrev_b32_e32 v82, 16, v82
	v_lshlrev_b32_e32 v83, 16, v83
	v_lshlrev_b32_e32 v84, 16, v84
	v_lshlrev_b32_e32 v85, 16, v85
	v_lshlrev_b32_e32 v86, 16, v86
	v_lshlrev_b32_e32 v87, 16, v87
	v_pk_mul_f32 v[124:125], v[40:41], v[80:81]
	v_pk_mul_f32 v[126:127], v[42:43], v[82:83]
	v_pk_mul_f32 v[128:129], v[44:45], v[84:85]
	v_pk_mul_f32 v[130:131], v[46:47], v[86:87]
	ds_read_b128 v[40:43], v11 offset:160
	ds_read_b128 v[44:47], v11 offset:176
	ds_read_u16 v80, v10 offset:10880
	ds_read_u16 v81, v10 offset:11152
	ds_read_u16 v82, v10 offset:11424
	ds_read_u16 v83, v10 offset:11696
	ds_read_u16 v84, v10 offset:11968
	ds_read_u16 v85, v10 offset:12240
	ds_read_u16 v86, v10 offset:12512
	ds_read_u16 v87, v10 offset:12784
	s_waitcnt lgkmcnt(10)
	v_lshlrev_b32_e32 v0, 16, v0
	v_lshlrev_b32_e32 v1, 16, v1
	v_lshlrev_b32_e32 v2, 16, v2
	v_lshlrev_b32_e32 v3, 16, v3
	v_lshlrev_b32_e32 v4, 16, v4
	v_lshlrev_b32_e32 v5, 16, v5
	v_lshlrev_b32_e32 v6, 16, v6
	v_lshlrev_b32_e32 v7, 16, v7
	v_pk_mul_f32 v[132:133], v[24:25], v[0:1]
	v_pk_mul_f32 v[134:135], v[26:27], v[2:3]
	v_pk_mul_f32 v[136:137], v[28:29], v[4:5]
	v_pk_mul_f32 v[138:139], v[30:31], v[6:7]
	ds_read_b128 v[24:27], v11 offset:192
	ds_read_b128 v[28:31], v11 offset:208
	ds_read_u16 v0, v10 offset:13056
	ds_read_u16 v1, v10 offset:13328
	ds_read_u16 v2, v10 offset:13600
	ds_read_u16 v3, v10 offset:13872
	ds_read_u16 v4, v10 offset:14144
	ds_read_u16 v5, v10 offset:14416
	ds_read_u16 v6, v10 offset:14688
	ds_read_u16 v7, v10 offset:14960
	s_waitcnt lgkmcnt(10)
	v_lshlrev_b32_e32 v80, 16, v80
	v_lshlrev_b32_e32 v81, 16, v81
	v_lshlrev_b32_e32 v82, 16, v82
	v_lshlrev_b32_e32 v83, 16, v83
	v_lshlrev_b32_e32 v84, 16, v84
	v_lshlrev_b32_e32 v85, 16, v85
	v_lshlrev_b32_e32 v86, 16, v86
	v_lshlrev_b32_e32 v87, 16, v87
	v_pk_mul_f32 v[140:141], v[40:41], v[80:81]
	v_pk_mul_f32 v[142:143], v[42:43], v[82:83]
	v_pk_mul_f32 v[144:145], v[44:45], v[84:85]
	v_pk_mul_f32 v[146:147], v[46:47], v[86:87]
	ds_read_b128 v[40:43], v11 offset:224
	ds_read_b128 v[44:47], v11 offset:240
	ds_read_u16 v80, v10 offset:15232
	ds_read_u16 v81, v10 offset:15504
	ds_read_u16 v82, v10 offset:15776
	ds_read_u16 v83, v10 offset:16048
	ds_read_u16 v84, v10 offset:16320
	ds_read_u16 v85, v10 offset:16592
	ds_read_u16 v86, v10 offset:16864
	ds_read_u16 v87, v10 offset:17136
	s_waitcnt lgkmcnt(10)
	v_lshlrev_b32_e32 v0, 16, v0
	v_lshlrev_b32_e32 v1, 16, v1
	v_lshlrev_b32_e32 v2, 16, v2
	v_lshlrev_b32_e32 v3, 16, v3
	v_lshlrev_b32_e32 v4, 16, v4
	v_lshlrev_b32_e32 v5, 16, v5
	v_lshlrev_b32_e32 v6, 16, v6
	v_lshlrev_b32_e32 v7, 16, v7
	v_pk_mul_f32 v[148:149], v[24:25], v[0:1]
	v_pk_mul_f32 v[150:151], v[26:27], v[2:3]
	v_pk_mul_f32 v[152:153], v[28:29], v[4:5]
	v_pk_mul_f32 v[154:155], v[30:31], v[6:7]
	s_waitcnt lgkmcnt(0)
	v_lshlrev_b32_e32 v80, 16, v80
	v_lshlrev_b32_e32 v81, 16, v81
	v_lshlrev_b32_e32 v82, 16, v82
	v_lshlrev_b32_e32 v83, 16, v83
	v_lshlrev_b32_e32 v84, 16, v84
	v_lshlrev_b32_e32 v85, 16, v85
	v_lshlrev_b32_e32 v86, 16, v86
	v_lshlrev_b32_e32 v87, 16, v87
	v_pk_mul_f32 v[156:157], v[40:41], v[80:81]
	v_pk_mul_f32 v[158:159], v[42:43], v[82:83]
	v_pk_mul_f32 v[160:161], v[44:45], v[84:85]
	v_pk_mul_f32 v[162:163], v[46:47], v[86:87]
	v_mov_b32_e32 v228, 0xcc00
	ds_read_b128 v[164:167], v228 offset:0
	ds_read_b128 v[168:171], v228 offset:512
	ds_read_b128 v[172:175], v228 offset:528
	ds_read_b128 v[176:179], v228 offset:1024
	ds_read_b128 v[180:183], v228 offset:1040
	ds_read_b128 v[184:187], v228 offset:1056
	ds_read_b128 v[188:191], v228 offset:1536
	ds_read_b128 v[192:195], v228 offset:1552
	ds_read_b128 v[196:199], v228 offset:1568
	ds_read_b128 v[200:203], v228 offset:1584
	ds_read_b128 v[204:207], v228 offset:2048
	ds_read_b128 v[208:211], v228 offset:2064
	ds_read_b128 v[212:215], v228 offset:2080
	ds_read_b128 v[216:219], v228 offset:2096
	ds_read_b128 v[220:223], v228 offset:2112
	ds_read_b128 v[224:227], v228 offset:2560
	s_waitcnt lgkmcnt(14)
	v_fma_f32 v101, -v165, v100, v101
	v_pk_fma_f32 v[102:103], v[168:169], v[100:101], v[102:103] op_sel_hi:[1,0,1] neg_lo:[1,0,0] neg_hi:[1,0,0]
	v_pk_fma_f32 v[102:103], v[170:171], v[100:101], v[102:103] op_sel:[0,1,0] neg_lo:[1,0,0] neg_hi:[1,0,0]
	ds_read_b128 v[164:167], v228 offset:2576
	ds_read_b128 v[168:171], v228 offset:2592
	s_waitcnt lgkmcnt(14)
	v_fma_f32 v103, -v173, v102, v103
	v_pk_fma_f32 v[104:105], v[176:177], v[100:101], v[104:105] op_sel_hi:[1,0,1] neg_lo:[1,0,0] neg_hi:[1,0,0]
	v_pk_fma_f32 v[104:105], v[178:179], v[100:101], v[104:105] op_sel:[0,1,0] neg_lo:[1,0,0] neg_hi:[1,0,0]
	ds_read_b128 v[172:175], v228 offset:2608
	ds_read_b128 v[176:179], v228 offset:2624
	s_waitcnt lgkmcnt(14)
	v_pk_fma_f32 v[104:105], v[180:181], v[102:103], v[104:105] op_sel_hi:[1,0,1] neg_lo:[1,0,0] neg_hi:[1,0,0]
	v_pk_fma_f32 v[104:105], v[182:183], v[102:103], v[104:105] op_sel:[0,1,0] neg_lo:[1,0,0] neg_hi:[1,0,0]
	v_fma_f32 v105, -v185, v104, v105
	ds_read_b128 v[180:183], v228 offset:2640
	ds_read_b128 v[184:187], v228 offset:3072
	s_waitcnt lgkmcnt(14)
	v_pk_fma_f32 v[106:107], v[188:189], v[100:101], v[106:107] op_sel_hi:[1,0,1] neg_lo:[1,0,0] neg_hi:[1,0,0]
	v_pk_fma_f32 v[106:107], v[190:191], v[100:101], v[106:107] op_sel:[0,1,0] neg_lo:[1,0,0] neg_hi:[1,0,0]
	v_pk_fma_f32 v[106:107], v[192:193], v[102:103], v[106:107] op_sel_hi:[1,0,1] neg_lo:[1,0,0] neg_hi:[1,0,0]
	v_pk_fma_f32 v[106:107], v[194:195], v[102:103], v[106:107] op_sel:[0,1,0] neg_lo:[1,0,0] neg_hi:[1,0,0]
	ds_read_b128 v[188:191], v228 offset:3088
	ds_read_b128 v[192:195], v228 offset:3104
	s_waitcnt lgkmcnt(14)
	v_pk_fma_f32 v[106:107], v[196:197], v[104:105], v[106:107] op_sel_hi:[1,0,1] neg_lo:[1,0,0] neg_hi:[1,0,0]
	v_pk_fma_f32 v[106:107], v[198:199], v[104:105], v[106:107] op_sel:[0,1,0] neg_lo:[1,0,0] neg_hi:[1,0,0]
	v_fma_f32 v107, -v201, v106, v107
	ds_read_b128 v[196:199], v228 offset:3120
	ds_read_b128 v[200:203], v228 offset:3136
	s_waitcnt lgkmcnt(14)
	v_pk_fma_f32 v[108:109], v[204:205], v[100:101], v[108:109] op_sel_hi:[1,0,1] neg_lo:[1,0,0] neg_hi:[1,0,0]
	v_pk_fma_f32 v[108:109], v[206:207], v[100:101], v[108:109] op_sel:[0,1,0] neg_lo:[1,0,0] neg_hi:[1,0,0]
	v_pk_fma_f32 v[108:109], v[208:209], v[102:103], v[108:109] op_sel_hi:[1,0,1] neg_lo:[1,0,0] neg_hi:[1,0,0]
	v_pk_fma_f32 v[108:109], v[210:211], v[102:103], v[108:109] op_sel:[0,1,0] neg_lo:[1,0,0] neg_hi:[1,0,0]
	ds_read_b128 v[204:207], v228 offset:3152
	ds_read_b128 v[208:211], v228 offset:3168
	s_waitcnt lgkmcnt(14)
	v_pk_fma_f32 v[108:109], v[212:213], v[104:105], v[108:109] op_sel_hi:[1,0,1] neg_lo:[1,0,0] neg_hi:[1,0,0]
	v_pk_fma_f32 v[108:109], v[214:215], v[104:105], v[108:109] op_sel:[0,1,0] neg_lo:[1,0,0] neg_hi:[1,0,0]
	v_pk_fma_f32 v[108:109], v[216:217], v[106:107], v[108:109] op_sel_hi:[1,0,1] neg_lo:[1,0,0] neg_hi:[1,0,0]
	v_pk_fma_f32 v[108:109], v[218:219], v[106:107], v[108:109] op_sel:[0,1,0] neg_lo:[1,0,0] neg_hi:[1,0,0]
	ds_read_b128 v[212:215], v228 offset:3584
	ds_read_b128 v[216:219], v228 offset:3600
	s_waitcnt lgkmcnt(14)
	v_fma_f32 v109, -v221, v108, v109
	v_pk_fma_f32 v[110:111], v[224:225], v[100:101], v[110:111] op_sel_hi:[1,0,1] neg_lo:[1,0,0] neg_hi:[1,0,0]
	v_pk_fma_f32 v[110:111], v[226:227], v[100:101], v[110:111] op_sel:[0,1,0] neg_lo:[1,0,0] neg_hi:[1,0,0]
	ds_read_b128 v[220:223], v228 offset:3616
	ds_read_b128 v[224:227], v228 offset:3632
	s_waitcnt lgkmcnt(14)
	v_pk_fma_f32 v[110:111], v[164:165], v[102:103], v[110:111] op_sel_hi:[1,0,1] neg_lo:[1,0,0] neg_hi:[1,0,0]
	v_pk_fma_f32 v[110:111], v[166:167], v[102:103], v[110:111] op_sel:[0,1,0] neg_lo:[1,0,0] neg_hi:[1,0,0]
	v_pk_fma_f32 v[110:111], v[168:169], v[104:105], v[110:111] op_sel_hi:[1,0,1] neg_lo:[1,0,0] neg_hi:[1,0,0]
	v_pk_fma_f32 v[110:111], v[170:171], v[104:105], v[110:111] op_sel:[0,1,0] neg_lo:[1,0,0] neg_hi:[1,0,0]
	ds_read_b128 v[164:167], v228 offset:3648
	ds_read_b128 v[168:171], v228 offset:3664
	s_waitcnt lgkmcnt(14)
	v_pk_fma_f32 v[110:111], v[172:173], v[106:107], v[110:111] op_sel_hi:[1,0,1] neg_lo:[1,0,0] neg_hi:[1,0,0]
	v_pk_fma_f32 v[110:111], v[174:175], v[106:107], v[110:111] op_sel:[0,1,0] neg_lo:[1,0,0] neg_hi:[1,0,0]
	v_pk_fma_f32 v[110:111], v[176:177], v[108:109], v[110:111] op_sel_hi:[1,0,1] neg_lo:[1,0,0] neg_hi:[1,0,0]
	v_pk_fma_f32 v[110:111], v[178:179], v[108:109], v[110:111] op_sel:[0,1,0] neg_lo:[1,0,0] neg_hi:[1,0,0]
	ds_read_b128 v[172:175], v228 offset:3680
	ds_read_b128 v[176:179], v228 offset:3696
	s_waitcnt lgkmcnt(14)
	v_fma_f32 v111, -v181, v110, v111
	v_pk_fma_f32 v[112:113], v[184:185], v[100:101], v[112:113] op_sel_hi:[1,0,1] neg_lo:[1,0,0] neg_hi:[1,0,0]
	v_pk_fma_f32 v[112:113], v[186:187], v[100:101], v[112:113] op_sel:[0,1,0] neg_lo:[1,0,0] neg_hi:[1,0,0]
	ds_read_b128 v[180:183], v228 offset:4096
	ds_read_b128 v[184:187], v228 offset:4112
	s_waitcnt lgkmcnt(14)
	v_pk_fma_f32 v[112:113], v[188:189], v[102:103], v[112:113] op_sel_hi:[1,0,1] neg_lo:[1,0,0] neg_hi:[1,0,0]
	v_pk_fma_f32 v[112:113], v[190:191], v[102:103], v[112:113] op_sel:[0,1,0] neg_lo:[1,0,0] neg_hi:[1,0,0]
	v_pk_fma_f32 v[112:113], v[192:193], v[104:105], v[112:113] op_sel_hi:[1,0,1] neg_lo:[1,0,0] neg_hi:[1,0,0]
	v_pk_fma_f32 v[112:113], v[194:195], v[104:105], v[112:113] op_sel:[0,1,0] neg_lo:[1,0,0] neg_hi:[1,0,0]
	ds_read_b128 v[188:191], v228 offset:4128
	ds_read_b128 v[192:195], v228 offset:4144
	s_waitcnt lgkmcnt(14)
	v_pk_fma_f32 v[112:113], v[196:197], v[106:107], v[112:113] op_sel_hi:[1,0,1] neg_lo:[1,0,0] neg_hi:[1,0,0]
	v_pk_fma_f32 v[112:113], v[198:199], v[106:107], v[112:113] op_sel:[0,1,0] neg_lo:[1,0,0] neg_hi:[1,0,0]
	v_pk_fma_f32 v[112:113], v[200:201], v[108:109], v[112:113] op_sel_hi:[1,0,1] neg_lo:[1,0,0] neg_hi:[1,0,0]
	v_pk_fma_f32 v[112:113], v[202:203], v[108:109], v[112:113] op_sel:[0,1,0] neg_lo:[1,0,0] neg_hi:[1,0,0]
	ds_read_b128 v[196:199], v228 offset:4160
	ds_read_b128 v[200:203], v228 offset:4176
	s_waitcnt lgkmcnt(14)
	v_pk_fma_f32 v[112:113], v[204:205], v[110:111], v[112:113] op_sel_hi:[1,0,1] neg_lo:[1,0,0] neg_hi:[1,0,0]
	v_pk_fma_f32 v[112:113], v[206:207], v[110:111], v[112:113] op_sel:[0,1,0] neg_lo:[1,0,0] neg_hi:[1,0,0]
	v_fma_f32 v113, -v209, v112, v113
	ds_read_b128 v[204:207], v228 offset:4192
	ds_read_b128 v[208:211], v228 offset:4208
	s_waitcnt lgkmcnt(14)
	v_pk_fma_f32 v[114:115], v[212:213], v[100:101], v[114:115] op_sel_hi:[1,0,1] neg_lo:[1,0,0] neg_hi:[1,0,0]
	v_pk_fma_f32 v[114:115], v[214:215], v[100:101], v[114:115] op_sel:[0,1,0] neg_lo:[1,0,0] neg_hi:[1,0,0]
	v_pk_fma_f32 v[114:115], v[216:217], v[102:103], v[114:115] op_sel_hi:[1,0,1] neg_lo:[1,0,0] neg_hi:[1,0,0]
	v_pk_fma_f32 v[114:115], v[218:219], v[102:103], v[114:115] op_sel:[0,1,0] neg_lo:[1,0,0] neg_hi:[1,0,0]
	ds_read_b128 v[212:215], v228 offset:4224
	ds_read_b128 v[216:219], v228 offset:4608
	s_waitcnt lgkmcnt(14)
	v_pk_fma_f32 v[114:115], v[220:221], v[104:105], v[114:115] op_sel_hi:[1,0,1] neg_lo:[1,0,0] neg_hi:[1,0,0]
	v_pk_fma_f32 v[114:115], v[222:223], v[104:105], v[114:115] op_sel:[0,1,0] neg_lo:[1,0,0] neg_hi:[1,0,0]
	v_pk_fma_f32 v[114:115], v[224:225], v[106:107], v[114:115] op_sel_hi:[1,0,1] neg_lo:[1,0,0] neg_hi:[1,0,0]
	v_pk_fma_f32 v[114:115], v[226:227], v[106:107], v[114:115] op_sel:[0,1,0] neg_lo:[1,0,0] neg_hi:[1,0,0]
	ds_read_b128 v[220:223], v228 offset:4624
	ds_read_b128 v[224:227], v228 offset:4640
	s_waitcnt lgkmcnt(14)
	v_pk_fma_f32 v[114:115], v[164:165], v[108:109], v[114:115] op_sel_hi:[1,0,1] neg_lo:[1,0,0] neg_hi:[1,0,0]
	v_pk_fma_f32 v[114:115], v[166:167], v[108:109], v[114:115] op_sel:[0,1,0] neg_lo:[1,0,0] neg_hi:[1,0,0]
	v_pk_fma_f32 v[114:115], v[168:169], v[110:111], v[114:115] op_sel_hi:[1,0,1] neg_lo:[1,0,0] neg_hi:[1,0,0]
	v_pk_fma_f32 v[114:115], v[170:171], v[110:111], v[114:115] op_sel:[0,1,0] neg_lo:[1,0,0] neg_hi:[1,0,0]
	ds_read_b128 v[164:167], v228 offset:4656
	ds_read_b128 v[168:171], v228 offset:4672
	s_waitcnt lgkmcnt(14)
	v_pk_fma_f32 v[114:115], v[172:173], v[112:113], v[114:115] op_sel_hi:[1,0,1] neg_lo:[1,0,0] neg_hi:[1,0,0]
	v_pk_fma_f32 v[114:115], v[174:175], v[112:113], v[114:115] op_sel:[0,1,0] neg_lo:[1,0,0] neg_hi:[1,0,0]
	v_fma_f32 v115, -v177, v114, v115
	ds_read_b128 v[172:175], v228 offset:4688
	ds_read_b128 v[176:179], v228 offset:4704
	s_waitcnt lgkmcnt(14)
	v_pk_fma_f32 v[116:117], v[180:181], v[100:101], v[116:117] op_sel_hi:[1,0,1] neg_lo:[1,0,0] neg_hi:[1,0,0]
	v_pk_fma_f32 v[116:117], v[182:183], v[100:101], v[116:117] op_sel:[0,1,0] neg_lo:[1,0,0] neg_hi:[1,0,0]
	v_pk_fma_f32 v[116:117], v[184:185], v[102:103], v[116:117] op_sel_hi:[1,0,1] neg_lo:[1,0,0] neg_hi:[1,0,0]
	v_pk_fma_f32 v[116:117], v[186:187], v[102:103], v[116:117] op_sel:[0,1,0] neg_lo:[1,0,0] neg_hi:[1,0,0]
	ds_read_b128 v[180:183], v228 offset:4720
	ds_read_b128 v[184:187], v228 offset:4736
	s_waitcnt lgkmcnt(14)
	v_pk_fma_f32 v[116:117], v[188:189], v[104:105], v[116:117] op_sel_hi:[1,0,1] neg_lo:[1,0,0] neg_hi:[1,0,0]
	v_pk_fma_f32 v[116:117], v[190:191], v[104:105], v[116:117] op_sel:[0,1,0] neg_lo:[1,0,0] neg_hi:[1,0,0]
	v_pk_fma_f32 v[116:117], v[192:193], v[106:107], v[116:117] op_sel_hi:[1,0,1] neg_lo:[1,0,0] neg_hi:[1,0,0]
	v_pk_fma_f32 v[116:117], v[194:195], v[106:107], v[116:117] op_sel:[0,1,0] neg_lo:[1,0,0] neg_hi:[1,0,0]
	ds_read_b128 v[188:191], v228 offset:4752
	ds_read_b128 v[192:195], v228 offset:5120
	s_waitcnt lgkmcnt(14)
	v_pk_fma_f32 v[116:117], v[196:197], v[108:109], v[116:117] op_sel_hi:[1,0,1] neg_lo:[1,0,0] neg_hi:[1,0,0]
	v_pk_fma_f32 v[116:117], v[198:199], v[108:109], v[116:117] op_sel:[0,1,0] neg_lo:[1,0,0] neg_hi:[1,0,0]
	v_pk_fma_f32 v[116:117], v[200:201], v[110:111], v[116:117] op_sel_hi:[1,0,1] neg_lo:[1,0,0] neg_hi:[1,0,0]
	v_pk_fma_f32 v[116:117], v[202:203], v[110:111], v[116:117] op_sel:[0,1,0] neg_lo:[1,0,0] neg_hi:[1,0,0]
	ds_read_b128 v[196:199], v228 offset:5136
	ds_read_b128 v[200:203], v228 offset:5152
	s_waitcnt lgkmcnt(14)
	v_pk_fma_f32 v[116:117], v[204:205], v[112:113], v[116:117] op_sel_hi:[1,0,1] neg_lo:[1,0,0] neg_hi:[1,0,0]
	v_pk_fma_f32 v[116:117], v[206:207], v[112:113], v[116:117] op_sel:[0,1,0] neg_lo:[1,0,0] neg_hi:[1,0,0]
	v_pk_fma_f32 v[116:117], v[208:209], v[114:115], v[116:117] op_sel_hi:[1,0,1] neg_lo:[1,0,0] neg_hi:[1,0,0]
	v_pk_fma_f32 v[116:117], v[210:211], v[114:115], v[116:117] op_sel:[0,1,0] neg_lo:[1,0,0] neg_hi:[1,0,0]
	ds_read_b128 v[204:207], v228 offset:5168
	ds_read_b128 v[208:211], v228 offset:5184
	s_waitcnt lgkmcnt(14)
	v_fma_f32 v117, -v213, v116, v117
	v_pk_fma_f32 v[118:119], v[216:217], v[100:101], v[118:119] op_sel_hi:[1,0,1] neg_lo:[1,0,0] neg_hi:[1,0,0]
	v_pk_fma_f32 v[118:119], v[218:219], v[100:101], v[118:119] op_sel:[0,1,0] neg_lo:[1,0,0] neg_hi:[1,0,0]
	ds_read_b128 v[212:215], v228 offset:5200
	ds_read_b128 v[216:219], v228 offset:5216
	s_waitcnt lgkmcnt(14)
	v_pk_fma_f32 v[118:119], v[220:221], v[102:103], v[118:119] op_sel_hi:[1,0,1] neg_lo:[1,0,0] neg_hi:[1,0,0]
	v_pk_fma_f32 v[118:119], v[222:223], v[102:103], v[118:119] op_sel:[0,1,0] neg_lo:[1,0,0] neg_hi:[1,0,0]
	v_pk_fma_f32 v[118:119], v[224:225], v[104:105], v[118:119] op_sel_hi:[1,0,1] neg_lo:[1,0,0] neg_hi:[1,0,0]
	v_pk_fma_f32 v[118:119], v[226:227], v[104:105], v[118:119] op_sel:[0,1,0] neg_lo:[1,0,0] neg_hi:[1,0,0]
	ds_read_b128 v[220:223], v228 offset:5232
	ds_read_b128 v[224:227], v228 offset:5248
	s_waitcnt lgkmcnt(14)
	v_pk_fma_f32 v[118:119], v[164:165], v[106:107], v[118:119] op_sel_hi:[1,0,1] neg_lo:[1,0,0] neg_hi:[1,0,0]
	v_pk_fma_f32 v[118:119], v[166:167], v[106:107], v[118:119] op_sel:[0,1,0] neg_lo:[1,0,0] neg_hi:[1,0,0]
	v_pk_fma_f32 v[118:119], v[168:169], v[108:109], v[118:119] op_sel_hi:[1,0,1] neg_lo:[1,0,0] neg_hi:[1,0,0]
	v_pk_fma_f32 v[118:119], v[170:171], v[108:109], v[118:119] op_sel:[0,1,0] neg_lo:[1,0,0] neg_hi:[1,0,0]
	ds_read_b128 v[164:167], v228 offset:5264
	ds_read_b128 v[168:171], v228 offset:5280
	s_waitcnt lgkmcnt(14)
	v_pk_fma_f32 v[118:119], v[172:173], v[110:111], v[118:119] op_sel_hi:[1,0,1] neg_lo:[1,0,0] neg_hi:[1,0,0]
	v_pk_fma_f32 v[118:119], v[174:175], v[110:111], v[118:119] op_sel:[0,1,0] neg_lo:[1,0,0] neg_hi:[1,0,0]
	v_pk_fma_f32 v[118:119], v[176:177], v[112:113], v[118:119] op_sel_hi:[1,0,1] neg_lo:[1,0,0] neg_hi:[1,0,0]
	v_pk_fma_f32 v[118:119], v[178:179], v[112:113], v[118:119] op_sel:[0,1,0] neg_lo:[1,0,0] neg_hi:[1,0,0]
	ds_read_b128 v[172:175], v228 offset:5632
	ds_read_b128 v[176:179], v228 offset:5648
	s_waitcnt lgkmcnt(14)
	v_pk_fma_f32 v[118:119], v[180:181], v[114:115], v[118:119] op_sel_hi:[1,0,1] neg_lo:[1,0,0] neg_hi:[1,0,0]
	v_pk_fma_f32 v[118:119], v[182:183], v[114:115], v[118:119] op_sel:[0,1,0] neg_lo:[1,0,0] neg_hi:[1,0,0]
	v_pk_fma_f32 v[118:119], v[184:185], v[116:117], v[118:119] op_sel_hi:[1,0,1] neg_lo:[1,0,0] neg_hi:[1,0,0]
	v_pk_fma_f32 v[118:119], v[186:187], v[116:117], v[118:119] op_sel:[0,1,0] neg_lo:[1,0,0] neg_hi:[1,0,0]
	ds_read_b128 v[180:183], v228 offset:5664
	ds_read_b128 v[184:187], v228 offset:5680
	s_waitcnt lgkmcnt(14)
	v_fma_f32 v119, -v189, v118, v119
	v_pk_fma_f32 v[120:121], v[192:193], v[100:101], v[120:121] op_sel_hi:[1,0,1] neg_lo:[1,0,0] neg_hi:[1,0,0]
	v_pk_fma_f32 v[120:121], v[194:195], v[100:101], v[120:121] op_sel:[0,1,0] neg_lo:[1,0,0] neg_hi:[1,0,0]
	ds_read_b128 v[188:191], v228 offset:5696
	ds_read_b128 v[192:195], v228 offset:5712
	s_waitcnt lgkmcnt(14)
	v_pk_fma_f32 v[120:121], v[196:197], v[102:103], v[120:121] op_sel_hi:[1,0,1] neg_lo:[1,0,0] neg_hi:[1,0,0]
	v_pk_fma_f32 v[120:121], v[198:199], v[102:103], v[120:121] op_sel:[0,1,0] neg_lo:[1,0,0] neg_hi:[1,0,0]
	v_pk_fma_f32 v[120:121], v[200:201], v[104:105], v[120:121] op_sel_hi:[1,0,1] neg_lo:[1,0,0] neg_hi:[1,0,0]
	v_pk_fma_f32 v[120:121], v[202:203], v[104:105], v[120:121] op_sel:[0,1,0] neg_lo:[1,0,0] neg_hi:[1,0,0]
	ds_read_b128 v[196:199], v228 offset:5728
	ds_read_b128 v[200:203], v228 offset:5744
	s_waitcnt lgkmcnt(14)
	v_pk_fma_f32 v[120:121], v[204:205], v[106:107], v[120:121] op_sel_hi:[1,0,1] neg_lo:[1,0,0] neg_hi:[1,0,0]
	v_pk_fma_f32 v[120:121], v[206:207], v[106:107], v[120:121] op_sel:[0,1,0] neg_lo:[1,0,0] neg_hi:[1,0,0]
	v_pk_fma_f32 v[120:121], v[208:209], v[108:109], v[120:121] op_sel_hi:[1,0,1] neg_lo:[1,0,0] neg_hi:[1,0,0]
	v_pk_fma_f32 v[120:121], v[210:211], v[108:109], v[120:121] op_sel:[0,1,0] neg_lo:[1,0,0] neg_hi:[1,0,0]
	ds_read_b128 v[204:207], v228 offset:5760
	ds_read_b128 v[208:211], v228 offset:5776
	s_waitcnt lgkmcnt(14)
	v_pk_fma_f32 v[120:121], v[212:213], v[110:111], v[120:121] op_sel_hi:[1,0,1] neg_lo:[1,0,0] neg_hi:[1,0,0]
	v_pk_fma_f32 v[120:121], v[214:215], v[110:111], v[120:121] op_sel:[0,1,0] neg_lo:[1,0,0] neg_hi:[1,0,0]
	v_pk_fma_f32 v[120:121], v[216:217], v[112:113], v[120:121] op_sel_hi:[1,0,1] neg_lo:[1,0,0] neg_hi:[1,0,0]
	v_pk_fma_f32 v[120:121], v[218:219], v[112:113], v[120:121] op_sel:[0,1,0] neg_lo:[1,0,0] neg_hi:[1,0,0]
	ds_read_b128 v[212:215], v228 offset:5792
	ds_read_b128 v[216:219], v228 offset:5808
	s_waitcnt lgkmcnt(14)
	v_pk_fma_f32 v[120:121], v[220:221], v[114:115], v[120:121] op_sel_hi:[1,0,1] neg_lo:[1,0,0] neg_hi:[1,0,0]
	v_pk_fma_f32 v[120:121], v[222:223], v[114:115], v[120:121] op_sel:[0,1,0] neg_lo:[1,0,0] neg_hi:[1,0,0]
	v_pk_fma_f32 v[120:121], v[224:225], v[116:117], v[120:121] op_sel_hi:[1,0,1] neg_lo:[1,0,0] neg_hi:[1,0,0]
	v_pk_fma_f32 v[120:121], v[226:227], v[116:117], v[120:121] op_sel:[0,1,0] neg_lo:[1,0,0] neg_hi:[1,0,0]
	ds_read_b128 v[220:223], v228 offset:6144
	ds_read_b128 v[224:227], v228 offset:6160
	s_waitcnt lgkmcnt(14)
	v_pk_fma_f32 v[120:121], v[164:165], v[118:119], v[120:121] op_sel_hi:[1,0,1] neg_lo:[1,0,0] neg_hi:[1,0,0]
	v_pk_fma_f32 v[120:121], v[166:167], v[118:119], v[120:121] op_sel:[0,1,0] neg_lo:[1,0,0] neg_hi:[1,0,0]
	v_fma_f32 v121, -v169, v120, v121
	ds_read_b128 v[164:167], v228 offset:6176
	ds_read_b128 v[168:171], v228 offset:6192
	s_waitcnt lgkmcnt(14)
	v_pk_fma_f32 v[122:123], v[172:173], v[100:101], v[122:123] op_sel_hi:[1,0,1] neg_lo:[1,0,0] neg_hi:[1,0,0]
	v_pk_fma_f32 v[122:123], v[174:175], v[100:101], v[122:123] op_sel:[0,1,0] neg_lo:[1,0,0] neg_hi:[1,0,0]
	v_pk_fma_f32 v[122:123], v[176:177], v[102:103], v[122:123] op_sel_hi:[1,0,1] neg_lo:[1,0,0] neg_hi:[1,0,0]
	v_pk_fma_f32 v[122:123], v[178:179], v[102:103], v[122:123] op_sel:[0,1,0] neg_lo:[1,0,0] neg_hi:[1,0,0]
	ds_read_b128 v[172:175], v228 offset:6208
	ds_read_b128 v[176:179], v228 offset:6224
	s_waitcnt lgkmcnt(14)
	v_pk_fma_f32 v[122:123], v[180:181], v[104:105], v[122:123] op_sel_hi:[1,0,1] neg_lo:[1,0,0] neg_hi:[1,0,0]
	v_pk_fma_f32 v[122:123], v[182:183], v[104:105], v[122:123] op_sel:[0,1,0] neg_lo:[1,0,0] neg_hi:[1,0,0]
	v_pk_fma_f32 v[122:123], v[184:185], v[106:107], v[122:123] op_sel_hi:[1,0,1] neg_lo:[1,0,0] neg_hi:[1,0,0]
	v_pk_fma_f32 v[122:123], v[186:187], v[106:107], v[122:123] op_sel:[0,1,0] neg_lo:[1,0,0] neg_hi:[1,0,0]
	ds_read_b128 v[180:183], v228 offset:6240
	ds_read_b128 v[184:187], v228 offset:6256
	s_waitcnt lgkmcnt(14)
	v_pk_fma_f32 v[122:123], v[188:189], v[108:109], v[122:123] op_sel_hi:[1,0,1] neg_lo:[1,0,0] neg_hi:[1,0,0]
	v_pk_fma_f32 v[122:123], v[190:191], v[108:109], v[122:123] op_sel:[0,1,0] neg_lo:[1,0,0] neg_hi:[1,0,0]
	v_pk_fma_f32 v[122:123], v[192:193], v[110:111], v[122:123] op_sel_hi:[1,0,1] neg_lo:[1,0,0] neg_hi:[1,0,0]
	v_pk_fma_f32 v[122:123], v[194:195], v[110:111], v[122:123] op_sel:[0,1,0] neg_lo:[1,0,0] neg_hi:[1,0,0]
	ds_read_b128 v[188:191], v228 offset:6272
	ds_read_b128 v[192:195], v228 offset:6288
	s_waitcnt lgkmcnt(14)
	v_pk_fma_f32 v[122:123], v[196:197], v[112:113], v[122:123] op_sel_hi:[1,0,1] neg_lo:[1,0,0] neg_hi:[1,0,0]
	v_pk_fma_f32 v[122:123], v[198:199], v[112:113], v[122:123] op_sel:[0,1,0] neg_lo:[1,0,0] neg_hi:[1,0,0]
	v_pk_fma_f32 v[122:123], v[200:201], v[114:115], v[122:123] op_sel_hi:[1,0,1] neg_lo:[1,0,0] neg_hi:[1,0,0]
	v_pk_fma_f32 v[122:123], v[202:203], v[114:115], v[122:123] op_sel:[0,1,0] neg_lo:[1,0,0] neg_hi:[1,0,0]
	ds_read_b128 v[196:199], v228 offset:6304
	ds_read_b128 v[200:203], v228 offset:6320
	s_waitcnt lgkmcnt(14)
	v_pk_fma_f32 v[122:123], v[204:205], v[116:117], v[122:123] op_sel_hi:[1,0,1] neg_lo:[1,0,0] neg_hi:[1,0,0]
	v_pk_fma_f32 v[122:123], v[206:207], v[116:117], v[122:123] op_sel:[0,1,0] neg_lo:[1,0,0] neg_hi:[1,0,0]
	v_pk_fma_f32 v[122:123], v[208:209], v[118:119], v[122:123] op_sel_hi:[1,0,1] neg_lo:[1,0,0] neg_hi:[1,0,0]
	v_pk_fma_f32 v[122:123], v[210:211], v[118:119], v[122:123] op_sel:[0,1,0] neg_lo:[1,0,0] neg_hi:[1,0,0]
	ds_read_b128 v[204:207], v228 offset:6336
	ds_read_b128 v[208:211], v228 offset:6656
	s_waitcnt lgkmcnt(14)
	v_pk_fma_f32 v[122:123], v[212:213], v[120:121], v[122:123] op_sel_hi:[1,0,1] neg_lo:[1,0,0] neg_hi:[1,0,0]
	v_pk_fma_f32 v[122:123], v[214:215], v[120:121], v[122:123] op_sel:[0,1,0] neg_lo:[1,0,0] neg_hi:[1,0,0]
	v_fma_f32 v123, -v217, v122, v123
	ds_read_b128 v[212:215], v228 offset:6672
	ds_read_b128 v[216:219], v228 offset:6688
	s_waitcnt lgkmcnt(14)
	v_pk_fma_f32 v[124:125], v[220:221], v[100:101], v[124:125] op_sel_hi:[1,0,1] neg_lo:[1,0,0] neg_hi:[1,0,0]
	v_pk_fma_f32 v[124:125], v[222:223], v[100:101], v[124:125] op_sel:[0,1,0] neg_lo:[1,0,0] neg_hi:[1,0,0]
	v_pk_fma_f32 v[124:125], v[224:225], v[102:103], v[124:125] op_sel_hi:[1,0,1] neg_lo:[1,0,0] neg_hi:[1,0,0]
	v_pk_fma_f32 v[124:125], v[226:227], v[102:103], v[124:125] op_sel:[0,1,0] neg_lo:[1,0,0] neg_hi:[1,0,0]
	ds_read_b128 v[220:223], v228 offset:6704
	ds_read_b128 v[224:227], v228 offset:6720
	s_waitcnt lgkmcnt(14)
	v_pk_fma_f32 v[124:125], v[164:165], v[104:105], v[124:125] op_sel_hi:[1,0,1] neg_lo:[1,0,0] neg_hi:[1,0,0]
	v_pk_fma_f32 v[124:125], v[166:167], v[104:105], v[124:125] op_sel:[0,1,0] neg_lo:[1,0,0] neg_hi:[1,0,0]
	v_pk_fma_f32 v[124:125], v[168:169], v[106:107], v[124:125] op_sel_hi:[1,0,1] neg_lo:[1,0,0] neg_hi:[1,0,0]
	v_pk_fma_f32 v[124:125], v[170:171], v[106:107], v[124:125] op_sel:[0,1,0] neg_lo:[1,0,0] neg_hi:[1,0,0]
	ds_read_b128 v[164:167], v228 offset:6736
	ds_read_b128 v[168:171], v228 offset:6752
	s_waitcnt lgkmcnt(14)
	v_pk_fma_f32 v[124:125], v[172:173], v[108:109], v[124:125] op_sel_hi:[1,0,1] neg_lo:[1,0,0] neg_hi:[1,0,0]
	v_pk_fma_f32 v[124:125], v[174:175], v[108:109], v[124:125] op_sel:[0,1,0] neg_lo:[1,0,0] neg_hi:[1,0,0]
	v_pk_fma_f32 v[124:125], v[176:177], v[110:111], v[124:125] op_sel_hi:[1,0,1] neg_lo:[1,0,0] neg_hi:[1,0,0]
	v_pk_fma_f32 v[124:125], v[178:179], v[110:111], v[124:125] op_sel:[0,1,0] neg_lo:[1,0,0] neg_hi:[1,0,0]
	ds_read_b128 v[172:175], v228 offset:6768
	ds_read_b128 v[176:179], v228 offset:6784
	s_waitcnt lgkmcnt(14)
	v_pk_fma_f32 v[124:125], v[180:181], v[112:113], v[124:125] op_sel_hi:[1,0,1] neg_lo:[1,0,0] neg_hi:[1,0,0]
	v_pk_fma_f32 v[124:125], v[182:183], v[112:113], v[124:125] op_sel:[0,1,0] neg_lo:[1,0,0] neg_hi:[1,0,0]
	v_pk_fma_f32 v[124:125], v[184:185], v[114:115], v[124:125] op_sel_hi:[1,0,1] neg_lo:[1,0,0] neg_hi:[1,0,0]
	v_pk_fma_f32 v[124:125], v[186:187], v[114:115], v[124:125] op_sel:[0,1,0] neg_lo:[1,0,0] neg_hi:[1,0,0]
	ds_read_b128 v[180:183], v228 offset:6800
	ds_read_b128 v[184:187], v228 offset:6816
	s_waitcnt lgkmcnt(14)
	v_pk_fma_f32 v[124:125], v[188:189], v[116:117], v[124:125] op_sel_hi:[1,0,1] neg_lo:[1,0,0] neg_hi:[1,0,0]
	v_pk_fma_f32 v[124:125], v[190:191], v[116:117], v[124:125] op_sel:[0,1,0] neg_lo:[1,0,0] neg_hi:[1,0,0]
	v_pk_fma_f32 v[124:125], v[192:193], v[118:119], v[124:125] op_sel_hi:[1,0,1] neg_lo:[1,0,0] neg_hi:[1,0,0]
	v_pk_fma_f32 v[124:125], v[194:195], v[118:119], v[124:125] op_sel:[0,1,0] neg_lo:[1,0,0] neg_hi:[1,0,0]
	ds_read_b128 v[188:191], v228 offset:6832
	ds_read_b128 v[192:195], v228 offset:6848
	s_waitcnt lgkmcnt(14)
	v_pk_fma_f32 v[124:125], v[196:197], v[120:121], v[124:125] op_sel_hi:[1,0,1] neg_lo:[1,0,0] neg_hi:[1,0,0]
	v_pk_fma_f32 v[124:125], v[198:199], v[120:121], v[124:125] op_sel:[0,1,0] neg_lo:[1,0,0] neg_hi:[1,0,0]
	v_pk_fma_f32 v[124:125], v[200:201], v[122:123], v[124:125] op_sel_hi:[1,0,1] neg_lo:[1,0,0] neg_hi:[1,0,0]
	v_pk_fma_f32 v[124:125], v[202:203], v[122:123], v[124:125] op_sel:[0,1,0] neg_lo:[1,0,0] neg_hi:[1,0,0]
	ds_read_b128 v[196:199], v228 offset:6864
	ds_read_b128 v[200:203], v228 offset:7168
	s_waitcnt lgkmcnt(14)
	v_fma_f32 v125, -v205, v124, v125
	v_pk_fma_f32 v[126:127], v[208:209], v[100:101], v[126:127] op_sel_hi:[1,0,1] neg_lo:[1,0,0] neg_hi:[1,0,0]
	v_pk_fma_f32 v[126:127], v[210:211], v[100:101], v[126:127] op_sel:[0,1,0] neg_lo:[1,0,0] neg_hi:[1,0,0]
	ds_read_b128 v[204:207], v228 offset:7184
	ds_read_b128 v[208:211], v228 offset:7200
	s_waitcnt lgkmcnt(14)
	v_pk_fma_f32 v[126:127], v[212:213], v[102:103], v[126:127] op_sel_hi:[1,0,1] neg_lo:[1,0,0] neg_hi:[1,0,0]
	v_pk_fma_f32 v[126:127], v[214:215], v[102:103], v[126:127] op_sel:[0,1,0] neg_lo:[1,0,0] neg_hi:[1,0,0]
	v_pk_fma_f32 v[126:127], v[216:217], v[104:105], v[126:127] op_sel_hi:[1,0,1] neg_lo:[1,0,0] neg_hi:[1,0,0]
	v_pk_fma_f32 v[126:127], v[218:219], v[104:105], v[126:127] op_sel:[0,1,0] neg_lo:[1,0,0] neg_hi:[1,0,0]
	ds_read_b128 v[212:215], v228 offset:7216
	ds_read_b128 v[216:219], v228 offset:7232
	s_waitcnt lgkmcnt(14)
	v_pk_fma_f32 v[126:127], v[220:221], v[106:107], v[126:127] op_sel_hi:[1,0,1] neg_lo:[1,0,0] neg_hi:[1,0,0]
	v_pk_fma_f32 v[126:127], v[222:223], v[106:107], v[126:127] op_sel:[0,1,0] neg_lo:[1,0,0] neg_hi:[1,0,0]
	v_pk_fma_f32 v[126:127], v[224:225], v[108:109], v[126:127] op_sel_hi:[1,0,1] neg_lo:[1,0,0] neg_hi:[1,0,0]
	v_pk_fma_f32 v[126:127], v[226:227], v[108:109], v[126:127] op_sel:[0,1,0] neg_lo:[1,0,0] neg_hi:[1,0,0]
	ds_read_b128 v[220:223], v228 offset:7248
	ds_read_b128 v[224:227], v228 offset:7264
	s_waitcnt lgkmcnt(14)
	v_pk_fma_f32 v[126:127], v[164:165], v[110:111], v[126:127] op_sel_hi:[1,0,1] neg_lo:[1,0,0] neg_hi:[1,0,0]
	v_pk_fma_f32 v[126:127], v[166:167], v[110:111], v[126:127] op_sel:[0,1,0] neg_lo:[1,0,0] neg_hi:[1,0,0]
	v_pk_fma_f32 v[126:127], v[168:169], v[112:113], v[126:127] op_sel_hi:[1,0,1] neg_lo:[1,0,0] neg_hi:[1,0,0]
	v_pk_fma_f32 v[126:127], v[170:171], v[112:113], v[126:127] op_sel:[0,1,0] neg_lo:[1,0,0] neg_hi:[1,0,0]
	ds_read_b128 v[164:167], v228 offset:7280
	ds_read_b128 v[168:171], v228 offset:7296
	s_waitcnt lgkmcnt(14)
	v_pk_fma_f32 v[126:127], v[172:173], v[114:115], v[126:127] op_sel_hi:[1,0,1] neg_lo:[1,0,0] neg_hi:[1,0,0]
	v_pk_fma_f32 v[126:127], v[174:175], v[114:115], v[126:127] op_sel:[0,1,0] neg_lo:[1,0,0] neg_hi:[1,0,0]
	v_pk_fma_f32 v[126:127], v[176:177], v[116:117], v[126:127] op_sel_hi:[1,0,1] neg_lo:[1,0,0] neg_hi:[1,0,0]
	v_pk_fma_f32 v[126:127], v[178:179], v[116:117], v[126:127] op_sel:[0,1,0] neg_lo:[1,0,0] neg_hi:[1,0,0]
	ds_read_b128 v[172:175], v228 offset:7312
	ds_read_b128 v[176:179], v228 offset:7328
	s_waitcnt lgkmcnt(14)
	v_pk_fma_f32 v[126:127], v[180:181], v[118:119], v[126:127] op_sel_hi:[1,0,1] neg_lo:[1,0,0] neg_hi:[1,0,0]
	v_pk_fma_f32 v[126:127], v[182:183], v[118:119], v[126:127] op_sel:[0,1,0] neg_lo:[1,0,0] neg_hi:[1,0,0]
	v_pk_fma_f32 v[126:127], v[184:185], v[120:121], v[126:127] op_sel_hi:[1,0,1] neg_lo:[1,0,0] neg_hi:[1,0,0]
	v_pk_fma_f32 v[126:127], v[186:187], v[120:121], v[126:127] op_sel:[0,1,0] neg_lo:[1,0,0] neg_hi:[1,0,0]
	ds_read_b128 v[180:183], v228 offset:7344
	ds_read_b128 v[184:187], v228 offset:7360
	s_waitcnt lgkmcnt(14)
	v_pk_fma_f32 v[126:127], v[188:189], v[122:123], v[126:127] op_sel_hi:[1,0,1] neg_lo:[1,0,0] neg_hi:[1,0,0]
	v_pk_fma_f32 v[126:127], v[190:191], v[122:123], v[126:127] op_sel:[0,1,0] neg_lo:[1,0,0] neg_hi:[1,0,0]
	v_pk_fma_f32 v[126:127], v[192:193], v[124:125], v[126:127] op_sel_hi:[1,0,1] neg_lo:[1,0,0] neg_hi:[1,0,0]
	v_pk_fma_f32 v[126:127], v[194:195], v[124:125], v[126:127] op_sel:[0,1,0] neg_lo:[1,0,0] neg_hi:[1,0,0]
	ds_read_b128 v[188:191], v228 offset:7376
	ds_read_b128 v[192:195], v228 offset:7392
	s_waitcnt lgkmcnt(14)
	v_fma_f32 v127, -v197, v126, v127
	v_pk_fma_f32 v[128:129], v[200:201], v[100:101], v[128:129] op_sel_hi:[1,0,1] neg_lo:[1,0,0] neg_hi:[1,0,0]
	v_pk_fma_f32 v[128:129], v[202:203], v[100:101], v[128:129] op_sel:[0,1,0] neg_lo:[1,0,0] neg_hi:[1,0,0]
	ds_read_b128 v[196:199], v228 offset:7680
	ds_read_b128 v[200:203], v228 offset:7696
	s_waitcnt lgkmcnt(14)
	v_pk_fma_f32 v[128:129], v[204:205], v[102:103], v[128:129] op_sel_hi:[1,0,1] neg_lo:[1,0,0] neg_hi:[1,0,0]
	v_pk_fma_f32 v[128:129], v[206:207], v[102:103], v[128:129] op_sel:[0,1,0] neg_lo:[1,0,0] neg_hi:[1,0,0]
	v_pk_fma_f32 v[128:129], v[208:209], v[104:105], v[128:129] op_sel_hi:[1,0,1] neg_lo:[1,0,0] neg_hi:[1,0,0]
	v_pk_fma_f32 v[128:129], v[210:211], v[104:105], v[128:129] op_sel:[0,1,0] neg_lo:[1,0,0] neg_hi:[1,0,0]
	ds_read_b128 v[204:207], v228 offset:7712
	ds_read_b128 v[208:211], v228 offset:7728
	s_waitcnt lgkmcnt(14)
	v_pk_fma_f32 v[128:129], v[212:213], v[106:107], v[128:129] op_sel_hi:[1,0,1] neg_lo:[1,0,0] neg_hi:[1,0,0]
	v_pk_fma_f32 v[128:129], v[214:215], v[106:107], v[128:129] op_sel:[0,1,0] neg_lo:[1,0,0] neg_hi:[1,0,0]
	v_pk_fma_f32 v[128:129], v[216:217], v[108:109], v[128:129] op_sel_hi:[1,0,1] neg_lo:[1,0,0] neg_hi:[1,0,0]
	v_pk_fma_f32 v[128:129], v[218:219], v[108:109], v[128:129] op_sel:[0,1,0] neg_lo:[1,0,0] neg_hi:[1,0,0]
	ds_read_b128 v[212:215], v228 offset:7744
	ds_read_b128 v[216:219], v228 offset:7760
	s_waitcnt lgkmcnt(14)
	v_pk_fma_f32 v[128:129], v[220:221], v[110:111], v[128:129] op_sel_hi:[1,0,1] neg_lo:[1,0,0] neg_hi:[1,0,0]
	v_pk_fma_f32 v[128:129], v[222:223], v[110:111], v[128:129] op_sel:[0,1,0] neg_lo:[1,0,0] neg_hi:[1,0,0]
	v_pk_fma_f32 v[128:129], v[224:225], v[112:113], v[128:129] op_sel_hi:[1,0,1] neg_lo:[1,0,0] neg_hi:[1,0,0]
	v_pk_fma_f32 v[128:129], v[226:227], v[112:113], v[128:129] op_sel:[0,1,0] neg_lo:[1,0,0] neg_hi:[1,0,0]
	ds_read_b128 v[220:223], v228 offset:7776
	ds_read_b128 v[224:227], v228 offset:7792
	s_waitcnt lgkmcnt(14)
	v_pk_fma_f32 v[128:129], v[164:165], v[114:115], v[128:129] op_sel_hi:[1,0,1] neg_lo:[1,0,0] neg_hi:[1,0,0]
	v_pk_fma_f32 v[128:129], v[166:167], v[114:115], v[128:129] op_sel:[0,1,0] neg_lo:[1,0,0] neg_hi:[1,0,0]
	v_pk_fma_f32 v[128:129], v[168:169], v[116:117], v[128:129] op_sel_hi:[1,0,1] neg_lo:[1,0,0] neg_hi:[1,0,0]
	v_pk_fma_f32 v[128:129], v[170:171], v[116:117], v[128:129] op_sel:[0,1,0] neg_lo:[1,0,0] neg_hi:[1,0,0]
	ds_read_b128 v[164:167], v228 offset:7808
	ds_read_b128 v[168:171], v228 offset:7824
	s_waitcnt lgkmcnt(14)
	v_pk_fma_f32 v[128:129], v[172:173], v[118:119], v[128:129] op_sel_hi:[1,0,1] neg_lo:[1,0,0] neg_hi:[1,0,0]
	v_pk_fma_f32 v[128:129], v[174:175], v[118:119], v[128:129] op_sel:[0,1,0] neg_lo:[1,0,0] neg_hi:[1,0,0]
	v_pk_fma_f32 v[128:129], v[176:177], v[120:121], v[128:129] op_sel_hi:[1,0,1] neg_lo:[1,0,0] neg_hi:[1,0,0]
	v_pk_fma_f32 v[128:129], v[178:179], v[120:121], v[128:129] op_sel:[0,1,0] neg_lo:[1,0,0] neg_hi:[1,0,0]
	ds_read_b128 v[172:175], v228 offset:7840
	ds_read_b128 v[176:179], v228 offset:7856
	s_waitcnt lgkmcnt(14)
	v_pk_fma_f32 v[128:129], v[180:181], v[122:123], v[128:129] op_sel_hi:[1,0,1] neg_lo:[1,0,0] neg_hi:[1,0,0]
	v_pk_fma_f32 v[128:129], v[182:183], v[122:123], v[128:129] op_sel:[0,1,0] neg_lo:[1,0,0] neg_hi:[1,0,0]
	v_pk_fma_f32 v[128:129], v[184:185], v[124:125], v[128:129] op_sel_hi:[1,0,1] neg_lo:[1,0,0] neg_hi:[1,0,0]
	v_pk_fma_f32 v[128:129], v[186:187], v[124:125], v[128:129] op_sel:[0,1,0] neg_lo:[1,0,0] neg_hi:[1,0,0]
	ds_read_b128 v[180:183], v228 offset:7872
	ds_read_b128 v[184:187], v228 offset:7888
	s_waitcnt lgkmcnt(14)
	v_pk_fma_f32 v[128:129], v[188:189], v[126:127], v[128:129] op_sel_hi:[1,0,1] neg_lo:[1,0,0] neg_hi:[1,0,0]
	v_pk_fma_f32 v[128:129], v[190:191], v[126:127], v[128:129] op_sel:[0,1,0] neg_lo:[1,0,0] neg_hi:[1,0,0]
	v_fma_f32 v129, -v193, v128, v129
	ds_read_b128 v[188:191], v228 offset:7904
	ds_read_b128 v[192:195], v228 offset:7920
	s_waitcnt lgkmcnt(14)
	v_pk_fma_f32 v[130:131], v[196:197], v[100:101], v[130:131] op_sel_hi:[1,0,1] neg_lo:[1,0,0] neg_hi:[1,0,0]
	v_pk_fma_f32 v[130:131], v[198:199], v[100:101], v[130:131] op_sel:[0,1,0] neg_lo:[1,0,0] neg_hi:[1,0,0]
	v_pk_fma_f32 v[130:131], v[200:201], v[102:103], v[130:131] op_sel_hi:[1,0,1] neg_lo:[1,0,0] neg_hi:[1,0,0]
	v_pk_fma_f32 v[130:131], v[202:203], v[102:103], v[130:131] op_sel:[0,1,0] neg_lo:[1,0,0] neg_hi:[1,0,0]
	ds_read_b128 v[196:199], v228 offset:8192
	ds_read_b128 v[200:203], v228 offset:8208
	s_waitcnt lgkmcnt(14)
	v_pk_fma_f32 v[130:131], v[204:205], v[104:105], v[130:131] op_sel_hi:[1,0,1] neg_lo:[1,0,0] neg_hi:[1,0,0]
	v_pk_fma_f32 v[130:131], v[206:207], v[104:105], v[130:131] op_sel:[0,1,0] neg_lo:[1,0,0] neg_hi:[1,0,0]
	v_pk_fma_f32 v[130:131], v[208:209], v[106:107], v[130:131] op_sel_hi:[1,0,1] neg_lo:[1,0,0] neg_hi:[1,0,0]
	v_pk_fma_f32 v[130:131], v[210:211], v[106:107], v[130:131] op_sel:[0,1,0] neg_lo:[1,0,0] neg_hi:[1,0,0]
	ds_read_b128 v[204:207], v228 offset:8224
	ds_read_b128 v[208:211], v228 offset:8240
	s_waitcnt lgkmcnt(14)
	v_pk_fma_f32 v[130:131], v[212:213], v[108:109], v[130:131] op_sel_hi:[1,0,1] neg_lo:[1,0,0] neg_hi:[1,0,0]
	v_pk_fma_f32 v[130:131], v[214:215], v[108:109], v[130:131] op_sel:[0,1,0] neg_lo:[1,0,0] neg_hi:[1,0,0]
	v_pk_fma_f32 v[130:131], v[216:217], v[110:111], v[130:131] op_sel_hi:[1,0,1] neg_lo:[1,0,0] neg_hi:[1,0,0]
	v_pk_fma_f32 v[130:131], v[218:219], v[110:111], v[130:131] op_sel:[0,1,0] neg_lo:[1,0,0] neg_hi:[1,0,0]
	ds_read_b128 v[212:215], v228 offset:8256
	ds_read_b128 v[216:219], v228 offset:8272
	s_waitcnt lgkmcnt(14)
	v_pk_fma_f32 v[130:131], v[220:221], v[112:113], v[130:131] op_sel_hi:[1,0,1] neg_lo:[1,0,0] neg_hi:[1,0,0]
	v_pk_fma_f32 v[130:131], v[222:223], v[112:113], v[130:131] op_sel:[0,1,0] neg_lo:[1,0,0] neg_hi:[1,0,0]
	v_pk_fma_f32 v[130:131], v[224:225], v[114:115], v[130:131] op_sel_hi:[1,0,1] neg_lo:[1,0,0] neg_hi:[1,0,0]
	v_pk_fma_f32 v[130:131], v[226:227], v[114:115], v[130:131] op_sel:[0,1,0] neg_lo:[1,0,0] neg_hi:[1,0,0]
	ds_read_b128 v[220:223], v228 offset:8288
	ds_read_b128 v[224:227], v228 offset:8304
	s_waitcnt lgkmcnt(14)
	v_pk_fma_f32 v[130:131], v[164:165], v[116:117], v[130:131] op_sel_hi:[1,0,1] neg_lo:[1,0,0] neg_hi:[1,0,0]
	v_pk_fma_f32 v[130:131], v[166:167], v[116:117], v[130:131] op_sel:[0,1,0] neg_lo:[1,0,0] neg_hi:[1,0,0]
	v_pk_fma_f32 v[130:131], v[168:169], v[118:119], v[130:131] op_sel_hi:[1,0,1] neg_lo:[1,0,0] neg_hi:[1,0,0]
	v_pk_fma_f32 v[130:131], v[170:171], v[118:119], v[130:131] op_sel:[0,1,0] neg_lo:[1,0,0] neg_hi:[1,0,0]
	ds_read_b128 v[164:167], v228 offset:8320
	ds_read_b128 v[168:171], v228 offset:8336
	s_waitcnt lgkmcnt(14)
	v_pk_fma_f32 v[130:131], v[172:173], v[120:121], v[130:131] op_sel_hi:[1,0,1] neg_lo:[1,0,0] neg_hi:[1,0,0]
	v_pk_fma_f32 v[130:131], v[174:175], v[120:121], v[130:131] op_sel:[0,1,0] neg_lo:[1,0,0] neg_hi:[1,0,0]
	v_pk_fma_f32 v[130:131], v[176:177], v[122:123], v[130:131] op_sel_hi:[1,0,1] neg_lo:[1,0,0] neg_hi:[1,0,0]
	v_pk_fma_f32 v[130:131], v[178:179], v[122:123], v[130:131] op_sel:[0,1,0] neg_lo:[1,0,0] neg_hi:[1,0,0]
	ds_read_b128 v[172:175], v228 offset:8352
	ds_read_b128 v[176:179], v228 offset:8368
	s_waitcnt lgkmcnt(14)
	v_pk_fma_f32 v[130:131], v[180:181], v[124:125], v[130:131] op_sel_hi:[1,0,1] neg_lo:[1,0,0] neg_hi:[1,0,0]
	v_pk_fma_f32 v[130:131], v[182:183], v[124:125], v[130:131] op_sel:[0,1,0] neg_lo:[1,0,0] neg_hi:[1,0,0]
	v_pk_fma_f32 v[130:131], v[184:185], v[126:127], v[130:131] op_sel_hi:[1,0,1] neg_lo:[1,0,0] neg_hi:[1,0,0]
	v_pk_fma_f32 v[130:131], v[186:187], v[126:127], v[130:131] op_sel:[0,1,0] neg_lo:[1,0,0] neg_hi:[1,0,0]
	ds_read_b128 v[180:183], v228 offset:8384
	ds_read_b128 v[184:187], v228 offset:8400
	s_waitcnt lgkmcnt(14)
	v_pk_fma_f32 v[130:131], v[188:189], v[128:129], v[130:131] op_sel_hi:[1,0,1] neg_lo:[1,0,0] neg_hi:[1,0,0]
	v_pk_fma_f32 v[130:131], v[190:191], v[128:129], v[130:131] op_sel:[0,1,0] neg_lo:[1,0,0] neg_hi:[1,0,0]
	v_fma_f32 v131, -v193, v130, v131
	ds_read_b128 v[188:191], v228 offset:8416
	ds_read_b128 v[192:195], v228 offset:8432
	s_waitcnt lgkmcnt(14)
	v_pk_fma_f32 v[132:133], v[196:197], v[100:101], v[132:133] op_sel_hi:[1,0,1] neg_lo:[1,0,0] neg_hi:[1,0,0]
	v_pk_fma_f32 v[132:133], v[198:199], v[100:101], v[132:133] op_sel:[0,1,0] neg_lo:[1,0,0] neg_hi:[1,0,0]
	v_pk_fma_f32 v[132:133], v[200:201], v[102:103], v[132:133] op_sel_hi:[1,0,1] neg_lo:[1,0,0] neg_hi:[1,0,0]
	v_pk_fma_f32 v[132:133], v[202:203], v[102:103], v[132:133] op_sel:[0,1,0] neg_lo:[1,0,0] neg_hi:[1,0,0]
	ds_read_b128 v[196:199], v228 offset:8448
	ds_read_b128 v[200:203], v228 offset:8704
	s_waitcnt lgkmcnt(14)
	v_pk_fma_f32 v[132:133], v[204:205], v[104:105], v[132:133] op_sel_hi:[1,0,1] neg_lo:[1,0,0] neg_hi:[1,0,0]
	v_pk_fma_f32 v[132:133], v[206:207], v[104:105], v[132:133] op_sel:[0,1,0] neg_lo:[1,0,0] neg_hi:[1,0,0]
	v_pk_fma_f32 v[132:133], v[208:209], v[106:107], v[132:133] op_sel_hi:[1,0,1] neg_lo:[1,0,0] neg_hi:[1,0,0]
	v_pk_fma_f32 v[132:133], v[210:211], v[106:107], v[132:133] op_sel:[0,1,0] neg_lo:[1,0,0] neg_hi:[1,0,0]
	ds_read_b128 v[204:207], v228 offset:8720
	ds_read_b128 v[208:211], v228 offset:8736
	s_waitcnt lgkmcnt(14)
	v_pk_fma_f32 v[132:133], v[212:213], v[108:109], v[132:133] op_sel_hi:[1,0,1] neg_lo:[1,0,0] neg_hi:[1,0,0]
	v_pk_fma_f32 v[132:133], v[214:215], v[108:109], v[132:133] op_sel:[0,1,0] neg_lo:[1,0,0] neg_hi:[1,0,0]
	v_pk_fma_f32 v[132:133], v[216:217], v[110:111], v[132:133] op_sel_hi:[1,0,1] neg_lo:[1,0,0] neg_hi:[1,0,0]
	v_pk_fma_f32 v[132:133], v[218:219], v[110:111], v[132:133] op_sel:[0,1,0] neg_lo:[1,0,0] neg_hi:[1,0,0]
	ds_read_b128 v[212:215], v228 offset:8752
	ds_read_b128 v[216:219], v228 offset:8768
	s_waitcnt lgkmcnt(14)
	v_pk_fma_f32 v[132:133], v[220:221], v[112:113], v[132:133] op_sel_hi:[1,0,1] neg_lo:[1,0,0] neg_hi:[1,0,0]
	v_pk_fma_f32 v[132:133], v[222:223], v[112:113], v[132:133] op_sel:[0,1,0] neg_lo:[1,0,0] neg_hi:[1,0,0]
	v_pk_fma_f32 v[132:133], v[224:225], v[114:115], v[132:133] op_sel_hi:[1,0,1] neg_lo:[1,0,0] neg_hi:[1,0,0]
	v_pk_fma_f32 v[132:133], v[226:227], v[114:115], v[132:133] op_sel:[0,1,0] neg_lo:[1,0,0] neg_hi:[1,0,0]
	ds_read_b128 v[220:223], v228 offset:8784
	ds_read_b128 v[224:227], v228 offset:8800
	s_waitcnt lgkmcnt(14)
	v_pk_fma_f32 v[132:133], v[164:165], v[116:117], v[132:133] op_sel_hi:[1,0,1] neg_lo:[1,0,0] neg_hi:[1,0,0]
	v_pk_fma_f32 v[132:133], v[166:167], v[116:117], v[132:133] op_sel:[0,1,0] neg_lo:[1,0,0] neg_hi:[1,0,0]
	v_pk_fma_f32 v[132:133], v[168:169], v[118:119], v[132:133] op_sel_hi:[1,0,1] neg_lo:[1,0,0] neg_hi:[1,0,0]
	v_pk_fma_f32 v[132:133], v[170:171], v[118:119], v[132:133] op_sel:[0,1,0] neg_lo:[1,0,0] neg_hi:[1,0,0]
	ds_read_b128 v[164:167], v228 offset:8816
	ds_read_b128 v[168:171], v228 offset:8832
	s_waitcnt lgkmcnt(14)
	v_pk_fma_f32 v[132:133], v[172:173], v[120:121], v[132:133] op_sel_hi:[1,0,1] neg_lo:[1,0,0] neg_hi:[1,0,0]
	v_pk_fma_f32 v[132:133], v[174:175], v[120:121], v[132:133] op_sel:[0,1,0] neg_lo:[1,0,0] neg_hi:[1,0,0]
	v_pk_fma_f32 v[132:133], v[176:177], v[122:123], v[132:133] op_sel_hi:[1,0,1] neg_lo:[1,0,0] neg_hi:[1,0,0]
	v_pk_fma_f32 v[132:133], v[178:179], v[122:123], v[132:133] op_sel:[0,1,0] neg_lo:[1,0,0] neg_hi:[1,0,0]
	ds_read_b128 v[172:175], v228 offset:8848
	ds_read_b128 v[176:179], v228 offset:8864
	s_waitcnt lgkmcnt(14)
	v_pk_fma_f32 v[132:133], v[180:181], v[124:125], v[132:133] op_sel_hi:[1,0,1] neg_lo:[1,0,0] neg_hi:[1,0,0]
	v_pk_fma_f32 v[132:133], v[182:183], v[124:125], v[132:133] op_sel:[0,1,0] neg_lo:[1,0,0] neg_hi:[1,0,0]
	v_pk_fma_f32 v[132:133], v[184:185], v[126:127], v[132:133] op_sel_hi:[1,0,1] neg_lo:[1,0,0] neg_hi:[1,0,0]
	v_pk_fma_f32 v[132:133], v[186:187], v[126:127], v[132:133] op_sel:[0,1,0] neg_lo:[1,0,0] neg_hi:[1,0,0]
	ds_read_b128 v[180:183], v228 offset:8880
	ds_read_b128 v[184:187], v228 offset:8896
	s_waitcnt lgkmcnt(14)
	v_pk_fma_f32 v[132:133], v[188:189], v[128:129], v[132:133] op_sel_hi:[1,0,1] neg_lo:[1,0,0] neg_hi:[1,0,0]
	v_pk_fma_f32 v[132:133], v[190:191], v[128:129], v[132:133] op_sel:[0,1,0] neg_lo:[1,0,0] neg_hi:[1,0,0]
	v_pk_fma_f32 v[132:133], v[192:193], v[130:131], v[132:133] op_sel_hi:[1,0,1] neg_lo:[1,0,0] neg_hi:[1,0,0]
	v_pk_fma_f32 v[132:133], v[194:195], v[130:131], v[132:133] op_sel:[0,1,0] neg_lo:[1,0,0] neg_hi:[1,0,0]
	ds_read_b128 v[188:191], v228 offset:8912
	ds_read_b128 v[192:195], v228 offset:8928
	s_waitcnt lgkmcnt(14)
	v_fma_f32 v133, -v197, v132, v133
	v_pk_fma_f32 v[134:135], v[200:201], v[100:101], v[134:135] op_sel_hi:[1,0,1] neg_lo:[1,0,0] neg_hi:[1,0,0]
	v_pk_fma_f32 v[134:135], v[202:203], v[100:101], v[134:135] op_sel:[0,1,0] neg_lo:[1,0,0] neg_hi:[1,0,0]
	ds_read_b128 v[196:199], v228 offset:8944
	ds_read_b128 v[200:203], v228 offset:8960
	s_waitcnt lgkmcnt(14)
	v_pk_fma_f32 v[134:135], v[204:205], v[102:103], v[134:135] op_sel_hi:[1,0,1] neg_lo:[1,0,0] neg_hi:[1,0,0]
	v_pk_fma_f32 v[134:135], v[206:207], v[102:103], v[134:135] op_sel:[0,1,0] neg_lo:[1,0,0] neg_hi:[1,0,0]
	v_pk_fma_f32 v[134:135], v[208:209], v[104:105], v[134:135] op_sel_hi:[1,0,1] neg_lo:[1,0,0] neg_hi:[1,0,0]
	v_pk_fma_f32 v[134:135], v[210:211], v[104:105], v[134:135] op_sel:[0,1,0] neg_lo:[1,0,0] neg_hi:[1,0,0]
	ds_read_b128 v[204:207], v228 offset:8976
	ds_read_b128 v[208:211], v228 offset:9216
	s_waitcnt lgkmcnt(14)
	v_pk_fma_f32 v[134:135], v[212:213], v[106:107], v[134:135] op_sel_hi:[1,0,1] neg_lo:[1,0,0] neg_hi:[1,0,0]
	v_pk_fma_f32 v[134:135], v[214:215], v[106:107], v[134:135] op_sel:[0,1,0] neg_lo:[1,0,0] neg_hi:[1,0,0]
	v_pk_fma_f32 v[134:135], v[216:217], v[108:109], v[134:135] op_sel_hi:[1,0,1] neg_lo:[1,0,0] neg_hi:[1,0,0]
	v_pk_fma_f32 v[134:135], v[218:219], v[108:109], v[134:135] op_sel:[0,1,0] neg_lo:[1,0,0] neg_hi:[1,0,0]
	ds_read_b128 v[212:215], v228 offset:9232
	ds_read_b128 v[216:219], v228 offset:9248
	s_waitcnt lgkmcnt(14)
	v_pk_fma_f32 v[134:135], v[220:221], v[110:111], v[134:135] op_sel_hi:[1,0,1] neg_lo:[1,0,0] neg_hi:[1,0,0]
	v_pk_fma_f32 v[134:135], v[222:223], v[110:111], v[134:135] op_sel:[0,1,0] neg_lo:[1,0,0] neg_hi:[1,0,0]
	v_pk_fma_f32 v[134:135], v[224:225], v[112:113], v[134:135] op_sel_hi:[1,0,1] neg_lo:[1,0,0] neg_hi:[1,0,0]
	v_pk_fma_f32 v[134:135], v[226:227], v[112:113], v[134:135] op_sel:[0,1,0] neg_lo:[1,0,0] neg_hi:[1,0,0]
	ds_read_b128 v[220:223], v228 offset:9264
	ds_read_b128 v[224:227], v228 offset:9280
	s_waitcnt lgkmcnt(14)
	v_pk_fma_f32 v[134:135], v[164:165], v[114:115], v[134:135] op_sel_hi:[1,0,1] neg_lo:[1,0,0] neg_hi:[1,0,0]
	v_pk_fma_f32 v[134:135], v[166:167], v[114:115], v[134:135] op_sel:[0,1,0] neg_lo:[1,0,0] neg_hi:[1,0,0]
	v_pk_fma_f32 v[134:135], v[168:169], v[116:117], v[134:135] op_sel_hi:[1,0,1] neg_lo:[1,0,0] neg_hi:[1,0,0]
	v_pk_fma_f32 v[134:135], v[170:171], v[116:117], v[134:135] op_sel:[0,1,0] neg_lo:[1,0,0] neg_hi:[1,0,0]
	ds_read_b128 v[164:167], v228 offset:9296
	ds_read_b128 v[168:171], v228 offset:9312
	s_waitcnt lgkmcnt(14)
	v_pk_fma_f32 v[134:135], v[172:173], v[118:119], v[134:135] op_sel_hi:[1,0,1] neg_lo:[1,0,0] neg_hi:[1,0,0]
	v_pk_fma_f32 v[134:135], v[174:175], v[118:119], v[134:135] op_sel:[0,1,0] neg_lo:[1,0,0] neg_hi:[1,0,0]
	v_pk_fma_f32 v[134:135], v[176:177], v[120:121], v[134:135] op_sel_hi:[1,0,1] neg_lo:[1,0,0] neg_hi:[1,0,0]
	v_pk_fma_f32 v[134:135], v[178:179], v[120:121], v[134:135] op_sel:[0,1,0] neg_lo:[1,0,0] neg_hi:[1,0,0]
	ds_read_b128 v[172:175], v228 offset:9328
	ds_read_b128 v[176:179], v228 offset:9344
	s_waitcnt lgkmcnt(14)
	v_pk_fma_f32 v[134:135], v[180:181], v[122:123], v[134:135] op_sel_hi:[1,0,1] neg_lo:[1,0,0] neg_hi:[1,0,0]
	v_pk_fma_f32 v[134:135], v[182:183], v[122:123], v[134:135] op_sel:[0,1,0] neg_lo:[1,0,0] neg_hi:[1,0,0]
	v_pk_fma_f32 v[134:135], v[184:185], v[124:125], v[134:135] op_sel_hi:[1,0,1] neg_lo:[1,0,0] neg_hi:[1,0,0]
	v_pk_fma_f32 v[134:135], v[186:187], v[124:125], v[134:135] op_sel:[0,1,0] neg_lo:[1,0,0] neg_hi:[1,0,0]
	ds_read_b128 v[180:183], v228 offset:9360
	ds_read_b128 v[184:187], v228 offset:9376
	s_waitcnt lgkmcnt(14)
	v_pk_fma_f32 v[134:135], v[188:189], v[126:127], v[134:135] op_sel_hi:[1,0,1] neg_lo:[1,0,0] neg_hi:[1,0,0]
	v_pk_fma_f32 v[134:135], v[190:191], v[126:127], v[134:135] op_sel:[0,1,0] neg_lo:[1,0,0] neg_hi:[1,0,0]
	v_pk_fma_f32 v[134:135], v[192:193], v[128:129], v[134:135] op_sel_hi:[1,0,1] neg_lo:[1,0,0] neg_hi:[1,0,0]
	v_pk_fma_f32 v[134:135], v[194:195], v[128:129], v[134:135] op_sel:[0,1,0] neg_lo:[1,0,0] neg_hi:[1,0,0]
	ds_read_b128 v[188:191], v228 offset:9392
	ds_read_b128 v[192:195], v228 offset:9408
	s_waitcnt lgkmcnt(14)
	v_pk_fma_f32 v[134:135], v[196:197], v[130:131], v[134:135] op_sel_hi:[1,0,1] neg_lo:[1,0,0] neg_hi:[1,0,0]
	v_pk_fma_f32 v[134:135], v[198:199], v[130:131], v[134:135] op_sel:[0,1,0] neg_lo:[1,0,0] neg_hi:[1,0,0]
	v_pk_fma_f32 v[134:135], v[200:201], v[132:133], v[134:135] op_sel_hi:[1,0,1] neg_lo:[1,0,0] neg_hi:[1,0,0]
	v_pk_fma_f32 v[134:135], v[202:203], v[132:133], v[134:135] op_sel:[0,1,0] neg_lo:[1,0,0] neg_hi:[1,0,0]
	ds_read_b128 v[196:199], v228 offset:9424
	ds_read_b128 v[200:203], v228 offset:9440
	s_waitcnt lgkmcnt(14)
	v_fma_f32 v135, -v205, v134, v135
	v_pk_fma_f32 v[136:137], v[208:209], v[100:101], v[136:137] op_sel_hi:[1,0,1] neg_lo:[1,0,0] neg_hi:[1,0,0]
	v_pk_fma_f32 v[136:137], v[210:211], v[100:101], v[136:137] op_sel:[0,1,0] neg_lo:[1,0,0] neg_hi:[1,0,0]
	ds_read_b128 v[204:207], v228 offset:9456
	ds_read_b128 v[208:211], v228 offset:9472
	s_waitcnt lgkmcnt(14)
	v_pk_fma_f32 v[136:137], v[212:213], v[102:103], v[136:137] op_sel_hi:[1,0,1] neg_lo:[1,0,0] neg_hi:[1,0,0]
	v_pk_fma_f32 v[136:137], v[214:215], v[102:103], v[136:137] op_sel:[0,1,0] neg_lo:[1,0,0] neg_hi:[1,0,0]
	v_pk_fma_f32 v[136:137], v[216:217], v[104:105], v[136:137] op_sel_hi:[1,0,1] neg_lo:[1,0,0] neg_hi:[1,0,0]
	v_pk_fma_f32 v[136:137], v[218:219], v[104:105], v[136:137] op_sel:[0,1,0] neg_lo:[1,0,0] neg_hi:[1,0,0]
	ds_read_b128 v[212:215], v228 offset:9488
	ds_read_b128 v[216:219], v228 offset:9504
	s_waitcnt lgkmcnt(14)
	v_pk_fma_f32 v[136:137], v[220:221], v[106:107], v[136:137] op_sel_hi:[1,0,1] neg_lo:[1,0,0] neg_hi:[1,0,0]
	v_pk_fma_f32 v[136:137], v[222:223], v[106:107], v[136:137] op_sel:[0,1,0] neg_lo:[1,0,0] neg_hi:[1,0,0]
	v_pk_fma_f32 v[136:137], v[224:225], v[108:109], v[136:137] op_sel_hi:[1,0,1] neg_lo:[1,0,0] neg_hi:[1,0,0]
	v_pk_fma_f32 v[136:137], v[226:227], v[108:109], v[136:137] op_sel:[0,1,0] neg_lo:[1,0,0] neg_hi:[1,0,0]
	ds_read_b128 v[220:223], v228 offset:9728
	ds_read_b128 v[224:227], v228 offset:9744
	s_waitcnt lgkmcnt(14)
	v_pk_fma_f32 v[136:137], v[164:165], v[110:111], v[136:137] op_sel_hi:[1,0,1] neg_lo:[1,0,0] neg_hi:[1,0,0]
	v_pk_fma_f32 v[136:137], v[166:167], v[110:111], v[136:137] op_sel:[0,1,0] neg_lo:[1,0,0] neg_hi:[1,0,0]
	v_pk_fma_f32 v[136:137], v[168:169], v[112:113], v[136:137] op_sel_hi:[1,0,1] neg_lo:[1,0,0] neg_hi:[1,0,0]
	v_pk_fma_f32 v[136:137], v[170:171], v[112:113], v[136:137] op_sel:[0,1,0] neg_lo:[1,0,0] neg_hi:[1,0,0]
	ds_read_b128 v[164:167], v228 offset:9760
	ds_read_b128 v[168:171], v228 offset:9776
	s_waitcnt lgkmcnt(14)
	v_pk_fma_f32 v[136:137], v[172:173], v[114:115], v[136:137] op_sel_hi:[1,0,1] neg_lo:[1,0,0] neg_hi:[1,0,0]
	v_pk_fma_f32 v[136:137], v[174:175], v[114:115], v[136:137] op_sel:[0,1,0] neg_lo:[1,0,0] neg_hi:[1,0,0]
	v_pk_fma_f32 v[136:137], v[176:177], v[116:117], v[136:137] op_sel_hi:[1,0,1] neg_lo:[1,0,0] neg_hi:[1,0,0]
	v_pk_fma_f32 v[136:137], v[178:179], v[116:117], v[136:137] op_sel:[0,1,0] neg_lo:[1,0,0] neg_hi:[1,0,0]
	ds_read_b128 v[172:175], v228 offset:9792
	ds_read_b128 v[176:179], v228 offset:9808
	s_waitcnt lgkmcnt(14)
	v_pk_fma_f32 v[136:137], v[180:181], v[118:119], v[136:137] op_sel_hi:[1,0,1] neg_lo:[1,0,0] neg_hi:[1,0,0]
	v_pk_fma_f32 v[136:137], v[182:183], v[118:119], v[136:137] op_sel:[0,1,0] neg_lo:[1,0,0] neg_hi:[1,0,0]
	v_pk_fma_f32 v[136:137], v[184:185], v[120:121], v[136:137] op_sel_hi:[1,0,1] neg_lo:[1,0,0] neg_hi:[1,0,0]
	v_pk_fma_f32 v[136:137], v[186:187], v[120:121], v[136:137] op_sel:[0,1,0] neg_lo:[1,0,0] neg_hi:[1,0,0]
	ds_read_b128 v[180:183], v228 offset:9824
	ds_read_b128 v[184:187], v228 offset:9840
	s_waitcnt lgkmcnt(14)
	v_pk_fma_f32 v[136:137], v[188:189], v[122:123], v[136:137] op_sel_hi:[1,0,1] neg_lo:[1,0,0] neg_hi:[1,0,0]
	v_pk_fma_f32 v[136:137], v[190:191], v[122:123], v[136:137] op_sel:[0,1,0] neg_lo:[1,0,0] neg_hi:[1,0,0]
	v_pk_fma_f32 v[136:137], v[192:193], v[124:125], v[136:137] op_sel_hi:[1,0,1] neg_lo:[1,0,0] neg_hi:[1,0,0]
	v_pk_fma_f32 v[136:137], v[194:195], v[124:125], v[136:137] op_sel:[0,1,0] neg_lo:[1,0,0] neg_hi:[1,0,0]
	ds_read_b128 v[188:191], v228 offset:9856
	ds_read_b128 v[192:195], v228 offset:9872
	s_waitcnt lgkmcnt(14)
	v_pk_fma_f32 v[136:137], v[196:197], v[126:127], v[136:137] op_sel_hi:[1,0,1] neg_lo:[1,0,0] neg_hi:[1,0,0]
	v_pk_fma_f32 v[136:137], v[198:199], v[126:127], v[136:137] op_sel:[0,1,0] neg_lo:[1,0,0] neg_hi:[1,0,0]
	v_pk_fma_f32 v[136:137], v[200:201], v[128:129], v[136:137] op_sel_hi:[1,0,1] neg_lo:[1,0,0] neg_hi:[1,0,0]
	v_pk_fma_f32 v[136:137], v[202:203], v[128:129], v[136:137] op_sel:[0,1,0] neg_lo:[1,0,0] neg_hi:[1,0,0]
	ds_read_b128 v[196:199], v228 offset:9888
	ds_read_b128 v[200:203], v228 offset:9904
	s_waitcnt lgkmcnt(14)
	v_pk_fma_f32 v[136:137], v[204:205], v[130:131], v[136:137] op_sel_hi:[1,0,1] neg_lo:[1,0,0] neg_hi:[1,0,0]
	v_pk_fma_f32 v[136:137], v[206:207], v[130:131], v[136:137] op_sel:[0,1,0] neg_lo:[1,0,0] neg_hi:[1,0,0]
	v_pk_fma_f32 v[136:137], v[208:209], v[132:133], v[136:137] op_sel_hi:[1,0,1] neg_lo:[1,0,0] neg_hi:[1,0,0]
	v_pk_fma_f32 v[136:137], v[210:211], v[132:133], v[136:137] op_sel:[0,1,0] neg_lo:[1,0,0] neg_hi:[1,0,0]
	ds_read_b128 v[204:207], v228 offset:9920
	ds_read_b128 v[208:211], v228 offset:9936
	s_waitcnt lgkmcnt(14)
	v_pk_fma_f32 v[136:137], v[212:213], v[134:135], v[136:137] op_sel_hi:[1,0,1] neg_lo:[1,0,0] neg_hi:[1,0,0]
	v_pk_fma_f32 v[136:137], v[214:215], v[134:135], v[136:137] op_sel:[0,1,0] neg_lo:[1,0,0] neg_hi:[1,0,0]
	v_fma_f32 v137, -v217, v136, v137
	ds_read_b128 v[212:215], v228 offset:9952
	ds_read_b128 v[216:219], v228 offset:9968
	s_waitcnt lgkmcnt(14)
	v_pk_fma_f32 v[138:139], v[220:221], v[100:101], v[138:139] op_sel_hi:[1,0,1] neg_lo:[1,0,0] neg_hi:[1,0,0]
	v_pk_fma_f32 v[138:139], v[222:223], v[100:101], v[138:139] op_sel:[0,1,0] neg_lo:[1,0,0] neg_hi:[1,0,0]
	v_pk_fma_f32 v[138:139], v[224:225], v[102:103], v[138:139] op_sel_hi:[1,0,1] neg_lo:[1,0,0] neg_hi:[1,0,0]
	v_pk_fma_f32 v[138:139], v[226:227], v[102:103], v[138:139] op_sel:[0,1,0] neg_lo:[1,0,0] neg_hi:[1,0,0]
	ds_read_b128 v[220:223], v228 offset:9984
	ds_read_b128 v[224:227], v228 offset:10000
	s_waitcnt lgkmcnt(14)
	v_pk_fma_f32 v[138:139], v[164:165], v[104:105], v[138:139] op_sel_hi:[1,0,1] neg_lo:[1,0,0] neg_hi:[1,0,0]
	v_pk_fma_f32 v[138:139], v[166:167], v[104:105], v[138:139] op_sel:[0,1,0] neg_lo:[1,0,0] neg_hi:[1,0,0]
	v_pk_fma_f32 v[138:139], v[168:169], v[106:107], v[138:139] op_sel_hi:[1,0,1] neg_lo:[1,0,0] neg_hi:[1,0,0]
	v_pk_fma_f32 v[138:139], v[170:171], v[106:107], v[138:139] op_sel:[0,1,0] neg_lo:[1,0,0] neg_hi:[1,0,0]
	ds_read_b128 v[164:167], v228 offset:10016
	ds_read_b128 v[168:171], v228 offset:10032
	s_waitcnt lgkmcnt(14)
	v_pk_fma_f32 v[138:139], v[172:173], v[108:109], v[138:139] op_sel_hi:[1,0,1] neg_lo:[1,0,0] neg_hi:[1,0,0]
	v_pk_fma_f32 v[138:139], v[174:175], v[108:109], v[138:139] op_sel:[0,1,0] neg_lo:[1,0,0] neg_hi:[1,0,0]
	v_pk_fma_f32 v[138:139], v[176:177], v[110:111], v[138:139] op_sel_hi:[1,0,1] neg_lo:[1,0,0] neg_hi:[1,0,0]
	v_pk_fma_f32 v[138:139], v[178:179], v[110:111], v[138:139] op_sel:[0,1,0] neg_lo:[1,0,0] neg_hi:[1,0,0]
	ds_read_b128 v[172:175], v228 offset:10240
	ds_read_b128 v[176:179], v228 offset:10256
	s_waitcnt lgkmcnt(14)
	v_pk_fma_f32 v[138:139], v[180:181], v[112:113], v[138:139] op_sel_hi:[1,0,1] neg_lo:[1,0,0] neg_hi:[1,0,0]
	v_pk_fma_f32 v[138:139], v[182:183], v[112:113], v[138:139] op_sel:[0,1,0] neg_lo:[1,0,0] neg_hi:[1,0,0]
	v_pk_fma_f32 v[138:139], v[184:185], v[114:115], v[138:139] op_sel_hi:[1,0,1] neg_lo:[1,0,0] neg_hi:[1,0,0]
	v_pk_fma_f32 v[138:139], v[186:187], v[114:115], v[138:139] op_sel:[0,1,0] neg_lo:[1,0,0] neg_hi:[1,0,0]
	ds_read_b128 v[180:183], v228 offset:10272
	ds_read_b128 v[184:187], v228 offset:10288
	s_waitcnt lgkmcnt(14)
	v_pk_fma_f32 v[138:139], v[188:189], v[116:117], v[138:139] op_sel_hi:[1,0,1] neg_lo:[1,0,0] neg_hi:[1,0,0]
	v_pk_fma_f32 v[138:139], v[190:191], v[116:117], v[138:139] op_sel:[0,1,0] neg_lo:[1,0,0] neg_hi:[1,0,0]
	v_pk_fma_f32 v[138:139], v[192:193], v[118:119], v[138:139] op_sel_hi:[1,0,1] neg_lo:[1,0,0] neg_hi:[1,0,0]
	v_pk_fma_f32 v[138:139], v[194:195], v[118:119], v[138:139] op_sel:[0,1,0] neg_lo:[1,0,0] neg_hi:[1,0,0]
	ds_read_b128 v[188:191], v228 offset:10304
	ds_read_b128 v[192:195], v228 offset:10320
	s_waitcnt lgkmcnt(14)
	v_pk_fma_f32 v[138:139], v[196:197], v[120:121], v[138:139] op_sel_hi:[1,0,1] neg_lo:[1,0,0] neg_hi:[1,0,0]
	v_pk_fma_f32 v[138:139], v[198:199], v[120:121], v[138:139] op_sel:[0,1,0] neg_lo:[1,0,0] neg_hi:[1,0,0]
	v_pk_fma_f32 v[138:139], v[200:201], v[122:123], v[138:139] op_sel_hi:[1,0,1] neg_lo:[1,0,0] neg_hi:[1,0,0]
	v_pk_fma_f32 v[138:139], v[202:203], v[122:123], v[138:139] op_sel:[0,1,0] neg_lo:[1,0,0] neg_hi:[1,0,0]
	ds_read_b128 v[196:199], v228 offset:10336
	ds_read_b128 v[200:203], v228 offset:10352
	s_waitcnt lgkmcnt(14)
	v_pk_fma_f32 v[138:139], v[204:205], v[124:125], v[138:139] op_sel_hi:[1,0,1] neg_lo:[1,0,0] neg_hi:[1,0,0]
	v_pk_fma_f32 v[138:139], v[206:207], v[124:125], v[138:139] op_sel:[0,1,0] neg_lo:[1,0,0] neg_hi:[1,0,0]
	v_pk_fma_f32 v[138:139], v[208:209], v[126:127], v[138:139] op_sel_hi:[1,0,1] neg_lo:[1,0,0] neg_hi:[1,0,0]
	v_pk_fma_f32 v[138:139], v[210:211], v[126:127], v[138:139] op_sel:[0,1,0] neg_lo:[1,0,0] neg_hi:[1,0,0]
	ds_read_b128 v[204:207], v228 offset:10368
	ds_read_b128 v[208:211], v228 offset:10384
	s_waitcnt lgkmcnt(14)
	v_pk_fma_f32 v[138:139], v[212:213], v[128:129], v[138:139] op_sel_hi:[1,0,1] neg_lo:[1,0,0] neg_hi:[1,0,0]
	v_pk_fma_f32 v[138:139], v[214:215], v[128:129], v[138:139] op_sel:[0,1,0] neg_lo:[1,0,0] neg_hi:[1,0,0]
	v_pk_fma_f32 v[138:139], v[216:217], v[130:131], v[138:139] op_sel_hi:[1,0,1] neg_lo:[1,0,0] neg_hi:[1,0,0]
	v_pk_fma_f32 v[138:139], v[218:219], v[130:131], v[138:139] op_sel:[0,1,0] neg_lo:[1,0,0] neg_hi:[1,0,0]
	ds_read_b128 v[212:215], v228 offset:10400
	ds_read_b128 v[216:219], v228 offset:10416
	s_waitcnt lgkmcnt(14)
	v_pk_fma_f32 v[138:139], v[220:221], v[132:133], v[138:139] op_sel_hi:[1,0,1] neg_lo:[1,0,0] neg_hi:[1,0,0]
	v_pk_fma_f32 v[138:139], v[222:223], v[132:133], v[138:139] op_sel:[0,1,0] neg_lo:[1,0,0] neg_hi:[1,0,0]
	v_pk_fma_f32 v[138:139], v[224:225], v[134:135], v[138:139] op_sel_hi:[1,0,1] neg_lo:[1,0,0] neg_hi:[1,0,0]
	v_pk_fma_f32 v[138:139], v[226:227], v[134:135], v[138:139] op_sel:[0,1,0] neg_lo:[1,0,0] neg_hi:[1,0,0]
	ds_read_b128 v[220:223], v228 offset:10432
	ds_read_b128 v[224:227], v228 offset:10448
	s_waitcnt lgkmcnt(14)
	v_pk_fma_f32 v[138:139], v[164:165], v[136:137], v[138:139] op_sel_hi:[1,0,1] neg_lo:[1,0,0] neg_hi:[1,0,0]
	v_pk_fma_f32 v[138:139], v[166:167], v[136:137], v[138:139] op_sel:[0,1,0] neg_lo:[1,0,0] neg_hi:[1,0,0]
	v_fma_f32 v139, -v169, v138, v139
	ds_read_b128 v[164:167], v228 offset:10464
	ds_read_b128 v[168:171], v228 offset:10480
	s_waitcnt lgkmcnt(14)
	v_pk_fma_f32 v[140:141], v[172:173], v[100:101], v[140:141] op_sel_hi:[1,0,1] neg_lo:[1,0,0] neg_hi:[1,0,0]
	v_pk_fma_f32 v[140:141], v[174:175], v[100:101], v[140:141] op_sel:[0,1,0] neg_lo:[1,0,0] neg_hi:[1,0,0]
	v_pk_fma_f32 v[140:141], v[176:177], v[102:103], v[140:141] op_sel_hi:[1,0,1] neg_lo:[1,0,0] neg_hi:[1,0,0]
	v_pk_fma_f32 v[140:141], v[178:179], v[102:103], v[140:141] op_sel:[0,1,0] neg_lo:[1,0,0] neg_hi:[1,0,0]
	ds_read_b128 v[172:175], v228 offset:10496
	ds_read_b128 v[176:179], v228 offset:10512
	s_waitcnt lgkmcnt(14)
	v_pk_fma_f32 v[140:141], v[180:181], v[104:105], v[140:141] op_sel_hi:[1,0,1] neg_lo:[1,0,0] neg_hi:[1,0,0]
	v_pk_fma_f32 v[140:141], v[182:183], v[104:105], v[140:141] op_sel:[0,1,0] neg_lo:[1,0,0] neg_hi:[1,0,0]
	v_pk_fma_f32 v[140:141], v[184:185], v[106:107], v[140:141] op_sel_hi:[1,0,1] neg_lo:[1,0,0] neg_hi:[1,0,0]
	v_pk_fma_f32 v[140:141], v[186:187], v[106:107], v[140:141] op_sel:[0,1,0] neg_lo:[1,0,0] neg_hi:[1,0,0]
	ds_read_b128 v[180:183], v228 offset:10528
	ds_read_b128 v[184:187], v228 offset:10544
	s_waitcnt lgkmcnt(14)
	v_pk_fma_f32 v[140:141], v[188:189], v[108:109], v[140:141] op_sel_hi:[1,0,1] neg_lo:[1,0,0] neg_hi:[1,0,0]
	v_pk_fma_f32 v[140:141], v[190:191], v[108:109], v[140:141] op_sel:[0,1,0] neg_lo:[1,0,0] neg_hi:[1,0,0]
	v_pk_fma_f32 v[140:141], v[192:193], v[110:111], v[140:141] op_sel_hi:[1,0,1] neg_lo:[1,0,0] neg_hi:[1,0,0]
	v_pk_fma_f32 v[140:141], v[194:195], v[110:111], v[140:141] op_sel:[0,1,0] neg_lo:[1,0,0] neg_hi:[1,0,0]
	ds_read_b128 v[188:191], v228 offset:10560
	ds_read_b128 v[192:195], v228 offset:10752
	s_waitcnt lgkmcnt(14)
	v_pk_fma_f32 v[140:141], v[196:197], v[112:113], v[140:141] op_sel_hi:[1,0,1] neg_lo:[1,0,0] neg_hi:[1,0,0]
	v_pk_fma_f32 v[140:141], v[198:199], v[112:113], v[140:141] op_sel:[0,1,0] neg_lo:[1,0,0] neg_hi:[1,0,0]
	v_pk_fma_f32 v[140:141], v[200:201], v[114:115], v[140:141] op_sel_hi:[1,0,1] neg_lo:[1,0,0] neg_hi:[1,0,0]
	v_pk_fma_f32 v[140:141], v[202:203], v[114:115], v[140:141] op_sel:[0,1,0] neg_lo:[1,0,0] neg_hi:[1,0,0]
	ds_read_b128 v[196:199], v228 offset:10768
	ds_read_b128 v[200:203], v228 offset:10784
	s_waitcnt lgkmcnt(14)
	v_pk_fma_f32 v[140:141], v[204:205], v[116:117], v[140:141] op_sel_hi:[1,0,1] neg_lo:[1,0,0] neg_hi:[1,0,0]
	v_pk_fma_f32 v[140:141], v[206:207], v[116:117], v[140:141] op_sel:[0,1,0] neg_lo:[1,0,0] neg_hi:[1,0,0]
	v_pk_fma_f32 v[140:141], v[208:209], v[118:119], v[140:141] op_sel_hi:[1,0,1] neg_lo:[1,0,0] neg_hi:[1,0,0]
	v_pk_fma_f32 v[140:141], v[210:211], v[118:119], v[140:141] op_sel:[0,1,0] neg_lo:[1,0,0] neg_hi:[1,0,0]
	ds_read_b128 v[204:207], v228 offset:10800
	ds_read_b128 v[208:211], v228 offset:10816
	s_waitcnt lgkmcnt(14)
	v_pk_fma_f32 v[140:141], v[212:213], v[120:121], v[140:141] op_sel_hi:[1,0,1] neg_lo:[1,0,0] neg_hi:[1,0,0]
	v_pk_fma_f32 v[140:141], v[214:215], v[120:121], v[140:141] op_sel:[0,1,0] neg_lo:[1,0,0] neg_hi:[1,0,0]
	v_pk_fma_f32 v[140:141], v[216:217], v[122:123], v[140:141] op_sel_hi:[1,0,1] neg_lo:[1,0,0] neg_hi:[1,0,0]
	v_pk_fma_f32 v[140:141], v[218:219], v[122:123], v[140:141] op_sel:[0,1,0] neg_lo:[1,0,0] neg_hi:[1,0,0]
	ds_read_b128 v[212:215], v228 offset:10832
	ds_read_b128 v[216:219], v228 offset:10848
	s_waitcnt lgkmcnt(14)
	v_pk_fma_f32 v[140:141], v[220:221], v[124:125], v[140:141] op_sel_hi:[1,0,1] neg_lo:[1,0,0] neg_hi:[1,0,0]
	v_pk_fma_f32 v[140:141], v[222:223], v[124:125], v[140:141] op_sel:[0,1,0] neg_lo:[1,0,0] neg_hi:[1,0,0]
	v_pk_fma_f32 v[140:141], v[224:225], v[126:127], v[140:141] op_sel_hi:[1,0,1] neg_lo:[1,0,0] neg_hi:[1,0,0]
	v_pk_fma_f32 v[140:141], v[226:227], v[126:127], v[140:141] op_sel:[0,1,0] neg_lo:[1,0,0] neg_hi:[1,0,0]
	ds_read_b128 v[220:223], v228 offset:10864
	ds_read_b128 v[224:227], v228 offset:10880
	s_waitcnt lgkmcnt(14)
	v_pk_fma_f32 v[140:141], v[164:165], v[128:129], v[140:141] op_sel_hi:[1,0,1] neg_lo:[1,0,0] neg_hi:[1,0,0]
	v_pk_fma_f32 v[140:141], v[166:167], v[128:129], v[140:141] op_sel:[0,1,0] neg_lo:[1,0,0] neg_hi:[1,0,0]
	v_pk_fma_f32 v[140:141], v[168:169], v[130:131], v[140:141] op_sel_hi:[1,0,1] neg_lo:[1,0,0] neg_hi:[1,0,0]
	v_pk_fma_f32 v[140:141], v[170:171], v[130:131], v[140:141] op_sel:[0,1,0] neg_lo:[1,0,0] neg_hi:[1,0,0]
	ds_read_b128 v[164:167], v228 offset:10896
	ds_read_b128 v[168:171], v228 offset:10912
	s_waitcnt lgkmcnt(14)
	v_pk_fma_f32 v[140:141], v[172:173], v[132:133], v[140:141] op_sel_hi:[1,0,1] neg_lo:[1,0,0] neg_hi:[1,0,0]
	v_pk_fma_f32 v[140:141], v[174:175], v[132:133], v[140:141] op_sel:[0,1,0] neg_lo:[1,0,0] neg_hi:[1,0,0]
	v_pk_fma_f32 v[140:141], v[176:177], v[134:135], v[140:141] op_sel_hi:[1,0,1] neg_lo:[1,0,0] neg_hi:[1,0,0]
	v_pk_fma_f32 v[140:141], v[178:179], v[134:135], v[140:141] op_sel:[0,1,0] neg_lo:[1,0,0] neg_hi:[1,0,0]
	ds_read_b128 v[172:175], v228 offset:10928
	ds_read_b128 v[176:179], v228 offset:10944
	s_waitcnt lgkmcnt(14)
	v_pk_fma_f32 v[140:141], v[180:181], v[136:137], v[140:141] op_sel_hi:[1,0,1] neg_lo:[1,0,0] neg_hi:[1,0,0]
	v_pk_fma_f32 v[140:141], v[182:183], v[136:137], v[140:141] op_sel:[0,1,0] neg_lo:[1,0,0] neg_hi:[1,0,0]
	v_pk_fma_f32 v[140:141], v[184:185], v[138:139], v[140:141] op_sel_hi:[1,0,1] neg_lo:[1,0,0] neg_hi:[1,0,0]
	v_pk_fma_f32 v[140:141], v[186:187], v[138:139], v[140:141] op_sel:[0,1,0] neg_lo:[1,0,0] neg_hi:[1,0,0]
	ds_read_b128 v[180:183], v228 offset:10960
	ds_read_b128 v[184:187], v228 offset:10976
	s_waitcnt lgkmcnt(14)
	v_fma_f32 v141, -v189, v140, v141
	v_pk_fma_f32 v[142:143], v[192:193], v[100:101], v[142:143] op_sel_hi:[1,0,1] neg_lo:[1,0,0] neg_hi:[1,0,0]
	v_pk_fma_f32 v[142:143], v[194:195], v[100:101], v[142:143] op_sel:[0,1,0] neg_lo:[1,0,0] neg_hi:[1,0,0]
	ds_read_b128 v[188:191], v228 offset:10992
	ds_read_b128 v[192:195], v228 offset:11008
	s_waitcnt lgkmcnt(14)
	v_pk_fma_f32 v[142:143], v[196:197], v[102:103], v[142:143] op_sel_hi:[1,0,1] neg_lo:[1,0,0] neg_hi:[1,0,0]
	v_pk_fma_f32 v[142:143], v[198:199], v[102:103], v[142:143] op_sel:[0,1,0] neg_lo:[1,0,0] neg_hi:[1,0,0]
	v_pk_fma_f32 v[142:143], v[200:201], v[104:105], v[142:143] op_sel_hi:[1,0,1] neg_lo:[1,0,0] neg_hi:[1,0,0]
	v_pk_fma_f32 v[142:143], v[202:203], v[104:105], v[142:143] op_sel:[0,1,0] neg_lo:[1,0,0] neg_hi:[1,0,0]
	ds_read_b128 v[196:199], v228 offset:11024
	ds_read_b128 v[200:203], v228 offset:11040
	s_waitcnt lgkmcnt(14)
	v_pk_fma_f32 v[142:143], v[204:205], v[106:107], v[142:143] op_sel_hi:[1,0,1] neg_lo:[1,0,0] neg_hi:[1,0,0]
	v_pk_fma_f32 v[142:143], v[206:207], v[106:107], v[142:143] op_sel:[0,1,0] neg_lo:[1,0,0] neg_hi:[1,0,0]
	v_pk_fma_f32 v[142:143], v[208:209], v[108:109], v[142:143] op_sel_hi:[1,0,1] neg_lo:[1,0,0] neg_hi:[1,0,0]
	v_pk_fma_f32 v[142:143], v[210:211], v[108:109], v[142:143] op_sel:[0,1,0] neg_lo:[1,0,0] neg_hi:[1,0,0]
	ds_read_b128 v[204:207], v228 offset:11056
	ds_read_b128 v[208:211], v228 offset:11072
	s_waitcnt lgkmcnt(14)
	v_pk_fma_f32 v[142:143], v[212:213], v[110:111], v[142:143] op_sel_hi:[1,0,1] neg_lo:[1,0,0] neg_hi:[1,0,0]
	v_pk_fma_f32 v[142:143], v[214:215], v[110:111], v[142:143] op_sel:[0,1,0] neg_lo:[1,0,0] neg_hi:[1,0,0]
	v_pk_fma_f32 v[142:143], v[216:217], v[112:113], v[142:143] op_sel_hi:[1,0,1] neg_lo:[1,0,0] neg_hi:[1,0,0]
	v_pk_fma_f32 v[142:143], v[218:219], v[112:113], v[142:143] op_sel:[0,1,0] neg_lo:[1,0,0] neg_hi:[1,0,0]
	ds_read_b128 v[212:215], v228 offset:11088
	ds_read_b128 v[216:219], v228 offset:11264
	s_waitcnt lgkmcnt(14)
	v_pk_fma_f32 v[142:143], v[220:221], v[114:115], v[142:143] op_sel_hi:[1,0,1] neg_lo:[1,0,0] neg_hi:[1,0,0]
	v_pk_fma_f32 v[142:143], v[222:223], v[114:115], v[142:143] op_sel:[0,1,0] neg_lo:[1,0,0] neg_hi:[1,0,0]
	v_pk_fma_f32 v[142:143], v[224:225], v[116:117], v[142:143] op_sel_hi:[1,0,1] neg_lo:[1,0,0] neg_hi:[1,0,0]
	v_pk_fma_f32 v[142:143], v[226:227], v[116:117], v[142:143] op_sel:[0,1,0] neg_lo:[1,0,0] neg_hi:[1,0,0]
	ds_read_b128 v[220:223], v228 offset:11280
	ds_read_b128 v[224:227], v228 offset:11296
	s_waitcnt lgkmcnt(14)
	v_pk_fma_f32 v[142:143], v[164:165], v[118:119], v[142:143] op_sel_hi:[1,0,1] neg_lo:[1,0,0] neg_hi:[1,0,0]
	v_pk_fma_f32 v[142:143], v[166:167], v[118:119], v[142:143] op_sel:[0,1,0] neg_lo:[1,0,0] neg_hi:[1,0,0]
	v_pk_fma_f32 v[142:143], v[168:169], v[120:121], v[142:143] op_sel_hi:[1,0,1] neg_lo:[1,0,0] neg_hi:[1,0,0]
	v_pk_fma_f32 v[142:143], v[170:171], v[120:121], v[142:143] op_sel:[0,1,0] neg_lo:[1,0,0] neg_hi:[1,0,0]
	ds_read_b128 v[164:167], v228 offset:11312
	ds_read_b128 v[168:171], v228 offset:11328
	s_waitcnt lgkmcnt(14)
	v_pk_fma_f32 v[142:143], v[172:173], v[122:123], v[142:143] op_sel_hi:[1,0,1] neg_lo:[1,0,0] neg_hi:[1,0,0]
	v_pk_fma_f32 v[142:143], v[174:175], v[122:123], v[142:143] op_sel:[0,1,0] neg_lo:[1,0,0] neg_hi:[1,0,0]
	v_pk_fma_f32 v[142:143], v[176:177], v[124:125], v[142:143] op_sel_hi:[1,0,1] neg_lo:[1,0,0] neg_hi:[1,0,0]
	v_pk_fma_f32 v[142:143], v[178:179], v[124:125], v[142:143] op_sel:[0,1,0] neg_lo:[1,0,0] neg_hi:[1,0,0]
	ds_read_b128 v[172:175], v228 offset:11344
	ds_read_b128 v[176:179], v228 offset:11360
	s_waitcnt lgkmcnt(14)
	v_pk_fma_f32 v[142:143], v[180:181], v[126:127], v[142:143] op_sel_hi:[1,0,1] neg_lo:[1,0,0] neg_hi:[1,0,0]
	v_pk_fma_f32 v[142:143], v[182:183], v[126:127], v[142:143] op_sel:[0,1,0] neg_lo:[1,0,0] neg_hi:[1,0,0]
	v_pk_fma_f32 v[142:143], v[184:185], v[128:129], v[142:143] op_sel_hi:[1,0,1] neg_lo:[1,0,0] neg_hi:[1,0,0]
	v_pk_fma_f32 v[142:143], v[186:187], v[128:129], v[142:143] op_sel:[0,1,0] neg_lo:[1,0,0] neg_hi:[1,0,0]
	ds_read_b128 v[180:183], v228 offset:11376
	ds_read_b128 v[184:187], v228 offset:11392
	s_waitcnt lgkmcnt(14)
	v_pk_fma_f32 v[142:143], v[188:189], v[130:131], v[142:143] op_sel_hi:[1,0,1] neg_lo:[1,0,0] neg_hi:[1,0,0]
	v_pk_fma_f32 v[142:143], v[190:191], v[130:131], v[142:143] op_sel:[0,1,0] neg_lo:[1,0,0] neg_hi:[1,0,0]
	v_pk_fma_f32 v[142:143], v[192:193], v[132:133], v[142:143] op_sel_hi:[1,0,1] neg_lo:[1,0,0] neg_hi:[1,0,0]
	v_pk_fma_f32 v[142:143], v[194:195], v[132:133], v[142:143] op_sel:[0,1,0] neg_lo:[1,0,0] neg_hi:[1,0,0]
	ds_read_b128 v[188:191], v228 offset:11408
	ds_read_b128 v[192:195], v228 offset:11424
	s_waitcnt lgkmcnt(14)
	v_pk_fma_f32 v[142:143], v[196:197], v[134:135], v[142:143] op_sel_hi:[1,0,1] neg_lo:[1,0,0] neg_hi:[1,0,0]
	v_pk_fma_f32 v[142:143], v[198:199], v[134:135], v[142:143] op_sel:[0,1,0] neg_lo:[1,0,0] neg_hi:[1,0,0]
	v_pk_fma_f32 v[142:143], v[200:201], v[136:137], v[142:143] op_sel_hi:[1,0,1] neg_lo:[1,0,0] neg_hi:[1,0,0]
	v_pk_fma_f32 v[142:143], v[202:203], v[136:137], v[142:143] op_sel:[0,1,0] neg_lo:[1,0,0] neg_hi:[1,0,0]
	ds_read_b128 v[196:199], v228 offset:11440
	ds_read_b128 v[200:203], v228 offset:11456
	s_waitcnt lgkmcnt(14)
	v_pk_fma_f32 v[142:143], v[204:205], v[138:139], v[142:143] op_sel_hi:[1,0,1] neg_lo:[1,0,0] neg_hi:[1,0,0]
	v_pk_fma_f32 v[142:143], v[206:207], v[138:139], v[142:143] op_sel:[0,1,0] neg_lo:[1,0,0] neg_hi:[1,0,0]
	v_pk_fma_f32 v[142:143], v[208:209], v[140:141], v[142:143] op_sel_hi:[1,0,1] neg_lo:[1,0,0] neg_hi:[1,0,0]
	v_pk_fma_f32 v[142:143], v[210:211], v[140:141], v[142:143] op_sel:[0,1,0] neg_lo:[1,0,0] neg_hi:[1,0,0]
	ds_read_b128 v[204:207], v228 offset:11472
	ds_read_b128 v[208:211], v228 offset:11488
	s_waitcnt lgkmcnt(14)
	v_fma_f32 v143, -v213, v142, v143
	v_pk_fma_f32 v[144:145], v[216:217], v[100:101], v[144:145] op_sel_hi:[1,0,1] neg_lo:[1,0,0] neg_hi:[1,0,0]
	v_pk_fma_f32 v[144:145], v[218:219], v[100:101], v[144:145] op_sel:[0,1,0] neg_lo:[1,0,0] neg_hi:[1,0,0]
	ds_read_b128 v[212:215], v228 offset:11504
	ds_read_b128 v[216:219], v228 offset:11520
	s_waitcnt lgkmcnt(14)
	v_pk_fma_f32 v[144:145], v[220:221], v[102:103], v[144:145] op_sel_hi:[1,0,1] neg_lo:[1,0,0] neg_hi:[1,0,0]
	v_pk_fma_f32 v[144:145], v[222:223], v[102:103], v[144:145] op_sel:[0,1,0] neg_lo:[1,0,0] neg_hi:[1,0,0]
	v_pk_fma_f32 v[144:145], v[224:225], v[104:105], v[144:145] op_sel_hi:[1,0,1] neg_lo:[1,0,0] neg_hi:[1,0,0]
	v_pk_fma_f32 v[144:145], v[226:227], v[104:105], v[144:145] op_sel:[0,1,0] neg_lo:[1,0,0] neg_hi:[1,0,0]
	ds_read_b128 v[220:223], v228 offset:11536
	ds_read_b128 v[224:227], v228 offset:11552
	s_waitcnt lgkmcnt(14)
	v_pk_fma_f32 v[144:145], v[164:165], v[106:107], v[144:145] op_sel_hi:[1,0,1] neg_lo:[1,0,0] neg_hi:[1,0,0]
	v_pk_fma_f32 v[144:145], v[166:167], v[106:107], v[144:145] op_sel:[0,1,0] neg_lo:[1,0,0] neg_hi:[1,0,0]
	v_pk_fma_f32 v[144:145], v[168:169], v[108:109], v[144:145] op_sel_hi:[1,0,1] neg_lo:[1,0,0] neg_hi:[1,0,0]
	v_pk_fma_f32 v[144:145], v[170:171], v[108:109], v[144:145] op_sel:[0,1,0] neg_lo:[1,0,0] neg_hi:[1,0,0]
	ds_read_b128 v[164:167], v228 offset:11568
	ds_read_b128 v[168:171], v228 offset:11584
	s_waitcnt lgkmcnt(14)
	v_pk_fma_f32 v[144:145], v[172:173], v[110:111], v[144:145] op_sel_hi:[1,0,1] neg_lo:[1,0,0] neg_hi:[1,0,0]
	v_pk_fma_f32 v[144:145], v[174:175], v[110:111], v[144:145] op_sel:[0,1,0] neg_lo:[1,0,0] neg_hi:[1,0,0]
	v_pk_fma_f32 v[144:145], v[176:177], v[112:113], v[144:145] op_sel_hi:[1,0,1] neg_lo:[1,0,0] neg_hi:[1,0,0]
	v_pk_fma_f32 v[144:145], v[178:179], v[112:113], v[144:145] op_sel:[0,1,0] neg_lo:[1,0,0] neg_hi:[1,0,0]
	ds_read_b128 v[172:175], v228 offset:11600
	ds_read_b128 v[176:179], v228 offset:11616
	s_waitcnt lgkmcnt(14)
	v_pk_fma_f32 v[144:145], v[180:181], v[114:115], v[144:145] op_sel_hi:[1,0,1] neg_lo:[1,0,0] neg_hi:[1,0,0]
	v_pk_fma_f32 v[144:145], v[182:183], v[114:115], v[144:145] op_sel:[0,1,0] neg_lo:[1,0,0] neg_hi:[1,0,0]
	v_pk_fma_f32 v[144:145], v[184:185], v[116:117], v[144:145] op_sel_hi:[1,0,1] neg_lo:[1,0,0] neg_hi:[1,0,0]
	v_pk_fma_f32 v[144:145], v[186:187], v[116:117], v[144:145] op_sel:[0,1,0] neg_lo:[1,0,0] neg_hi:[1,0,0]
	ds_read_b128 v[180:183], v228 offset:11776
	ds_read_b128 v[184:187], v228 offset:11792
	s_waitcnt lgkmcnt(14)
	v_pk_fma_f32 v[144:145], v[188:189], v[118:119], v[144:145] op_sel_hi:[1,0,1] neg_lo:[1,0,0] neg_hi:[1,0,0]
	v_pk_fma_f32 v[144:145], v[190:191], v[118:119], v[144:145] op_sel:[0,1,0] neg_lo:[1,0,0] neg_hi:[1,0,0]
	v_pk_fma_f32 v[144:145], v[192:193], v[120:121], v[144:145] op_sel_hi:[1,0,1] neg_lo:[1,0,0] neg_hi:[1,0,0]
	v_pk_fma_f32 v[144:145], v[194:195], v[120:121], v[144:145] op_sel:[0,1,0] neg_lo:[1,0,0] neg_hi:[1,0,0]
	ds_read_b128 v[188:191], v228 offset:11808
	ds_read_b128 v[192:195], v228 offset:11824
	s_waitcnt lgkmcnt(14)
	v_pk_fma_f32 v[144:145], v[196:197], v[122:123], v[144:145] op_sel_hi:[1,0,1] neg_lo:[1,0,0] neg_hi:[1,0,0]
	v_pk_fma_f32 v[144:145], v[198:199], v[122:123], v[144:145] op_sel:[0,1,0] neg_lo:[1,0,0] neg_hi:[1,0,0]
	v_pk_fma_f32 v[144:145], v[200:201], v[124:125], v[144:145] op_sel_hi:[1,0,1] neg_lo:[1,0,0] neg_hi:[1,0,0]
	v_pk_fma_f32 v[144:145], v[202:203], v[124:125], v[144:145] op_sel:[0,1,0] neg_lo:[1,0,0] neg_hi:[1,0,0]
	ds_read_b128 v[196:199], v228 offset:11840
	ds_read_b128 v[200:203], v228 offset:11856
	s_waitcnt lgkmcnt(14)
	v_pk_fma_f32 v[144:145], v[204:205], v[126:127], v[144:145] op_sel_hi:[1,0,1] neg_lo:[1,0,0] neg_hi:[1,0,0]
	v_pk_fma_f32 v[144:145], v[206:207], v[126:127], v[144:145] op_sel:[0,1,0] neg_lo:[1,0,0] neg_hi:[1,0,0]
	v_pk_fma_f32 v[144:145], v[208:209], v[128:129], v[144:145] op_sel_hi:[1,0,1] neg_lo:[1,0,0] neg_hi:[1,0,0]
	v_pk_fma_f32 v[144:145], v[210:211], v[128:129], v[144:145] op_sel:[0,1,0] neg_lo:[1,0,0] neg_hi:[1,0,0]
	ds_read_b128 v[204:207], v228 offset:11872
	ds_read_b128 v[208:211], v228 offset:11888
	s_waitcnt lgkmcnt(14)
	v_pk_fma_f32 v[144:145], v[212:213], v[130:131], v[144:145] op_sel_hi:[1,0,1] neg_lo:[1,0,0] neg_hi:[1,0,0]
	v_pk_fma_f32 v[144:145], v[214:215], v[130:131], v[144:145] op_sel:[0,1,0] neg_lo:[1,0,0] neg_hi:[1,0,0]
	v_pk_fma_f32 v[144:145], v[216:217], v[132:133], v[144:145] op_sel_hi:[1,0,1] neg_lo:[1,0,0] neg_hi:[1,0,0]
	v_pk_fma_f32 v[144:145], v[218:219], v[132:133], v[144:145] op_sel:[0,1,0] neg_lo:[1,0,0] neg_hi:[1,0,0]
	ds_read_b128 v[212:215], v228 offset:11904
	ds_read_b128 v[216:219], v228 offset:11920
	s_waitcnt lgkmcnt(14)
	v_pk_fma_f32 v[144:145], v[220:221], v[134:135], v[144:145] op_sel_hi:[1,0,1] neg_lo:[1,0,0] neg_hi:[1,0,0]
	v_pk_fma_f32 v[144:145], v[222:223], v[134:135], v[144:145] op_sel:[0,1,0] neg_lo:[1,0,0] neg_hi:[1,0,0]
	v_pk_fma_f32 v[144:145], v[224:225], v[136:137], v[144:145] op_sel_hi:[1,0,1] neg_lo:[1,0,0] neg_hi:[1,0,0]
	v_pk_fma_f32 v[144:145], v[226:227], v[136:137], v[144:145] op_sel:[0,1,0] neg_lo:[1,0,0] neg_hi:[1,0,0]
	ds_read_b128 v[220:223], v228 offset:11936
	ds_read_b128 v[224:227], v228 offset:11952
	s_waitcnt lgkmcnt(14)
	v_pk_fma_f32 v[144:145], v[164:165], v[138:139], v[144:145] op_sel_hi:[1,0,1] neg_lo:[1,0,0] neg_hi:[1,0,0]
	v_pk_fma_f32 v[144:145], v[166:167], v[138:139], v[144:145] op_sel:[0,1,0] neg_lo:[1,0,0] neg_hi:[1,0,0]
	v_pk_fma_f32 v[144:145], v[168:169], v[140:141], v[144:145] op_sel_hi:[1,0,1] neg_lo:[1,0,0] neg_hi:[1,0,0]
	v_pk_fma_f32 v[144:145], v[170:171], v[140:141], v[144:145] op_sel:[0,1,0] neg_lo:[1,0,0] neg_hi:[1,0,0]
	ds_read_b128 v[164:167], v228 offset:11968
	ds_read_b128 v[168:171], v228 offset:11984
	s_waitcnt lgkmcnt(14)
	v_pk_fma_f32 v[144:145], v[172:173], v[142:143], v[144:145] op_sel_hi:[1,0,1] neg_lo:[1,0,0] neg_hi:[1,0,0]
	v_pk_fma_f32 v[144:145], v[174:175], v[142:143], v[144:145] op_sel:[0,1,0] neg_lo:[1,0,0] neg_hi:[1,0,0]
	v_fma_f32 v145, -v177, v144, v145
	ds_read_b128 v[172:175], v228 offset:12000
	ds_read_b128 v[176:179], v228 offset:12016
	s_waitcnt lgkmcnt(14)
	v_pk_fma_f32 v[146:147], v[180:181], v[100:101], v[146:147] op_sel_hi:[1,0,1] neg_lo:[1,0,0] neg_hi:[1,0,0]
	v_pk_fma_f32 v[146:147], v[182:183], v[100:101], v[146:147] op_sel:[0,1,0] neg_lo:[1,0,0] neg_hi:[1,0,0]
	v_pk_fma_f32 v[146:147], v[184:185], v[102:103], v[146:147] op_sel_hi:[1,0,1] neg_lo:[1,0,0] neg_hi:[1,0,0]
	v_pk_fma_f32 v[146:147], v[186:187], v[102:103], v[146:147] op_sel:[0,1,0] neg_lo:[1,0,0] neg_hi:[1,0,0]
	ds_read_b128 v[180:183], v228 offset:12032
	ds_read_b128 v[184:187], v228 offset:12048
	s_waitcnt lgkmcnt(14)
	v_pk_fma_f32 v[146:147], v[188:189], v[104:105], v[146:147] op_sel_hi:[1,0,1] neg_lo:[1,0,0] neg_hi:[1,0,0]
	v_pk_fma_f32 v[146:147], v[190:191], v[104:105], v[146:147] op_sel:[0,1,0] neg_lo:[1,0,0] neg_hi:[1,0,0]
	v_pk_fma_f32 v[146:147], v[192:193], v[106:107], v[146:147] op_sel_hi:[1,0,1] neg_lo:[1,0,0] neg_hi:[1,0,0]
	v_pk_fma_f32 v[146:147], v[194:195], v[106:107], v[146:147] op_sel:[0,1,0] neg_lo:[1,0,0] neg_hi:[1,0,0]
	ds_read_b128 v[188:191], v228 offset:12064
	ds_read_b128 v[192:195], v228 offset:12080
	s_waitcnt lgkmcnt(14)
	v_pk_fma_f32 v[146:147], v[196:197], v[108:109], v[146:147] op_sel_hi:[1,0,1] neg_lo:[1,0,0] neg_hi:[1,0,0]
	v_pk_fma_f32 v[146:147], v[198:199], v[108:109], v[146:147] op_sel:[0,1,0] neg_lo:[1,0,0] neg_hi:[1,0,0]
	v_pk_fma_f32 v[146:147], v[200:201], v[110:111], v[146:147] op_sel_hi:[1,0,1] neg_lo:[1,0,0] neg_hi:[1,0,0]
	v_pk_fma_f32 v[146:147], v[202:203], v[110:111], v[146:147] op_sel:[0,1,0] neg_lo:[1,0,0] neg_hi:[1,0,0]
	ds_read_b128 v[196:199], v228 offset:12096
	ds_read_b128 v[200:203], v228 offset:12112
	s_waitcnt lgkmcnt(14)
	v_pk_fma_f32 v[146:147], v[204:205], v[112:113], v[146:147] op_sel_hi:[1,0,1] neg_lo:[1,0,0] neg_hi:[1,0,0]
	v_pk_fma_f32 v[146:147], v[206:207], v[112:113], v[146:147] op_sel:[0,1,0] neg_lo:[1,0,0] neg_hi:[1,0,0]
	v_pk_fma_f32 v[146:147], v[208:209], v[114:115], v[146:147] op_sel_hi:[1,0,1] neg_lo:[1,0,0] neg_hi:[1,0,0]
	v_pk_fma_f32 v[146:147], v[210:211], v[114:115], v[146:147] op_sel:[0,1,0] neg_lo:[1,0,0] neg_hi:[1,0,0]
	ds_read_b128 v[204:207], v228 offset:12128
	ds_read_b128 v[208:211], v228 offset:12144
	s_waitcnt lgkmcnt(14)
	v_pk_fma_f32 v[146:147], v[212:213], v[116:117], v[146:147] op_sel_hi:[1,0,1] neg_lo:[1,0,0] neg_hi:[1,0,0]
	v_pk_fma_f32 v[146:147], v[214:215], v[116:117], v[146:147] op_sel:[0,1,0] neg_lo:[1,0,0] neg_hi:[1,0,0]
	v_pk_fma_f32 v[146:147], v[216:217], v[118:119], v[146:147] op_sel_hi:[1,0,1] neg_lo:[1,0,0] neg_hi:[1,0,0]
	v_pk_fma_f32 v[146:147], v[218:219], v[118:119], v[146:147] op_sel:[0,1,0] neg_lo:[1,0,0] neg_hi:[1,0,0]
	ds_read_b128 v[212:215], v228 offset:12288
	ds_read_b128 v[216:219], v228 offset:12304
	s_waitcnt lgkmcnt(14)
	v_pk_fma_f32 v[146:147], v[220:221], v[120:121], v[146:147] op_sel_hi:[1,0,1] neg_lo:[1,0,0] neg_hi:[1,0,0]
	v_pk_fma_f32 v[146:147], v[222:223], v[120:121], v[146:147] op_sel:[0,1,0] neg_lo:[1,0,0] neg_hi:[1,0,0]
	v_pk_fma_f32 v[146:147], v[224:225], v[122:123], v[146:147] op_sel_hi:[1,0,1] neg_lo:[1,0,0] neg_hi:[1,0,0]
	v_pk_fma_f32 v[146:147], v[226:227], v[122:123], v[146:147] op_sel:[0,1,0] neg_lo:[1,0,0] neg_hi:[1,0,0]
	ds_read_b128 v[220:223], v228 offset:12320
	ds_read_b128 v[224:227], v228 offset:12336
	s_waitcnt lgkmcnt(14)
	v_pk_fma_f32 v[146:147], v[164:165], v[124:125], v[146:147] op_sel_hi:[1,0,1] neg_lo:[1,0,0] neg_hi:[1,0,0]
	v_pk_fma_f32 v[146:147], v[166:167], v[124:125], v[146:147] op_sel:[0,1,0] neg_lo:[1,0,0] neg_hi:[1,0,0]
	v_pk_fma_f32 v[146:147], v[168:169], v[126:127], v[146:147] op_sel_hi:[1,0,1] neg_lo:[1,0,0] neg_hi:[1,0,0]
	v_pk_fma_f32 v[146:147], v[170:171], v[126:127], v[146:147] op_sel:[0,1,0] neg_lo:[1,0,0] neg_hi:[1,0,0]
	ds_read_b128 v[164:167], v228 offset:12352
	ds_read_b128 v[168:171], v228 offset:12368
	s_waitcnt lgkmcnt(14)
	v_pk_fma_f32 v[146:147], v[172:173], v[128:129], v[146:147] op_sel_hi:[1,0,1] neg_lo:[1,0,0] neg_hi:[1,0,0]
	v_pk_fma_f32 v[146:147], v[174:175], v[128:129], v[146:147] op_sel:[0,1,0] neg_lo:[1,0,0] neg_hi:[1,0,0]
	v_pk_fma_f32 v[146:147], v[176:177], v[130:131], v[146:147] op_sel_hi:[1,0,1] neg_lo:[1,0,0] neg_hi:[1,0,0]
	v_pk_fma_f32 v[146:147], v[178:179], v[130:131], v[146:147] op_sel:[0,1,0] neg_lo:[1,0,0] neg_hi:[1,0,0]
	ds_read_b128 v[172:175], v228 offset:12384
	ds_read_b128 v[176:179], v228 offset:12400
	s_waitcnt lgkmcnt(14)
	v_pk_fma_f32 v[146:147], v[180:181], v[132:133], v[146:147] op_sel_hi:[1,0,1] neg_lo:[1,0,0] neg_hi:[1,0,0]
	v_pk_fma_f32 v[146:147], v[182:183], v[132:133], v[146:147] op_sel:[0,1,0] neg_lo:[1,0,0] neg_hi:[1,0,0]
	v_pk_fma_f32 v[146:147], v[184:185], v[134:135], v[146:147] op_sel_hi:[1,0,1] neg_lo:[1,0,0] neg_hi:[1,0,0]
	v_pk_fma_f32 v[146:147], v[186:187], v[134:135], v[146:147] op_sel:[0,1,0] neg_lo:[1,0,0] neg_hi:[1,0,0]
	ds_read_b128 v[180:183], v228 offset:12416
	ds_read_b128 v[184:187], v228 offset:12432
	s_waitcnt lgkmcnt(14)
	v_pk_fma_f32 v[146:147], v[188:189], v[136:137], v[146:147] op_sel_hi:[1,0,1] neg_lo:[1,0,0] neg_hi:[1,0,0]
	v_pk_fma_f32 v[146:147], v[190:191], v[136:137], v[146:147] op_sel:[0,1,0] neg_lo:[1,0,0] neg_hi:[1,0,0]
	v_pk_fma_f32 v[146:147], v[192:193], v[138:139], v[146:147] op_sel_hi:[1,0,1] neg_lo:[1,0,0] neg_hi:[1,0,0]
	v_pk_fma_f32 v[146:147], v[194:195], v[138:139], v[146:147] op_sel:[0,1,0] neg_lo:[1,0,0] neg_hi:[1,0,0]
	ds_read_b128 v[188:191], v228 offset:12448
	ds_read_b128 v[192:195], v228 offset:12464
	s_waitcnt lgkmcnt(14)
	v_pk_fma_f32 v[146:147], v[196:197], v[140:141], v[146:147] op_sel_hi:[1,0,1] neg_lo:[1,0,0] neg_hi:[1,0,0]
	v_pk_fma_f32 v[146:147], v[198:199], v[140:141], v[146:147] op_sel:[0,1,0] neg_lo:[1,0,0] neg_hi:[1,0,0]
	v_pk_fma_f32 v[146:147], v[200:201], v[142:143], v[146:147] op_sel_hi:[1,0,1] neg_lo:[1,0,0] neg_hi:[1,0,0]
	v_pk_fma_f32 v[146:147], v[202:203], v[142:143], v[146:147] op_sel:[0,1,0] neg_lo:[1,0,0] neg_hi:[1,0,0]
	ds_read_b128 v[196:199], v228 offset:12480
	ds_read_b128 v[200:203], v228 offset:12496
	s_waitcnt lgkmcnt(14)
	v_pk_fma_f32 v[146:147], v[204:205], v[144:145], v[146:147] op_sel_hi:[1,0,1] neg_lo:[1,0,0] neg_hi:[1,0,0]
	v_pk_fma_f32 v[146:147], v[206:207], v[144:145], v[146:147] op_sel:[0,1,0] neg_lo:[1,0,0] neg_hi:[1,0,0]
	v_fma_f32 v147, -v209, v146, v147
	ds_read_b128 v[204:207], v228 offset:12512
	ds_read_b128 v[208:211], v228 offset:12528
	s_waitcnt lgkmcnt(14)
	v_pk_fma_f32 v[148:149], v[212:213], v[100:101], v[148:149] op_sel_hi:[1,0,1] neg_lo:[1,0,0] neg_hi:[1,0,0]
	v_pk_fma_f32 v[148:149], v[214:215], v[100:101], v[148:149] op_sel:[0,1,0] neg_lo:[1,0,0] neg_hi:[1,0,0]
	v_pk_fma_f32 v[148:149], v[216:217], v[102:103], v[148:149] op_sel_hi:[1,0,1] neg_lo:[1,0,0] neg_hi:[1,0,0]
	v_pk_fma_f32 v[148:149], v[218:219], v[102:103], v[148:149] op_sel:[0,1,0] neg_lo:[1,0,0] neg_hi:[1,0,0]
	ds_read_b128 v[212:215], v228 offset:12544
	ds_read_b128 v[216:219], v228 offset:12560
	s_waitcnt lgkmcnt(14)
	v_pk_fma_f32 v[148:149], v[220:221], v[104:105], v[148:149] op_sel_hi:[1,0,1] neg_lo:[1,0,0] neg_hi:[1,0,0]
	v_pk_fma_f32 v[148:149], v[222:223], v[104:105], v[148:149] op_sel:[0,1,0] neg_lo:[1,0,0] neg_hi:[1,0,0]
	v_pk_fma_f32 v[148:149], v[224:225], v[106:107], v[148:149] op_sel_hi:[1,0,1] neg_lo:[1,0,0] neg_hi:[1,0,0]
	v_pk_fma_f32 v[148:149], v[226:227], v[106:107], v[148:149] op_sel:[0,1,0] neg_lo:[1,0,0] neg_hi:[1,0,0]
	ds_read_b128 v[220:223], v228 offset:12576
	ds_read_b128 v[224:227], v228 offset:12592
	s_waitcnt lgkmcnt(14)
	v_pk_fma_f32 v[148:149], v[164:165], v[108:109], v[148:149] op_sel_hi:[1,0,1] neg_lo:[1,0,0] neg_hi:[1,0,0]
	v_pk_fma_f32 v[148:149], v[166:167], v[108:109], v[148:149] op_sel:[0,1,0] neg_lo:[1,0,0] neg_hi:[1,0,0]
	v_pk_fma_f32 v[148:149], v[168:169], v[110:111], v[148:149] op_sel_hi:[1,0,1] neg_lo:[1,0,0] neg_hi:[1,0,0]
	v_pk_fma_f32 v[148:149], v[170:171], v[110:111], v[148:149] op_sel:[0,1,0] neg_lo:[1,0,0] neg_hi:[1,0,0]
	ds_read_b128 v[164:167], v228 offset:12608
	ds_read_b128 v[168:171], v228 offset:12624
	s_waitcnt lgkmcnt(14)
	v_pk_fma_f32 v[148:149], v[172:173], v[112:113], v[148:149] op_sel_hi:[1,0,1] neg_lo:[1,0,0] neg_hi:[1,0,0]
	v_pk_fma_f32 v[148:149], v[174:175], v[112:113], v[148:149] op_sel:[0,1,0] neg_lo:[1,0,0] neg_hi:[1,0,0]
	v_pk_fma_f32 v[148:149], v[176:177], v[114:115], v[148:149] op_sel_hi:[1,0,1] neg_lo:[1,0,0] neg_hi:[1,0,0]
	v_pk_fma_f32 v[148:149], v[178:179], v[114:115], v[148:149] op_sel:[0,1,0] neg_lo:[1,0,0] neg_hi:[1,0,0]
	ds_read_b128 v[172:175], v228 offset:12640
	ds_read_b128 v[176:179], v228 offset:12656
	s_waitcnt lgkmcnt(14)
	v_pk_fma_f32 v[148:149], v[180:181], v[116:117], v[148:149] op_sel_hi:[1,0,1] neg_lo:[1,0,0] neg_hi:[1,0,0]
	v_pk_fma_f32 v[148:149], v[182:183], v[116:117], v[148:149] op_sel:[0,1,0] neg_lo:[1,0,0] neg_hi:[1,0,0]
	v_pk_fma_f32 v[148:149], v[184:185], v[118:119], v[148:149] op_sel_hi:[1,0,1] neg_lo:[1,0,0] neg_hi:[1,0,0]
	v_pk_fma_f32 v[148:149], v[186:187], v[118:119], v[148:149] op_sel:[0,1,0] neg_lo:[1,0,0] neg_hi:[1,0,0]
	ds_read_b128 v[180:183], v228 offset:12672
	ds_read_b128 v[184:187], v228 offset:12800
	s_waitcnt lgkmcnt(14)
	v_pk_fma_f32 v[148:149], v[188:189], v[120:121], v[148:149] op_sel_hi:[1,0,1] neg_lo:[1,0,0] neg_hi:[1,0,0]
	v_pk_fma_f32 v[148:149], v[190:191], v[120:121], v[148:149] op_sel:[0,1,0] neg_lo:[1,0,0] neg_hi:[1,0,0]
	v_pk_fma_f32 v[148:149], v[192:193], v[122:123], v[148:149] op_sel_hi:[1,0,1] neg_lo:[1,0,0] neg_hi:[1,0,0]
	v_pk_fma_f32 v[148:149], v[194:195], v[122:123], v[148:149] op_sel:[0,1,0] neg_lo:[1,0,0] neg_hi:[1,0,0]
	ds_read_b128 v[188:191], v228 offset:12816
	ds_read_b128 v[192:195], v228 offset:12832
	s_waitcnt lgkmcnt(14)
	v_pk_fma_f32 v[148:149], v[196:197], v[124:125], v[148:149] op_sel_hi:[1,0,1] neg_lo:[1,0,0] neg_hi:[1,0,0]
	v_pk_fma_f32 v[148:149], v[198:199], v[124:125], v[148:149] op_sel:[0,1,0] neg_lo:[1,0,0] neg_hi:[1,0,0]
	v_pk_fma_f32 v[148:149], v[200:201], v[126:127], v[148:149] op_sel_hi:[1,0,1] neg_lo:[1,0,0] neg_hi:[1,0,0]
	v_pk_fma_f32 v[148:149], v[202:203], v[126:127], v[148:149] op_sel:[0,1,0] neg_lo:[1,0,0] neg_hi:[1,0,0]
	ds_read_b128 v[196:199], v228 offset:12848
	ds_read_b128 v[200:203], v228 offset:12864
	s_waitcnt lgkmcnt(14)
	v_pk_fma_f32 v[148:149], v[204:205], v[128:129], v[148:149] op_sel_hi:[1,0,1] neg_lo:[1,0,0] neg_hi:[1,0,0]
	v_pk_fma_f32 v[148:149], v[206:207], v[128:129], v[148:149] op_sel:[0,1,0] neg_lo:[1,0,0] neg_hi:[1,0,0]
	v_pk_fma_f32 v[148:149], v[208:209], v[130:131], v[148:149] op_sel_hi:[1,0,1] neg_lo:[1,0,0] neg_hi:[1,0,0]
	v_pk_fma_f32 v[148:149], v[210:211], v[130:131], v[148:149] op_sel:[0,1,0] neg_lo:[1,0,0] neg_hi:[1,0,0]
	ds_read_b128 v[204:207], v228 offset:12880
	ds_read_b128 v[208:211], v228 offset:12896
	s_waitcnt lgkmcnt(14)
	v_pk_fma_f32 v[148:149], v[212:213], v[132:133], v[148:149] op_sel_hi:[1,0,1] neg_lo:[1,0,0] neg_hi:[1,0,0]
	v_pk_fma_f32 v[148:149], v[214:215], v[132:133], v[148:149] op_sel:[0,1,0] neg_lo:[1,0,0] neg_hi:[1,0,0]
	v_pk_fma_f32 v[148:149], v[216:217], v[134:135], v[148:149] op_sel_hi:[1,0,1] neg_lo:[1,0,0] neg_hi:[1,0,0]
	v_pk_fma_f32 v[148:149], v[218:219], v[134:135], v[148:149] op_sel:[0,1,0] neg_lo:[1,0,0] neg_hi:[1,0,0]
	ds_read_b128 v[212:215], v228 offset:12912
	ds_read_b128 v[216:219], v228 offset:12928
	s_waitcnt lgkmcnt(14)
	v_pk_fma_f32 v[148:149], v[220:221], v[136:137], v[148:149] op_sel_hi:[1,0,1] neg_lo:[1,0,0] neg_hi:[1,0,0]
	v_pk_fma_f32 v[148:149], v[222:223], v[136:137], v[148:149] op_sel:[0,1,0] neg_lo:[1,0,0] neg_hi:[1,0,0]
	v_pk_fma_f32 v[148:149], v[224:225], v[138:139], v[148:149] op_sel_hi:[1,0,1] neg_lo:[1,0,0] neg_hi:[1,0,0]
	v_pk_fma_f32 v[148:149], v[226:227], v[138:139], v[148:149] op_sel:[0,1,0] neg_lo:[1,0,0] neg_hi:[1,0,0]
	ds_read_b128 v[220:223], v228 offset:12944
	ds_read_b128 v[224:227], v228 offset:12960
	s_waitcnt lgkmcnt(14)
	v_pk_fma_f32 v[148:149], v[164:165], v[140:141], v[148:149] op_sel_hi:[1,0,1] neg_lo:[1,0,0] neg_hi:[1,0,0]
	v_pk_fma_f32 v[148:149], v[166:167], v[140:141], v[148:149] op_sel:[0,1,0] neg_lo:[1,0,0] neg_hi:[1,0,0]
	v_pk_fma_f32 v[148:149], v[168:169], v[142:143], v[148:149] op_sel_hi:[1,0,1] neg_lo:[1,0,0] neg_hi:[1,0,0]
	v_pk_fma_f32 v[148:149], v[170:171], v[142:143], v[148:149] op_sel:[0,1,0] neg_lo:[1,0,0] neg_hi:[1,0,0]
	ds_read_b128 v[164:167], v228 offset:12976
	ds_read_b128 v[168:171], v228 offset:12992
	s_waitcnt lgkmcnt(14)
	v_pk_fma_f32 v[148:149], v[172:173], v[144:145], v[148:149] op_sel_hi:[1,0,1] neg_lo:[1,0,0] neg_hi:[1,0,0]
	v_pk_fma_f32 v[148:149], v[174:175], v[144:145], v[148:149] op_sel:[0,1,0] neg_lo:[1,0,0] neg_hi:[1,0,0]
	v_pk_fma_f32 v[148:149], v[176:177], v[146:147], v[148:149] op_sel_hi:[1,0,1] neg_lo:[1,0,0] neg_hi:[1,0,0]
	v_pk_fma_f32 v[148:149], v[178:179], v[146:147], v[148:149] op_sel:[0,1,0] neg_lo:[1,0,0] neg_hi:[1,0,0]
	ds_read_b128 v[172:175], v228 offset:13008
	ds_read_b128 v[176:179], v228 offset:13024
	s_waitcnt lgkmcnt(14)
	v_fma_f32 v149, -v181, v148, v149
	v_pk_fma_f32 v[150:151], v[184:185], v[100:101], v[150:151] op_sel_hi:[1,0,1] neg_lo:[1,0,0] neg_hi:[1,0,0]
	v_pk_fma_f32 v[150:151], v[186:187], v[100:101], v[150:151] op_sel:[0,1,0] neg_lo:[1,0,0] neg_hi:[1,0,0]
	ds_read_b128 v[180:183], v228 offset:13040
	ds_read_b128 v[184:187], v228 offset:13056
	s_waitcnt lgkmcnt(14)
	v_pk_fma_f32 v[150:151], v[188:189], v[102:103], v[150:151] op_sel_hi:[1,0,1] neg_lo:[1,0,0] neg_hi:[1,0,0]
	v_pk_fma_f32 v[150:151], v[190:191], v[102:103], v[150:151] op_sel:[0,1,0] neg_lo:[1,0,0] neg_hi:[1,0,0]
	v_pk_fma_f32 v[150:151], v[192:193], v[104:105], v[150:151] op_sel_hi:[1,0,1] neg_lo:[1,0,0] neg_hi:[1,0,0]
	v_pk_fma_f32 v[150:151], v[194:195], v[104:105], v[150:151] op_sel:[0,1,0] neg_lo:[1,0,0] neg_hi:[1,0,0]
	ds_read_b128 v[188:191], v228 offset:13072
	ds_read_b128 v[192:195], v228 offset:13088
	s_waitcnt lgkmcnt(14)
	v_pk_fma_f32 v[150:151], v[196:197], v[106:107], v[150:151] op_sel_hi:[1,0,1] neg_lo:[1,0,0] neg_hi:[1,0,0]
	v_pk_fma_f32 v[150:151], v[198:199], v[106:107], v[150:151] op_sel:[0,1,0] neg_lo:[1,0,0] neg_hi:[1,0,0]
	v_pk_fma_f32 v[150:151], v[200:201], v[108:109], v[150:151] op_sel_hi:[1,0,1] neg_lo:[1,0,0] neg_hi:[1,0,0]
	v_pk_fma_f32 v[150:151], v[202:203], v[108:109], v[150:151] op_sel:[0,1,0] neg_lo:[1,0,0] neg_hi:[1,0,0]
	ds_read_b128 v[196:199], v228 offset:13104
	ds_read_b128 v[200:203], v228 offset:13120
	s_waitcnt lgkmcnt(14)
	v_pk_fma_f32 v[150:151], v[204:205], v[110:111], v[150:151] op_sel_hi:[1,0,1] neg_lo:[1,0,0] neg_hi:[1,0,0]
	v_pk_fma_f32 v[150:151], v[206:207], v[110:111], v[150:151] op_sel:[0,1,0] neg_lo:[1,0,0] neg_hi:[1,0,0]
	v_pk_fma_f32 v[150:151], v[208:209], v[112:113], v[150:151] op_sel_hi:[1,0,1] neg_lo:[1,0,0] neg_hi:[1,0,0]
	v_pk_fma_f32 v[150:151], v[210:211], v[112:113], v[150:151] op_sel:[0,1,0] neg_lo:[1,0,0] neg_hi:[1,0,0]
	ds_read_b128 v[204:207], v228 offset:13136
	ds_read_b128 v[208:211], v228 offset:13152
	s_waitcnt lgkmcnt(14)
	v_pk_fma_f32 v[150:151], v[212:213], v[114:115], v[150:151] op_sel_hi:[1,0,1] neg_lo:[1,0,0] neg_hi:[1,0,0]
	v_pk_fma_f32 v[150:151], v[214:215], v[114:115], v[150:151] op_sel:[0,1,0] neg_lo:[1,0,0] neg_hi:[1,0,0]
	v_pk_fma_f32 v[150:151], v[216:217], v[116:117], v[150:151] op_sel_hi:[1,0,1] neg_lo:[1,0,0] neg_hi:[1,0,0]
	v_pk_fma_f32 v[150:151], v[218:219], v[116:117], v[150:151] op_sel:[0,1,0] neg_lo:[1,0,0] neg_hi:[1,0,0]
	ds_read_b128 v[212:215], v228 offset:13168
	ds_read_b128 v[216:219], v228 offset:13184
	s_waitcnt lgkmcnt(14)
	v_pk_fma_f32 v[150:151], v[220:221], v[118:119], v[150:151] op_sel_hi:[1,0,1] neg_lo:[1,0,0] neg_hi:[1,0,0]
	v_pk_fma_f32 v[150:151], v[222:223], v[118:119], v[150:151] op_sel:[0,1,0] neg_lo:[1,0,0] neg_hi:[1,0,0]
	v_pk_fma_f32 v[150:151], v[224:225], v[120:121], v[150:151] op_sel_hi:[1,0,1] neg_lo:[1,0,0] neg_hi:[1,0,0]
	v_pk_fma_f32 v[150:151], v[226:227], v[120:121], v[150:151] op_sel:[0,1,0] neg_lo:[1,0,0] neg_hi:[1,0,0]
	ds_read_b128 v[220:223], v228 offset:13200
	ds_read_b128 v[224:227], v228 offset:13312
	s_waitcnt lgkmcnt(14)
	v_pk_fma_f32 v[150:151], v[164:165], v[122:123], v[150:151] op_sel_hi:[1,0,1] neg_lo:[1,0,0] neg_hi:[1,0,0]
	v_pk_fma_f32 v[150:151], v[166:167], v[122:123], v[150:151] op_sel:[0,1,0] neg_lo:[1,0,0] neg_hi:[1,0,0]
	v_pk_fma_f32 v[150:151], v[168:169], v[124:125], v[150:151] op_sel_hi:[1,0,1] neg_lo:[1,0,0] neg_hi:[1,0,0]
	v_pk_fma_f32 v[150:151], v[170:171], v[124:125], v[150:151] op_sel:[0,1,0] neg_lo:[1,0,0] neg_hi:[1,0,0]
	ds_read_b128 v[164:167], v228 offset:13328
	ds_read_b128 v[168:171], v228 offset:13344
	s_waitcnt lgkmcnt(14)
	v_pk_fma_f32 v[150:151], v[172:173], v[126:127], v[150:151] op_sel_hi:[1,0,1] neg_lo:[1,0,0] neg_hi:[1,0,0]
	v_pk_fma_f32 v[150:151], v[174:175], v[126:127], v[150:151] op_sel:[0,1,0] neg_lo:[1,0,0] neg_hi:[1,0,0]
	v_pk_fma_f32 v[150:151], v[176:177], v[128:129], v[150:151] op_sel_hi:[1,0,1] neg_lo:[1,0,0] neg_hi:[1,0,0]
	v_pk_fma_f32 v[150:151], v[178:179], v[128:129], v[150:151] op_sel:[0,1,0] neg_lo:[1,0,0] neg_hi:[1,0,0]
	ds_read_b128 v[172:175], v228 offset:13360
	ds_read_b128 v[176:179], v228 offset:13376
	s_waitcnt lgkmcnt(14)
	v_pk_fma_f32 v[150:151], v[180:181], v[130:131], v[150:151] op_sel_hi:[1,0,1] neg_lo:[1,0,0] neg_hi:[1,0,0]
	v_pk_fma_f32 v[150:151], v[182:183], v[130:131], v[150:151] op_sel:[0,1,0] neg_lo:[1,0,0] neg_hi:[1,0,0]
	v_pk_fma_f32 v[150:151], v[184:185], v[132:133], v[150:151] op_sel_hi:[1,0,1] neg_lo:[1,0,0] neg_hi:[1,0,0]
	v_pk_fma_f32 v[150:151], v[186:187], v[132:133], v[150:151] op_sel:[0,1,0] neg_lo:[1,0,0] neg_hi:[1,0,0]
	ds_read_b128 v[180:183], v228 offset:13392
	ds_read_b128 v[184:187], v228 offset:13408
	s_waitcnt lgkmcnt(14)
	v_pk_fma_f32 v[150:151], v[188:189], v[134:135], v[150:151] op_sel_hi:[1,0,1] neg_lo:[1,0,0] neg_hi:[1,0,0]
	v_pk_fma_f32 v[150:151], v[190:191], v[134:135], v[150:151] op_sel:[0,1,0] neg_lo:[1,0,0] neg_hi:[1,0,0]
	v_pk_fma_f32 v[150:151], v[192:193], v[136:137], v[150:151] op_sel_hi:[1,0,1] neg_lo:[1,0,0] neg_hi:[1,0,0]
	v_pk_fma_f32 v[150:151], v[194:195], v[136:137], v[150:151] op_sel:[0,1,0] neg_lo:[1,0,0] neg_hi:[1,0,0]
	ds_read_b128 v[188:191], v228 offset:13424
	ds_read_b128 v[192:195], v228 offset:13440
	s_waitcnt lgkmcnt(14)
	v_pk_fma_f32 v[150:151], v[196:197], v[138:139], v[150:151] op_sel_hi:[1,0,1] neg_lo:[1,0,0] neg_hi:[1,0,0]
	v_pk_fma_f32 v[150:151], v[198:199], v[138:139], v[150:151] op_sel:[0,1,0] neg_lo:[1,0,0] neg_hi:[1,0,0]
	v_pk_fma_f32 v[150:151], v[200:201], v[140:141], v[150:151] op_sel_hi:[1,0,1] neg_lo:[1,0,0] neg_hi:[1,0,0]
	v_pk_fma_f32 v[150:151], v[202:203], v[140:141], v[150:151] op_sel:[0,1,0] neg_lo:[1,0,0] neg_hi:[1,0,0]
	ds_read_b128 v[196:199], v228 offset:13456
	ds_read_b128 v[200:203], v228 offset:13472
	s_waitcnt lgkmcnt(14)
	v_pk_fma_f32 v[150:151], v[204:205], v[142:143], v[150:151] op_sel_hi:[1,0,1] neg_lo:[1,0,0] neg_hi:[1,0,0]
	v_pk_fma_f32 v[150:151], v[206:207], v[142:143], v[150:151] op_sel:[0,1,0] neg_lo:[1,0,0] neg_hi:[1,0,0]
	v_pk_fma_f32 v[150:151], v[208:209], v[144:145], v[150:151] op_sel_hi:[1,0,1] neg_lo:[1,0,0] neg_hi:[1,0,0]
	v_pk_fma_f32 v[150:151], v[210:211], v[144:145], v[150:151] op_sel:[0,1,0] neg_lo:[1,0,0] neg_hi:[1,0,0]
	ds_read_b128 v[204:207], v228 offset:13488
	ds_read_b128 v[208:211], v228 offset:13504
	s_waitcnt lgkmcnt(14)
	v_pk_fma_f32 v[150:151], v[212:213], v[146:147], v[150:151] op_sel_hi:[1,0,1] neg_lo:[1,0,0] neg_hi:[1,0,0]
	v_pk_fma_f32 v[150:151], v[214:215], v[146:147], v[150:151] op_sel:[0,1,0] neg_lo:[1,0,0] neg_hi:[1,0,0]
	v_pk_fma_f32 v[150:151], v[216:217], v[148:149], v[150:151] op_sel_hi:[1,0,1] neg_lo:[1,0,0] neg_hi:[1,0,0]
	v_pk_fma_f32 v[150:151], v[218:219], v[148:149], v[150:151] op_sel:[0,1,0] neg_lo:[1,0,0] neg_hi:[1,0,0]
	ds_read_b128 v[212:215], v228 offset:13520
	ds_read_b128 v[216:219], v228 offset:13536
	s_waitcnt lgkmcnt(14)
	v_fma_f32 v151, -v221, v150, v151
	v_pk_fma_f32 v[152:153], v[224:225], v[100:101], v[152:153] op_sel_hi:[1,0,1] neg_lo:[1,0,0] neg_hi:[1,0,0]
	v_pk_fma_f32 v[152:153], v[226:227], v[100:101], v[152:153] op_sel:[0,1,0] neg_lo:[1,0,0] neg_hi:[1,0,0]
	ds_read_b128 v[220:223], v228 offset:13552
	ds_read_b128 v[224:227], v228 offset:13568
	s_barrier
	s_waitcnt lgkmcnt(14)
	v_pk_fma_f32 v[152:153], v[164:165], v[102:103], v[152:153] op_sel_hi:[1,0,1] neg_lo:[1,0,0] neg_hi:[1,0,0]
	v_pk_fma_f32 v[152:153], v[166:167], v[102:103], v[152:153] op_sel:[0,1,0] neg_lo:[1,0,0] neg_hi:[1,0,0]
	v_pk_fma_f32 v[152:153], v[168:169], v[104:105], v[152:153] op_sel_hi:[1,0,1] neg_lo:[1,0,0] neg_hi:[1,0,0]
	v_pk_fma_f32 v[152:153], v[170:171], v[104:105], v[152:153] op_sel:[0,1,0] neg_lo:[1,0,0] neg_hi:[1,0,0]
	ds_read_b128 v[164:167], v228 offset:13584
	ds_read_b128 v[168:171], v228 offset:13600
	s_waitcnt lgkmcnt(14)
	v_pk_fma_f32 v[152:153], v[172:173], v[106:107], v[152:153] op_sel_hi:[1,0,1] neg_lo:[1,0,0] neg_hi:[1,0,0]
	v_pk_fma_f32 v[152:153], v[174:175], v[106:107], v[152:153] op_sel:[0,1,0] neg_lo:[1,0,0] neg_hi:[1,0,0]
	v_pk_fma_f32 v[152:153], v[176:177], v[108:109], v[152:153] op_sel_hi:[1,0,1] neg_lo:[1,0,0] neg_hi:[1,0,0]
	v_pk_fma_f32 v[152:153], v[178:179], v[108:109], v[152:153] op_sel:[0,1,0] neg_lo:[1,0,0] neg_hi:[1,0,0]
	ds_read_b128 v[172:175], v228 offset:13616
	ds_read_b128 v[176:179], v228 offset:13632
	s_waitcnt lgkmcnt(14)
	v_pk_fma_f32 v[152:153], v[180:181], v[110:111], v[152:153] op_sel_hi:[1,0,1] neg_lo:[1,0,0] neg_hi:[1,0,0]
	v_pk_fma_f32 v[152:153], v[182:183], v[110:111], v[152:153] op_sel:[0,1,0] neg_lo:[1,0,0] neg_hi:[1,0,0]
	v_pk_fma_f32 v[152:153], v[184:185], v[112:113], v[152:153] op_sel_hi:[1,0,1] neg_lo:[1,0,0] neg_hi:[1,0,0]
	v_pk_fma_f32 v[152:153], v[186:187], v[112:113], v[152:153] op_sel:[0,1,0] neg_lo:[1,0,0] neg_hi:[1,0,0]
	ds_read_b128 v[180:183], v228 offset:13648
	ds_read_b128 v[184:187], v228 offset:13664
	s_waitcnt lgkmcnt(14)
	v_pk_fma_f32 v[152:153], v[188:189], v[114:115], v[152:153] op_sel_hi:[1,0,1] neg_lo:[1,0,0] neg_hi:[1,0,0]
	v_pk_fma_f32 v[152:153], v[190:191], v[114:115], v[152:153] op_sel:[0,1,0] neg_lo:[1,0,0] neg_hi:[1,0,0]
	v_pk_fma_f32 v[152:153], v[192:193], v[116:117], v[152:153] op_sel_hi:[1,0,1] neg_lo:[1,0,0] neg_hi:[1,0,0]
	v_pk_fma_f32 v[152:153], v[194:195], v[116:117], v[152:153] op_sel:[0,1,0] neg_lo:[1,0,0] neg_hi:[1,0,0]
	ds_read_b128 v[188:191], v228 offset:13680
	ds_read_b128 v[192:195], v228 offset:13696
	s_waitcnt lgkmcnt(14)
	v_pk_fma_f32 v[152:153], v[196:197], v[118:119], v[152:153] op_sel_hi:[1,0,1] neg_lo:[1,0,0] neg_hi:[1,0,0]
	v_pk_fma_f32 v[152:153], v[198:199], v[118:119], v[152:153] op_sel:[0,1,0] neg_lo:[1,0,0] neg_hi:[1,0,0]
	v_pk_fma_f32 v[152:153], v[200:201], v[120:121], v[152:153] op_sel_hi:[1,0,1] neg_lo:[1,0,0] neg_hi:[1,0,0]
	v_pk_fma_f32 v[152:153], v[202:203], v[120:121], v[152:153] op_sel:[0,1,0] neg_lo:[1,0,0] neg_hi:[1,0,0]
	ds_read_b128 v[196:199], v228 offset:13712
	ds_read_b128 v[200:203], v228 offset:13728
	s_waitcnt lgkmcnt(14)
	v_pk_fma_f32 v[152:153], v[204:205], v[122:123], v[152:153] op_sel_hi:[1,0,1] neg_lo:[1,0,0] neg_hi:[1,0,0]
	v_pk_fma_f32 v[152:153], v[206:207], v[122:123], v[152:153] op_sel:[0,1,0] neg_lo:[1,0,0] neg_hi:[1,0,0]
	v_pk_fma_f32 v[152:153], v[208:209], v[124:125], v[152:153] op_sel_hi:[1,0,1] neg_lo:[1,0,0] neg_hi:[1,0,0]
	v_pk_fma_f32 v[152:153], v[210:211], v[124:125], v[152:153] op_sel:[0,1,0] neg_lo:[1,0,0] neg_hi:[1,0,0]
	ds_read_b128 v[204:207], v228 offset:13824
	ds_read_b128 v[208:211], v228 offset:13840
	s_waitcnt lgkmcnt(14)
	v_pk_fma_f32 v[152:153], v[212:213], v[126:127], v[152:153] op_sel_hi:[1,0,1] neg_lo:[1,0,0] neg_hi:[1,0,0]
	v_pk_fma_f32 v[152:153], v[214:215], v[126:127], v[152:153] op_sel:[0,1,0] neg_lo:[1,0,0] neg_hi:[1,0,0]
	v_pk_fma_f32 v[152:153], v[216:217], v[128:129], v[152:153] op_sel_hi:[1,0,1] neg_lo:[1,0,0] neg_hi:[1,0,0]
	v_pk_fma_f32 v[152:153], v[218:219], v[128:129], v[152:153] op_sel:[0,1,0] neg_lo:[1,0,0] neg_hi:[1,0,0]
	ds_read_b128 v[212:215], v228 offset:13856
	ds_read_b128 v[216:219], v228 offset:13872
	s_waitcnt lgkmcnt(14)
	v_pk_fma_f32 v[152:153], v[220:221], v[130:131], v[152:153] op_sel_hi:[1,0,1] neg_lo:[1,0,0] neg_hi:[1,0,0]
	v_pk_fma_f32 v[152:153], v[222:223], v[130:131], v[152:153] op_sel:[0,1,0] neg_lo:[1,0,0] neg_hi:[1,0,0]
	v_pk_fma_f32 v[152:153], v[224:225], v[132:133], v[152:153] op_sel_hi:[1,0,1] neg_lo:[1,0,0] neg_hi:[1,0,0]
	v_pk_fma_f32 v[152:153], v[226:227], v[132:133], v[152:153] op_sel:[0,1,0] neg_lo:[1,0,0] neg_hi:[1,0,0]
	ds_read_b128 v[220:223], v228 offset:13888
	ds_read_b128 v[224:227], v228 offset:13904
	s_waitcnt lgkmcnt(14)
	v_pk_fma_f32 v[152:153], v[164:165], v[134:135], v[152:153] op_sel_hi:[1,0,1] neg_lo:[1,0,0] neg_hi:[1,0,0]
	v_pk_fma_f32 v[152:153], v[166:167], v[134:135], v[152:153] op_sel:[0,1,0] neg_lo:[1,0,0] neg_hi:[1,0,0]
	v_pk_fma_f32 v[152:153], v[168:169], v[136:137], v[152:153] op_sel_hi:[1,0,1] neg_lo:[1,0,0] neg_hi:[1,0,0]
	v_pk_fma_f32 v[152:153], v[170:171], v[136:137], v[152:153] op_sel:[0,1,0] neg_lo:[1,0,0] neg_hi:[1,0,0]
	ds_read_b128 v[164:167], v228 offset:13920
	ds_read_b128 v[168:171], v228 offset:13936
	s_waitcnt lgkmcnt(14)
	v_pk_fma_f32 v[152:153], v[172:173], v[138:139], v[152:153] op_sel_hi:[1,0,1] neg_lo:[1,0,0] neg_hi:[1,0,0]
	v_pk_fma_f32 v[152:153], v[174:175], v[138:139], v[152:153] op_sel:[0,1,0] neg_lo:[1,0,0] neg_hi:[1,0,0]
	v_pk_fma_f32 v[152:153], v[176:177], v[140:141], v[152:153] op_sel_hi:[1,0,1] neg_lo:[1,0,0] neg_hi:[1,0,0]
	v_pk_fma_f32 v[152:153], v[178:179], v[140:141], v[152:153] op_sel:[0,1,0] neg_lo:[1,0,0] neg_hi:[1,0,0]
	ds_read_b128 v[172:175], v228 offset:13952
	ds_read_b128 v[176:179], v228 offset:13968
	s_waitcnt lgkmcnt(14)
	v_pk_fma_f32 v[152:153], v[180:181], v[142:143], v[152:153] op_sel_hi:[1,0,1] neg_lo:[1,0,0] neg_hi:[1,0,0]
	v_pk_fma_f32 v[152:153], v[182:183], v[142:143], v[152:153] op_sel:[0,1,0] neg_lo:[1,0,0] neg_hi:[1,0,0]
	v_pk_fma_f32 v[152:153], v[184:185], v[144:145], v[152:153] op_sel_hi:[1,0,1] neg_lo:[1,0,0] neg_hi:[1,0,0]
	v_pk_fma_f32 v[152:153], v[186:187], v[144:145], v[152:153] op_sel:[0,1,0] neg_lo:[1,0,0] neg_hi:[1,0,0]
	ds_read_b128 v[180:183], v228 offset:13984
	ds_read_b128 v[184:187], v228 offset:14000
	s_waitcnt lgkmcnt(14)
	v_pk_fma_f32 v[152:153], v[188:189], v[146:147], v[152:153] op_sel_hi:[1,0,1] neg_lo:[1,0,0] neg_hi:[1,0,0]
	v_pk_fma_f32 v[152:153], v[190:191], v[146:147], v[152:153] op_sel:[0,1,0] neg_lo:[1,0,0] neg_hi:[1,0,0]
	v_pk_fma_f32 v[152:153], v[192:193], v[148:149], v[152:153] op_sel_hi:[1,0,1] neg_lo:[1,0,0] neg_hi:[1,0,0]
	v_pk_fma_f32 v[152:153], v[194:195], v[148:149], v[152:153] op_sel:[0,1,0] neg_lo:[1,0,0] neg_hi:[1,0,0]
	ds_read_b128 v[188:191], v228 offset:14016
	ds_read_b128 v[192:195], v228 offset:14032
	s_waitcnt lgkmcnt(14)
	v_pk_fma_f32 v[152:153], v[196:197], v[150:151], v[152:153] op_sel_hi:[1,0,1] neg_lo:[1,0,0] neg_hi:[1,0,0]
	v_pk_fma_f32 v[152:153], v[198:199], v[150:151], v[152:153] op_sel:[0,1,0] neg_lo:[1,0,0] neg_hi:[1,0,0]
	v_fma_f32 v153, -v201, v152, v153
	ds_read_b128 v[196:199], v228 offset:14048
	ds_read_b128 v[200:203], v228 offset:14064
	s_waitcnt lgkmcnt(14)
	v_pk_fma_f32 v[154:155], v[204:205], v[100:101], v[154:155] op_sel_hi:[1,0,1] neg_lo:[1,0,0] neg_hi:[1,0,0]
	v_pk_fma_f32 v[154:155], v[206:207], v[100:101], v[154:155] op_sel:[0,1,0] neg_lo:[1,0,0] neg_hi:[1,0,0]
	v_pk_fma_f32 v[154:155], v[208:209], v[102:103], v[154:155] op_sel_hi:[1,0,1] neg_lo:[1,0,0] neg_hi:[1,0,0]
	v_pk_fma_f32 v[154:155], v[210:211], v[102:103], v[154:155] op_sel:[0,1,0] neg_lo:[1,0,0] neg_hi:[1,0,0]
	ds_read_b128 v[204:207], v228 offset:14080
	ds_read_b128 v[208:211], v228 offset:14096
	s_waitcnt lgkmcnt(14)
	v_pk_fma_f32 v[154:155], v[212:213], v[104:105], v[154:155] op_sel_hi:[1,0,1] neg_lo:[1,0,0] neg_hi:[1,0,0]
	v_pk_fma_f32 v[154:155], v[214:215], v[104:105], v[154:155] op_sel:[0,1,0] neg_lo:[1,0,0] neg_hi:[1,0,0]
	v_pk_fma_f32 v[154:155], v[216:217], v[106:107], v[154:155] op_sel_hi:[1,0,1] neg_lo:[1,0,0] neg_hi:[1,0,0]
	v_pk_fma_f32 v[154:155], v[218:219], v[106:107], v[154:155] op_sel:[0,1,0] neg_lo:[1,0,0] neg_hi:[1,0,0]
	ds_read_b128 v[212:215], v228 offset:14112
	ds_read_b128 v[216:219], v228 offset:14128
	s_waitcnt lgkmcnt(14)
	v_pk_fma_f32 v[154:155], v[220:221], v[108:109], v[154:155] op_sel_hi:[1,0,1] neg_lo:[1,0,0] neg_hi:[1,0,0]
	v_pk_fma_f32 v[154:155], v[222:223], v[108:109], v[154:155] op_sel:[0,1,0] neg_lo:[1,0,0] neg_hi:[1,0,0]
	v_pk_fma_f32 v[154:155], v[224:225], v[110:111], v[154:155] op_sel_hi:[1,0,1] neg_lo:[1,0,0] neg_hi:[1,0,0]
	v_pk_fma_f32 v[154:155], v[226:227], v[110:111], v[154:155] op_sel:[0,1,0] neg_lo:[1,0,0] neg_hi:[1,0,0]
	ds_read_b128 v[220:223], v228 offset:14144
	ds_read_b128 v[224:227], v228 offset:14160
	s_waitcnt lgkmcnt(14)
	v_pk_fma_f32 v[154:155], v[164:165], v[112:113], v[154:155] op_sel_hi:[1,0,1] neg_lo:[1,0,0] neg_hi:[1,0,0]
	v_pk_fma_f32 v[154:155], v[166:167], v[112:113], v[154:155] op_sel:[0,1,0] neg_lo:[1,0,0] neg_hi:[1,0,0]
	v_pk_fma_f32 v[154:155], v[168:169], v[114:115], v[154:155] op_sel_hi:[1,0,1] neg_lo:[1,0,0] neg_hi:[1,0,0]
	v_pk_fma_f32 v[154:155], v[170:171], v[114:115], v[154:155] op_sel:[0,1,0] neg_lo:[1,0,0] neg_hi:[1,0,0]
	ds_read_b128 v[164:167], v228 offset:14176
	ds_read_b128 v[168:171], v228 offset:14192
	s_waitcnt lgkmcnt(14)
	v_pk_fma_f32 v[154:155], v[172:173], v[116:117], v[154:155] op_sel_hi:[1,0,1] neg_lo:[1,0,0] neg_hi:[1,0,0]
	v_pk_fma_f32 v[154:155], v[174:175], v[116:117], v[154:155] op_sel:[0,1,0] neg_lo:[1,0,0] neg_hi:[1,0,0]
	v_pk_fma_f32 v[154:155], v[176:177], v[118:119], v[154:155] op_sel_hi:[1,0,1] neg_lo:[1,0,0] neg_hi:[1,0,0]
	v_pk_fma_f32 v[154:155], v[178:179], v[118:119], v[154:155] op_sel:[0,1,0] neg_lo:[1,0,0] neg_hi:[1,0,0]
	ds_read_b128 v[172:175], v228 offset:14208
	ds_read_b128 v[176:179], v228 offset:14224
	s_waitcnt lgkmcnt(14)
	v_pk_fma_f32 v[154:155], v[180:181], v[120:121], v[154:155] op_sel_hi:[1,0,1] neg_lo:[1,0,0] neg_hi:[1,0,0]
	v_pk_fma_f32 v[154:155], v[182:183], v[120:121], v[154:155] op_sel:[0,1,0] neg_lo:[1,0,0] neg_hi:[1,0,0]
	v_pk_fma_f32 v[154:155], v[184:185], v[122:123], v[154:155] op_sel_hi:[1,0,1] neg_lo:[1,0,0] neg_hi:[1,0,0]
	v_pk_fma_f32 v[154:155], v[186:187], v[122:123], v[154:155] op_sel:[0,1,0] neg_lo:[1,0,0] neg_hi:[1,0,0]
	ds_read_b128 v[180:183], v228 offset:14240
	ds_read_b128 v[184:187], v228 offset:14256
	s_waitcnt lgkmcnt(14)
	v_pk_fma_f32 v[154:155], v[188:189], v[124:125], v[154:155] op_sel_hi:[1,0,1] neg_lo:[1,0,0] neg_hi:[1,0,0]
	v_pk_fma_f32 v[154:155], v[190:191], v[124:125], v[154:155] op_sel:[0,1,0] neg_lo:[1,0,0] neg_hi:[1,0,0]
	v_pk_fma_f32 v[154:155], v[192:193], v[126:127], v[154:155] op_sel_hi:[1,0,1] neg_lo:[1,0,0] neg_hi:[1,0,0]
	v_pk_fma_f32 v[154:155], v[194:195], v[126:127], v[154:155] op_sel:[0,1,0] neg_lo:[1,0,0] neg_hi:[1,0,0]
	ds_read_b128 v[188:191], v228 offset:14336
	ds_read_b128 v[192:195], v228 offset:14352
	s_waitcnt lgkmcnt(14)
	v_pk_fma_f32 v[154:155], v[196:197], v[128:129], v[154:155] op_sel_hi:[1,0,1] neg_lo:[1,0,0] neg_hi:[1,0,0]
	v_pk_fma_f32 v[154:155], v[198:199], v[128:129], v[154:155] op_sel:[0,1,0] neg_lo:[1,0,0] neg_hi:[1,0,0]
	v_pk_fma_f32 v[154:155], v[200:201], v[130:131], v[154:155] op_sel_hi:[1,0,1] neg_lo:[1,0,0] neg_hi:[1,0,0]
	v_pk_fma_f32 v[154:155], v[202:203], v[130:131], v[154:155] op_sel:[0,1,0] neg_lo:[1,0,0] neg_hi:[1,0,0]
	ds_read_b128 v[196:199], v228 offset:14368
	ds_read_b128 v[200:203], v228 offset:14384
	s_waitcnt lgkmcnt(14)
	v_pk_fma_f32 v[154:155], v[204:205], v[132:133], v[154:155] op_sel_hi:[1,0,1] neg_lo:[1,0,0] neg_hi:[1,0,0]
	v_pk_fma_f32 v[154:155], v[206:207], v[132:133], v[154:155] op_sel:[0,1,0] neg_lo:[1,0,0] neg_hi:[1,0,0]
	v_pk_fma_f32 v[154:155], v[208:209], v[134:135], v[154:155] op_sel_hi:[1,0,1] neg_lo:[1,0,0] neg_hi:[1,0,0]
	v_pk_fma_f32 v[154:155], v[210:211], v[134:135], v[154:155] op_sel:[0,1,0] neg_lo:[1,0,0] neg_hi:[1,0,0]
	ds_read_b128 v[204:207], v228 offset:14400
	ds_read_b128 v[208:211], v228 offset:14416
	s_waitcnt lgkmcnt(14)
	v_pk_fma_f32 v[154:155], v[212:213], v[136:137], v[154:155] op_sel_hi:[1,0,1] neg_lo:[1,0,0] neg_hi:[1,0,0]
	v_pk_fma_f32 v[154:155], v[214:215], v[136:137], v[154:155] op_sel:[0,1,0] neg_lo:[1,0,0] neg_hi:[1,0,0]
	v_pk_fma_f32 v[154:155], v[216:217], v[138:139], v[154:155] op_sel_hi:[1,0,1] neg_lo:[1,0,0] neg_hi:[1,0,0]
	v_pk_fma_f32 v[154:155], v[218:219], v[138:139], v[154:155] op_sel:[0,1,0] neg_lo:[1,0,0] neg_hi:[1,0,0]
	ds_read_b128 v[212:215], v228 offset:14432
	ds_read_b128 v[216:219], v228 offset:14448
	s_waitcnt lgkmcnt(14)
	v_pk_fma_f32 v[154:155], v[220:221], v[140:141], v[154:155] op_sel_hi:[1,0,1] neg_lo:[1,0,0] neg_hi:[1,0,0]
	v_pk_fma_f32 v[154:155], v[222:223], v[140:141], v[154:155] op_sel:[0,1,0] neg_lo:[1,0,0] neg_hi:[1,0,0]
	v_pk_fma_f32 v[154:155], v[224:225], v[142:143], v[154:155] op_sel_hi:[1,0,1] neg_lo:[1,0,0] neg_hi:[1,0,0]
	v_pk_fma_f32 v[154:155], v[226:227], v[142:143], v[154:155] op_sel:[0,1,0] neg_lo:[1,0,0] neg_hi:[1,0,0]
	ds_read_b128 v[220:223], v228 offset:14464
	ds_read_b128 v[224:227], v228 offset:14480
	s_waitcnt lgkmcnt(14)
	v_pk_fma_f32 v[154:155], v[164:165], v[144:145], v[154:155] op_sel_hi:[1,0,1] neg_lo:[1,0,0] neg_hi:[1,0,0]
	v_pk_fma_f32 v[154:155], v[166:167], v[144:145], v[154:155] op_sel:[0,1,0] neg_lo:[1,0,0] neg_hi:[1,0,0]
	v_pk_fma_f32 v[154:155], v[168:169], v[146:147], v[154:155] op_sel_hi:[1,0,1] neg_lo:[1,0,0] neg_hi:[1,0,0]
	v_pk_fma_f32 v[154:155], v[170:171], v[146:147], v[154:155] op_sel:[0,1,0] neg_lo:[1,0,0] neg_hi:[1,0,0]
	ds_read_b128 v[164:167], v228 offset:14496
	ds_read_b128 v[168:171], v228 offset:14512
	s_waitcnt lgkmcnt(14)
	v_pk_fma_f32 v[154:155], v[172:173], v[148:149], v[154:155] op_sel_hi:[1,0,1] neg_lo:[1,0,0] neg_hi:[1,0,0]
	v_pk_fma_f32 v[154:155], v[174:175], v[148:149], v[154:155] op_sel:[0,1,0] neg_lo:[1,0,0] neg_hi:[1,0,0]
	v_pk_fma_f32 v[154:155], v[176:177], v[150:151], v[154:155] op_sel_hi:[1,0,1] neg_lo:[1,0,0] neg_hi:[1,0,0]
	v_pk_fma_f32 v[154:155], v[178:179], v[150:151], v[154:155] op_sel:[0,1,0] neg_lo:[1,0,0] neg_hi:[1,0,0]
	ds_read_b128 v[172:175], v228 offset:14528
	ds_read_b128 v[176:179], v228 offset:14544
	s_waitcnt lgkmcnt(14)
	v_pk_fma_f32 v[154:155], v[180:181], v[152:153], v[154:155] op_sel_hi:[1,0,1] neg_lo:[1,0,0] neg_hi:[1,0,0]
	v_pk_fma_f32 v[154:155], v[182:183], v[152:153], v[154:155] op_sel:[0,1,0] neg_lo:[1,0,0] neg_hi:[1,0,0]
	v_fma_f32 v155, -v185, v154, v155
	ds_read_b128 v[180:183], v228 offset:14560
	ds_read_b128 v[184:187], v228 offset:14576
	s_waitcnt lgkmcnt(14)
	v_pk_fma_f32 v[156:157], v[188:189], v[100:101], v[156:157] op_sel_hi:[1,0,1] neg_lo:[1,0,0] neg_hi:[1,0,0]
	v_pk_fma_f32 v[156:157], v[190:191], v[100:101], v[156:157] op_sel:[0,1,0] neg_lo:[1,0,0] neg_hi:[1,0,0]
	v_pk_fma_f32 v[156:157], v[192:193], v[102:103], v[156:157] op_sel_hi:[1,0,1] neg_lo:[1,0,0] neg_hi:[1,0,0]
	v_pk_fma_f32 v[156:157], v[194:195], v[102:103], v[156:157] op_sel:[0,1,0] neg_lo:[1,0,0] neg_hi:[1,0,0]
	ds_read_b128 v[188:191], v228 offset:14592
	ds_read_b128 v[192:195], v228 offset:14608
	s_waitcnt lgkmcnt(14)
	v_pk_fma_f32 v[156:157], v[196:197], v[104:105], v[156:157] op_sel_hi:[1,0,1] neg_lo:[1,0,0] neg_hi:[1,0,0]
	v_pk_fma_f32 v[156:157], v[198:199], v[104:105], v[156:157] op_sel:[0,1,0] neg_lo:[1,0,0] neg_hi:[1,0,0]
	v_pk_fma_f32 v[156:157], v[200:201], v[106:107], v[156:157] op_sel_hi:[1,0,1] neg_lo:[1,0,0] neg_hi:[1,0,0]
	v_pk_fma_f32 v[156:157], v[202:203], v[106:107], v[156:157] op_sel:[0,1,0] neg_lo:[1,0,0] neg_hi:[1,0,0]
	ds_read_b128 v[196:199], v228 offset:14624
	ds_read_b128 v[200:203], v228 offset:14640
	s_waitcnt lgkmcnt(14)
	v_pk_fma_f32 v[156:157], v[204:205], v[108:109], v[156:157] op_sel_hi:[1,0,1] neg_lo:[1,0,0] neg_hi:[1,0,0]
	v_pk_fma_f32 v[156:157], v[206:207], v[108:109], v[156:157] op_sel:[0,1,0] neg_lo:[1,0,0] neg_hi:[1,0,0]
	v_pk_fma_f32 v[156:157], v[208:209], v[110:111], v[156:157] op_sel_hi:[1,0,1] neg_lo:[1,0,0] neg_hi:[1,0,0]
	v_pk_fma_f32 v[156:157], v[210:211], v[110:111], v[156:157] op_sel:[0,1,0] neg_lo:[1,0,0] neg_hi:[1,0,0]
	ds_read_b128 v[204:207], v228 offset:14656
	ds_read_b128 v[208:211], v228 offset:14672
	s_waitcnt lgkmcnt(14)
	v_pk_fma_f32 v[156:157], v[212:213], v[112:113], v[156:157] op_sel_hi:[1,0,1] neg_lo:[1,0,0] neg_hi:[1,0,0]
	v_pk_fma_f32 v[156:157], v[214:215], v[112:113], v[156:157] op_sel:[0,1,0] neg_lo:[1,0,0] neg_hi:[1,0,0]
	v_pk_fma_f32 v[156:157], v[216:217], v[114:115], v[156:157] op_sel_hi:[1,0,1] neg_lo:[1,0,0] neg_hi:[1,0,0]
	v_pk_fma_f32 v[156:157], v[218:219], v[114:115], v[156:157] op_sel:[0,1,0] neg_lo:[1,0,0] neg_hi:[1,0,0]
	ds_read_b128 v[212:215], v228 offset:14688
	ds_read_b128 v[216:219], v228 offset:14704
	s_waitcnt lgkmcnt(14)
	v_pk_fma_f32 v[156:157], v[220:221], v[116:117], v[156:157] op_sel_hi:[1,0,1] neg_lo:[1,0,0] neg_hi:[1,0,0]
	v_pk_fma_f32 v[156:157], v[222:223], v[116:117], v[156:157] op_sel:[0,1,0] neg_lo:[1,0,0] neg_hi:[1,0,0]
	v_pk_fma_f32 v[156:157], v[224:225], v[118:119], v[156:157] op_sel_hi:[1,0,1] neg_lo:[1,0,0] neg_hi:[1,0,0]
	v_pk_fma_f32 v[156:157], v[226:227], v[118:119], v[156:157] op_sel:[0,1,0] neg_lo:[1,0,0] neg_hi:[1,0,0]
	ds_read_b128 v[220:223], v228 offset:14720
	ds_read_b128 v[224:227], v228 offset:14736
	s_waitcnt lgkmcnt(14)
	v_pk_fma_f32 v[156:157], v[164:165], v[120:121], v[156:157] op_sel_hi:[1,0,1] neg_lo:[1,0,0] neg_hi:[1,0,0]
	v_pk_fma_f32 v[156:157], v[166:167], v[120:121], v[156:157] op_sel:[0,1,0] neg_lo:[1,0,0] neg_hi:[1,0,0]
	v_pk_fma_f32 v[156:157], v[168:169], v[122:123], v[156:157] op_sel_hi:[1,0,1] neg_lo:[1,0,0] neg_hi:[1,0,0]
	v_pk_fma_f32 v[156:157], v[170:171], v[122:123], v[156:157] op_sel:[0,1,0] neg_lo:[1,0,0] neg_hi:[1,0,0]
	ds_read_b128 v[164:167], v228 offset:14752
	ds_read_b128 v[168:171], v228 offset:14768
	s_waitcnt lgkmcnt(14)
	v_pk_fma_f32 v[156:157], v[172:173], v[124:125], v[156:157] op_sel_hi:[1,0,1] neg_lo:[1,0,0] neg_hi:[1,0,0]
	v_pk_fma_f32 v[156:157], v[174:175], v[124:125], v[156:157] op_sel:[0,1,0] neg_lo:[1,0,0] neg_hi:[1,0,0]
	v_pk_fma_f32 v[156:157], v[176:177], v[126:127], v[156:157] op_sel_hi:[1,0,1] neg_lo:[1,0,0] neg_hi:[1,0,0]
	v_pk_fma_f32 v[156:157], v[178:179], v[126:127], v[156:157] op_sel:[0,1,0] neg_lo:[1,0,0] neg_hi:[1,0,0]
	ds_read_b128 v[172:175], v228 offset:14784
	ds_read_b128 v[176:179], v228 offset:14848
	s_waitcnt lgkmcnt(14)
	v_pk_fma_f32 v[156:157], v[180:181], v[128:129], v[156:157] op_sel_hi:[1,0,1] neg_lo:[1,0,0] neg_hi:[1,0,0]
	v_pk_fma_f32 v[156:157], v[182:183], v[128:129], v[156:157] op_sel:[0,1,0] neg_lo:[1,0,0] neg_hi:[1,0,0]
	v_pk_fma_f32 v[156:157], v[184:185], v[130:131], v[156:157] op_sel_hi:[1,0,1] neg_lo:[1,0,0] neg_hi:[1,0,0]
	v_pk_fma_f32 v[156:157], v[186:187], v[130:131], v[156:157] op_sel:[0,1,0] neg_lo:[1,0,0] neg_hi:[1,0,0]
	ds_read_b128 v[180:183], v228 offset:14864
	ds_read_b128 v[184:187], v228 offset:14880
	s_waitcnt lgkmcnt(14)
	v_pk_fma_f32 v[156:157], v[188:189], v[132:133], v[156:157] op_sel_hi:[1,0,1] neg_lo:[1,0,0] neg_hi:[1,0,0]
	v_pk_fma_f32 v[156:157], v[190:191], v[132:133], v[156:157] op_sel:[0,1,0] neg_lo:[1,0,0] neg_hi:[1,0,0]
	v_pk_fma_f32 v[156:157], v[192:193], v[134:135], v[156:157] op_sel_hi:[1,0,1] neg_lo:[1,0,0] neg_hi:[1,0,0]
	v_pk_fma_f32 v[156:157], v[194:195], v[134:135], v[156:157] op_sel:[0,1,0] neg_lo:[1,0,0] neg_hi:[1,0,0]
	ds_read_b128 v[188:191], v228 offset:14896
	ds_read_b128 v[192:195], v228 offset:14912
	s_waitcnt lgkmcnt(14)
	v_pk_fma_f32 v[156:157], v[196:197], v[136:137], v[156:157] op_sel_hi:[1,0,1] neg_lo:[1,0,0] neg_hi:[1,0,0]
	v_pk_fma_f32 v[156:157], v[198:199], v[136:137], v[156:157] op_sel:[0,1,0] neg_lo:[1,0,0] neg_hi:[1,0,0]
	v_pk_fma_f32 v[156:157], v[200:201], v[138:139], v[156:157] op_sel_hi:[1,0,1] neg_lo:[1,0,0] neg_hi:[1,0,0]
	v_pk_fma_f32 v[156:157], v[202:203], v[138:139], v[156:157] op_sel:[0,1,0] neg_lo:[1,0,0] neg_hi:[1,0,0]
	ds_read_b128 v[196:199], v228 offset:14928
	ds_read_b128 v[200:203], v228 offset:14944
	s_waitcnt lgkmcnt(14)
	v_pk_fma_f32 v[156:157], v[204:205], v[140:141], v[156:157] op_sel_hi:[1,0,1] neg_lo:[1,0,0] neg_hi:[1,0,0]
	v_pk_fma_f32 v[156:157], v[206:207], v[140:141], v[156:157] op_sel:[0,1,0] neg_lo:[1,0,0] neg_hi:[1,0,0]
	v_pk_fma_f32 v[156:157], v[208:209], v[142:143], v[156:157] op_sel_hi:[1,0,1] neg_lo:[1,0,0] neg_hi:[1,0,0]
	v_pk_fma_f32 v[156:157], v[210:211], v[142:143], v[156:157] op_sel:[0,1,0] neg_lo:[1,0,0] neg_hi:[1,0,0]
	ds_read_b128 v[204:207], v228 offset:14960
	ds_read_b128 v[208:211], v228 offset:14976
	s_waitcnt lgkmcnt(14)
	v_pk_fma_f32 v[156:157], v[212:213], v[144:145], v[156:157] op_sel_hi:[1,0,1] neg_lo:[1,0,0] neg_hi:[1,0,0]
	v_pk_fma_f32 v[156:157], v[214:215], v[144:145], v[156:157] op_sel:[0,1,0] neg_lo:[1,0,0] neg_hi:[1,0,0]
	v_pk_fma_f32 v[156:157], v[216:217], v[146:147], v[156:157] op_sel_hi:[1,0,1] neg_lo:[1,0,0] neg_hi:[1,0,0]
	v_pk_fma_f32 v[156:157], v[218:219], v[146:147], v[156:157] op_sel:[0,1,0] neg_lo:[1,0,0] neg_hi:[1,0,0]
	ds_read_b128 v[212:215], v228 offset:14992
	ds_read_b128 v[216:219], v228 offset:15008
	s_waitcnt lgkmcnt(14)
	v_pk_fma_f32 v[156:157], v[220:221], v[148:149], v[156:157] op_sel_hi:[1,0,1] neg_lo:[1,0,0] neg_hi:[1,0,0]
	v_pk_fma_f32 v[156:157], v[222:223], v[148:149], v[156:157] op_sel:[0,1,0] neg_lo:[1,0,0] neg_hi:[1,0,0]
	v_pk_fma_f32 v[156:157], v[224:225], v[150:151], v[156:157] op_sel_hi:[1,0,1] neg_lo:[1,0,0] neg_hi:[1,0,0]
	v_pk_fma_f32 v[156:157], v[226:227], v[150:151], v[156:157] op_sel:[0,1,0] neg_lo:[1,0,0] neg_hi:[1,0,0]
	ds_read_b128 v[220:223], v228 offset:15024
	ds_read_b128 v[224:227], v228 offset:15040
	s_waitcnt lgkmcnt(14)
	v_pk_fma_f32 v[156:157], v[164:165], v[152:153], v[156:157] op_sel_hi:[1,0,1] neg_lo:[1,0,0] neg_hi:[1,0,0]
	v_pk_fma_f32 v[156:157], v[166:167], v[152:153], v[156:157] op_sel:[0,1,0] neg_lo:[1,0,0] neg_hi:[1,0,0]
	v_pk_fma_f32 v[156:157], v[168:169], v[154:155], v[156:157] op_sel_hi:[1,0,1] neg_lo:[1,0,0] neg_hi:[1,0,0]
	v_pk_fma_f32 v[156:157], v[170:171], v[154:155], v[156:157] op_sel:[0,1,0] neg_lo:[1,0,0] neg_hi:[1,0,0]
	ds_read_b128 v[164:167], v228 offset:15056
	ds_read_b128 v[168:171], v228 offset:15072
	s_waitcnt lgkmcnt(14)
	v_fma_f32 v157, -v173, v156, v157
	v_pk_fma_f32 v[158:159], v[176:177], v[100:101], v[158:159] op_sel_hi:[1,0,1] neg_lo:[1,0,0] neg_hi:[1,0,0]
	v_pk_fma_f32 v[158:159], v[178:179], v[100:101], v[158:159] op_sel:[0,1,0] neg_lo:[1,0,0] neg_hi:[1,0,0]
	ds_read_b128 v[172:175], v228 offset:15088
	ds_read_b128 v[176:179], v228 offset:15104
	s_waitcnt lgkmcnt(14)
	v_pk_fma_f32 v[158:159], v[180:181], v[102:103], v[158:159] op_sel_hi:[1,0,1] neg_lo:[1,0,0] neg_hi:[1,0,0]
	v_pk_fma_f32 v[158:159], v[182:183], v[102:103], v[158:159] op_sel:[0,1,0] neg_lo:[1,0,0] neg_hi:[1,0,0]
	v_pk_fma_f32 v[158:159], v[184:185], v[104:105], v[158:159] op_sel_hi:[1,0,1] neg_lo:[1,0,0] neg_hi:[1,0,0]
	v_pk_fma_f32 v[158:159], v[186:187], v[104:105], v[158:159] op_sel:[0,1,0] neg_lo:[1,0,0] neg_hi:[1,0,0]
	ds_read_b128 v[180:183], v228 offset:15120
	ds_read_b128 v[184:187], v228 offset:15136
	s_waitcnt lgkmcnt(14)
	v_pk_fma_f32 v[158:159], v[188:189], v[106:107], v[158:159] op_sel_hi:[1,0,1] neg_lo:[1,0,0] neg_hi:[1,0,0]
	v_pk_fma_f32 v[158:159], v[190:191], v[106:107], v[158:159] op_sel:[0,1,0] neg_lo:[1,0,0] neg_hi:[1,0,0]
	v_pk_fma_f32 v[158:159], v[192:193], v[108:109], v[158:159] op_sel_hi:[1,0,1] neg_lo:[1,0,0] neg_hi:[1,0,0]
	v_pk_fma_f32 v[158:159], v[194:195], v[108:109], v[158:159] op_sel:[0,1,0] neg_lo:[1,0,0] neg_hi:[1,0,0]
	ds_read_b128 v[188:191], v228 offset:15152
	ds_read_b128 v[192:195], v228 offset:15168
	s_waitcnt lgkmcnt(14)
	v_pk_fma_f32 v[158:159], v[196:197], v[110:111], v[158:159] op_sel_hi:[1,0,1] neg_lo:[1,0,0] neg_hi:[1,0,0]
	v_pk_fma_f32 v[158:159], v[198:199], v[110:111], v[158:159] op_sel:[0,1,0] neg_lo:[1,0,0] neg_hi:[1,0,0]
	v_pk_fma_f32 v[158:159], v[200:201], v[112:113], v[158:159] op_sel_hi:[1,0,1] neg_lo:[1,0,0] neg_hi:[1,0,0]
	v_pk_fma_f32 v[158:159], v[202:203], v[112:113], v[158:159] op_sel:[0,1,0] neg_lo:[1,0,0] neg_hi:[1,0,0]
	ds_read_b128 v[196:199], v228 offset:15184
	ds_read_b128 v[200:203], v228 offset:15200
	s_waitcnt lgkmcnt(14)
	v_pk_fma_f32 v[158:159], v[204:205], v[114:115], v[158:159] op_sel_hi:[1,0,1] neg_lo:[1,0,0] neg_hi:[1,0,0]
	v_pk_fma_f32 v[158:159], v[206:207], v[114:115], v[158:159] op_sel:[0,1,0] neg_lo:[1,0,0] neg_hi:[1,0,0]
	v_pk_fma_f32 v[158:159], v[208:209], v[116:117], v[158:159] op_sel_hi:[1,0,1] neg_lo:[1,0,0] neg_hi:[1,0,0]
	v_pk_fma_f32 v[158:159], v[210:211], v[116:117], v[158:159] op_sel:[0,1,0] neg_lo:[1,0,0] neg_hi:[1,0,0]
	ds_read_b128 v[204:207], v228 offset:15216
	ds_read_b128 v[208:211], v228 offset:15232
	s_waitcnt lgkmcnt(14)
	v_pk_fma_f32 v[158:159], v[212:213], v[118:119], v[158:159] op_sel_hi:[1,0,1] neg_lo:[1,0,0] neg_hi:[1,0,0]
	v_pk_fma_f32 v[158:159], v[214:215], v[118:119], v[158:159] op_sel:[0,1,0] neg_lo:[1,0,0] neg_hi:[1,0,0]
	v_pk_fma_f32 v[158:159], v[216:217], v[120:121], v[158:159] op_sel_hi:[1,0,1] neg_lo:[1,0,0] neg_hi:[1,0,0]
	v_pk_fma_f32 v[158:159], v[218:219], v[120:121], v[158:159] op_sel:[0,1,0] neg_lo:[1,0,0] neg_hi:[1,0,0]
	ds_read_b128 v[212:215], v228 offset:15248
	ds_read_b128 v[216:219], v228 offset:15264
	s_waitcnt lgkmcnt(14)
	v_pk_fma_f32 v[158:159], v[220:221], v[122:123], v[158:159] op_sel_hi:[1,0,1] neg_lo:[1,0,0] neg_hi:[1,0,0]
	v_pk_fma_f32 v[158:159], v[222:223], v[122:123], v[158:159] op_sel:[0,1,0] neg_lo:[1,0,0] neg_hi:[1,0,0]
	v_pk_fma_f32 v[158:159], v[224:225], v[124:125], v[158:159] op_sel_hi:[1,0,1] neg_lo:[1,0,0] neg_hi:[1,0,0]
	v_pk_fma_f32 v[158:159], v[226:227], v[124:125], v[158:159] op_sel:[0,1,0] neg_lo:[1,0,0] neg_hi:[1,0,0]
	ds_read_b128 v[220:223], v228 offset:15280
	ds_read_b128 v[224:227], v228 offset:15296
	s_waitcnt lgkmcnt(14)
	v_pk_fma_f32 v[158:159], v[164:165], v[126:127], v[158:159] op_sel_hi:[1,0,1] neg_lo:[1,0,0] neg_hi:[1,0,0]
	v_pk_fma_f32 v[158:159], v[166:167], v[126:127], v[158:159] op_sel:[0,1,0] neg_lo:[1,0,0] neg_hi:[1,0,0]
	v_pk_fma_f32 v[158:159], v[168:169], v[128:129], v[158:159] op_sel_hi:[1,0,1] neg_lo:[1,0,0] neg_hi:[1,0,0]
	v_pk_fma_f32 v[158:159], v[170:171], v[128:129], v[158:159] op_sel:[0,1,0] neg_lo:[1,0,0] neg_hi:[1,0,0]
	ds_read_b128 v[164:167], v228 offset:15312
	ds_read_b128 v[168:171], v228 offset:15360
	s_waitcnt lgkmcnt(14)
	v_pk_fma_f32 v[158:159], v[172:173], v[130:131], v[158:159] op_sel_hi:[1,0,1] neg_lo:[1,0,0] neg_hi:[1,0,0]
	v_pk_fma_f32 v[158:159], v[174:175], v[130:131], v[158:159] op_sel:[0,1,0] neg_lo:[1,0,0] neg_hi:[1,0,0]
	v_pk_fma_f32 v[158:159], v[176:177], v[132:133], v[158:159] op_sel_hi:[1,0,1] neg_lo:[1,0,0] neg_hi:[1,0,0]
	v_pk_fma_f32 v[158:159], v[178:179], v[132:133], v[158:159] op_sel:[0,1,0] neg_lo:[1,0,0] neg_hi:[1,0,0]
	ds_read_b128 v[172:175], v228 offset:15376
	ds_read_b128 v[176:179], v228 offset:15392
	s_waitcnt lgkmcnt(14)
	v_pk_fma_f32 v[158:159], v[180:181], v[134:135], v[158:159] op_sel_hi:[1,0,1] neg_lo:[1,0,0] neg_hi:[1,0,0]
	v_pk_fma_f32 v[158:159], v[182:183], v[134:135], v[158:159] op_sel:[0,1,0] neg_lo:[1,0,0] neg_hi:[1,0,0]
	v_pk_fma_f32 v[158:159], v[184:185], v[136:137], v[158:159] op_sel_hi:[1,0,1] neg_lo:[1,0,0] neg_hi:[1,0,0]
	v_pk_fma_f32 v[158:159], v[186:187], v[136:137], v[158:159] op_sel:[0,1,0] neg_lo:[1,0,0] neg_hi:[1,0,0]
	ds_read_b128 v[180:183], v228 offset:15408
	ds_read_b128 v[184:187], v228 offset:15424
	s_waitcnt lgkmcnt(14)
	v_pk_fma_f32 v[158:159], v[188:189], v[138:139], v[158:159] op_sel_hi:[1,0,1] neg_lo:[1,0,0] neg_hi:[1,0,0]
	v_pk_fma_f32 v[158:159], v[190:191], v[138:139], v[158:159] op_sel:[0,1,0] neg_lo:[1,0,0] neg_hi:[1,0,0]
	v_pk_fma_f32 v[158:159], v[192:193], v[140:141], v[158:159] op_sel_hi:[1,0,1] neg_lo:[1,0,0] neg_hi:[1,0,0]
	v_pk_fma_f32 v[158:159], v[194:195], v[140:141], v[158:159] op_sel:[0,1,0] neg_lo:[1,0,0] neg_hi:[1,0,0]
	ds_read_b128 v[188:191], v228 offset:15440
	ds_read_b128 v[192:195], v228 offset:15456
	s_waitcnt lgkmcnt(14)
	v_pk_fma_f32 v[158:159], v[196:197], v[142:143], v[158:159] op_sel_hi:[1,0,1] neg_lo:[1,0,0] neg_hi:[1,0,0]
	v_pk_fma_f32 v[158:159], v[198:199], v[142:143], v[158:159] op_sel:[0,1,0] neg_lo:[1,0,0] neg_hi:[1,0,0]
	v_pk_fma_f32 v[158:159], v[200:201], v[144:145], v[158:159] op_sel_hi:[1,0,1] neg_lo:[1,0,0] neg_hi:[1,0,0]
	v_pk_fma_f32 v[158:159], v[202:203], v[144:145], v[158:159] op_sel:[0,1,0] neg_lo:[1,0,0] neg_hi:[1,0,0]
	ds_read_b128 v[196:199], v228 offset:15472
	ds_read_b128 v[200:203], v228 offset:15488
	s_waitcnt lgkmcnt(14)
	v_pk_fma_f32 v[158:159], v[204:205], v[146:147], v[158:159] op_sel_hi:[1,0,1] neg_lo:[1,0,0] neg_hi:[1,0,0]
	v_pk_fma_f32 v[158:159], v[206:207], v[146:147], v[158:159] op_sel:[0,1,0] neg_lo:[1,0,0] neg_hi:[1,0,0]
	v_pk_fma_f32 v[158:159], v[208:209], v[148:149], v[158:159] op_sel_hi:[1,0,1] neg_lo:[1,0,0] neg_hi:[1,0,0]
	v_pk_fma_f32 v[158:159], v[210:211], v[148:149], v[158:159] op_sel:[0,1,0] neg_lo:[1,0,0] neg_hi:[1,0,0]
	ds_read_b128 v[204:207], v228 offset:15504
	ds_read_b128 v[208:211], v228 offset:15520
	s_waitcnt lgkmcnt(14)
	v_pk_fma_f32 v[158:159], v[212:213], v[150:151], v[158:159] op_sel_hi:[1,0,1] neg_lo:[1,0,0] neg_hi:[1,0,0]
	v_pk_fma_f32 v[158:159], v[214:215], v[150:151], v[158:159] op_sel:[0,1,0] neg_lo:[1,0,0] neg_hi:[1,0,0]
	v_pk_fma_f32 v[158:159], v[216:217], v[152:153], v[158:159] op_sel_hi:[1,0,1] neg_lo:[1,0,0] neg_hi:[1,0,0]
	v_pk_fma_f32 v[158:159], v[218:219], v[152:153], v[158:159] op_sel:[0,1,0] neg_lo:[1,0,0] neg_hi:[1,0,0]
	ds_read_b128 v[212:215], v228 offset:15536
	ds_read_b128 v[216:219], v228 offset:15552
	s_waitcnt lgkmcnt(14)
	v_pk_fma_f32 v[158:159], v[220:221], v[154:155], v[158:159] op_sel_hi:[1,0,1] neg_lo:[1,0,0] neg_hi:[1,0,0]
	v_pk_fma_f32 v[158:159], v[222:223], v[154:155], v[158:159] op_sel:[0,1,0] neg_lo:[1,0,0] neg_hi:[1,0,0]
	v_pk_fma_f32 v[158:159], v[224:225], v[156:157], v[158:159] op_sel_hi:[1,0,1] neg_lo:[1,0,0] neg_hi:[1,0,0]
	v_pk_fma_f32 v[158:159], v[226:227], v[156:157], v[158:159] op_sel:[0,1,0] neg_lo:[1,0,0] neg_hi:[1,0,0]
	ds_read_b128 v[220:223], v228 offset:15568
	ds_read_b128 v[224:227], v228 offset:15584
	s_waitcnt lgkmcnt(14)
	v_fma_f32 v159, -v165, v158, v159
	v_pk_fma_f32 v[160:161], v[168:169], v[100:101], v[160:161] op_sel_hi:[1,0,1] neg_lo:[1,0,0] neg_hi:[1,0,0]
	v_pk_fma_f32 v[160:161], v[170:171], v[100:101], v[160:161] op_sel:[0,1,0] neg_lo:[1,0,0] neg_hi:[1,0,0]
	ds_read_b128 v[164:167], v228 offset:15600
	ds_read_b128 v[168:171], v228 offset:15616
	s_waitcnt lgkmcnt(14)
	v_pk_fma_f32 v[160:161], v[172:173], v[102:103], v[160:161] op_sel_hi:[1,0,1] neg_lo:[1,0,0] neg_hi:[1,0,0]
	v_pk_fma_f32 v[160:161], v[174:175], v[102:103], v[160:161] op_sel:[0,1,0] neg_lo:[1,0,0] neg_hi:[1,0,0]
	v_pk_fma_f32 v[160:161], v[176:177], v[104:105], v[160:161] op_sel_hi:[1,0,1] neg_lo:[1,0,0] neg_hi:[1,0,0]
	v_pk_fma_f32 v[160:161], v[178:179], v[104:105], v[160:161] op_sel:[0,1,0] neg_lo:[1,0,0] neg_hi:[1,0,0]
	ds_read_b128 v[172:175], v228 offset:15632
	ds_read_b128 v[176:179], v228 offset:15648
	s_waitcnt lgkmcnt(14)
	v_pk_fma_f32 v[160:161], v[180:181], v[106:107], v[160:161] op_sel_hi:[1,0,1] neg_lo:[1,0,0] neg_hi:[1,0,0]
	v_pk_fma_f32 v[160:161], v[182:183], v[106:107], v[160:161] op_sel:[0,1,0] neg_lo:[1,0,0] neg_hi:[1,0,0]
	v_pk_fma_f32 v[160:161], v[184:185], v[108:109], v[160:161] op_sel_hi:[1,0,1] neg_lo:[1,0,0] neg_hi:[1,0,0]
	v_pk_fma_f32 v[160:161], v[186:187], v[108:109], v[160:161] op_sel:[0,1,0] neg_lo:[1,0,0] neg_hi:[1,0,0]
	ds_read_b128 v[180:183], v228 offset:15664
	ds_read_b128 v[184:187], v228 offset:15680
	s_waitcnt lgkmcnt(14)
	v_pk_fma_f32 v[160:161], v[188:189], v[110:111], v[160:161] op_sel_hi:[1,0,1] neg_lo:[1,0,0] neg_hi:[1,0,0]
	v_pk_fma_f32 v[160:161], v[190:191], v[110:111], v[160:161] op_sel:[0,1,0] neg_lo:[1,0,0] neg_hi:[1,0,0]
	v_pk_fma_f32 v[160:161], v[192:193], v[112:113], v[160:161] op_sel_hi:[1,0,1] neg_lo:[1,0,0] neg_hi:[1,0,0]
	v_pk_fma_f32 v[160:161], v[194:195], v[112:113], v[160:161] op_sel:[0,1,0] neg_lo:[1,0,0] neg_hi:[1,0,0]
	ds_read_b128 v[188:191], v228 offset:15696
	ds_read_b128 v[192:195], v228 offset:15712
	s_waitcnt lgkmcnt(14)
	v_pk_fma_f32 v[160:161], v[196:197], v[114:115], v[160:161] op_sel_hi:[1,0,1] neg_lo:[1,0,0] neg_hi:[1,0,0]
	v_pk_fma_f32 v[160:161], v[198:199], v[114:115], v[160:161] op_sel:[0,1,0] neg_lo:[1,0,0] neg_hi:[1,0,0]
	v_pk_fma_f32 v[160:161], v[200:201], v[116:117], v[160:161] op_sel_hi:[1,0,1] neg_lo:[1,0,0] neg_hi:[1,0,0]
	v_pk_fma_f32 v[160:161], v[202:203], v[116:117], v[160:161] op_sel:[0,1,0] neg_lo:[1,0,0] neg_hi:[1,0,0]
	ds_read_b128 v[196:199], v228 offset:15728
	ds_read_b128 v[200:203], v228 offset:15744
	s_waitcnt lgkmcnt(14)
	v_pk_fma_f32 v[160:161], v[204:205], v[118:119], v[160:161] op_sel_hi:[1,0,1] neg_lo:[1,0,0] neg_hi:[1,0,0]
	v_pk_fma_f32 v[160:161], v[206:207], v[118:119], v[160:161] op_sel:[0,1,0] neg_lo:[1,0,0] neg_hi:[1,0,0]
	v_pk_fma_f32 v[160:161], v[208:209], v[120:121], v[160:161] op_sel_hi:[1,0,1] neg_lo:[1,0,0] neg_hi:[1,0,0]
	v_pk_fma_f32 v[160:161], v[210:211], v[120:121], v[160:161] op_sel:[0,1,0] neg_lo:[1,0,0] neg_hi:[1,0,0]
	ds_read_b128 v[204:207], v228 offset:15760
	ds_read_b128 v[208:211], v228 offset:15776
	s_waitcnt lgkmcnt(14)
	v_pk_fma_f32 v[160:161], v[212:213], v[122:123], v[160:161] op_sel_hi:[1,0,1] neg_lo:[1,0,0] neg_hi:[1,0,0]
	v_pk_fma_f32 v[160:161], v[214:215], v[122:123], v[160:161] op_sel:[0,1,0] neg_lo:[1,0,0] neg_hi:[1,0,0]
	v_pk_fma_f32 v[160:161], v[216:217], v[124:125], v[160:161] op_sel_hi:[1,0,1] neg_lo:[1,0,0] neg_hi:[1,0,0]
	v_pk_fma_f32 v[160:161], v[218:219], v[124:125], v[160:161] op_sel:[0,1,0] neg_lo:[1,0,0] neg_hi:[1,0,0]
	ds_read_b128 v[212:215], v228 offset:15792
	ds_read_b128 v[216:219], v228 offset:15808
	s_waitcnt lgkmcnt(14)
	v_pk_fma_f32 v[160:161], v[220:221], v[126:127], v[160:161] op_sel_hi:[1,0,1] neg_lo:[1,0,0] neg_hi:[1,0,0]
	v_pk_fma_f32 v[160:161], v[222:223], v[126:127], v[160:161] op_sel:[0,1,0] neg_lo:[1,0,0] neg_hi:[1,0,0]
	v_pk_fma_f32 v[160:161], v[224:225], v[128:129], v[160:161] op_sel_hi:[1,0,1] neg_lo:[1,0,0] neg_hi:[1,0,0]
	v_pk_fma_f32 v[160:161], v[226:227], v[128:129], v[160:161] op_sel:[0,1,0] neg_lo:[1,0,0] neg_hi:[1,0,0]
	ds_read_b128 v[220:223], v228 offset:15824
	ds_read_b128 v[224:227], v228 offset:15840
	s_waitcnt lgkmcnt(14)
	v_pk_fma_f32 v[160:161], v[164:165], v[130:131], v[160:161] op_sel_hi:[1,0,1] neg_lo:[1,0,0] neg_hi:[1,0,0]
	v_pk_fma_f32 v[160:161], v[166:167], v[130:131], v[160:161] op_sel:[0,1,0] neg_lo:[1,0,0] neg_hi:[1,0,0]
	v_pk_fma_f32 v[160:161], v[168:169], v[132:133], v[160:161] op_sel_hi:[1,0,1] neg_lo:[1,0,0] neg_hi:[1,0,0]
	v_pk_fma_f32 v[160:161], v[170:171], v[132:133], v[160:161] op_sel:[0,1,0] neg_lo:[1,0,0] neg_hi:[1,0,0]
	ds_read_b128 v[164:167], v228 offset:15872
	ds_read_b128 v[168:171], v228 offset:15888
	s_waitcnt lgkmcnt(14)
	v_pk_fma_f32 v[160:161], v[172:173], v[134:135], v[160:161] op_sel_hi:[1,0,1] neg_lo:[1,0,0] neg_hi:[1,0,0]
	v_pk_fma_f32 v[160:161], v[174:175], v[134:135], v[160:161] op_sel:[0,1,0] neg_lo:[1,0,0] neg_hi:[1,0,0]
	v_pk_fma_f32 v[160:161], v[176:177], v[136:137], v[160:161] op_sel_hi:[1,0,1] neg_lo:[1,0,0] neg_hi:[1,0,0]
	v_pk_fma_f32 v[160:161], v[178:179], v[136:137], v[160:161] op_sel:[0,1,0] neg_lo:[1,0,0] neg_hi:[1,0,0]
	ds_read_b128 v[172:175], v228 offset:15904
	ds_read_b128 v[176:179], v228 offset:15920
	s_waitcnt lgkmcnt(14)
	v_pk_fma_f32 v[160:161], v[180:181], v[138:139], v[160:161] op_sel_hi:[1,0,1] neg_lo:[1,0,0] neg_hi:[1,0,0]
	v_pk_fma_f32 v[160:161], v[182:183], v[138:139], v[160:161] op_sel:[0,1,0] neg_lo:[1,0,0] neg_hi:[1,0,0]
	v_pk_fma_f32 v[160:161], v[184:185], v[140:141], v[160:161] op_sel_hi:[1,0,1] neg_lo:[1,0,0] neg_hi:[1,0,0]
	v_pk_fma_f32 v[160:161], v[186:187], v[140:141], v[160:161] op_sel:[0,1,0] neg_lo:[1,0,0] neg_hi:[1,0,0]
	ds_read_b128 v[180:183], v228 offset:15936
	ds_read_b128 v[184:187], v228 offset:15952
	s_waitcnt lgkmcnt(14)
	v_pk_fma_f32 v[160:161], v[188:189], v[142:143], v[160:161] op_sel_hi:[1,0,1] neg_lo:[1,0,0] neg_hi:[1,0,0]
	v_pk_fma_f32 v[160:161], v[190:191], v[142:143], v[160:161] op_sel:[0,1,0] neg_lo:[1,0,0] neg_hi:[1,0,0]
	v_pk_fma_f32 v[160:161], v[192:193], v[144:145], v[160:161] op_sel_hi:[1,0,1] neg_lo:[1,0,0] neg_hi:[1,0,0]
	v_pk_fma_f32 v[160:161], v[194:195], v[144:145], v[160:161] op_sel:[0,1,0] neg_lo:[1,0,0] neg_hi:[1,0,0]
	ds_read_b128 v[188:191], v228 offset:15968
	ds_read_b128 v[192:195], v228 offset:15984
	s_waitcnt lgkmcnt(14)
	v_pk_fma_f32 v[160:161], v[196:197], v[146:147], v[160:161] op_sel_hi:[1,0,1] neg_lo:[1,0,0] neg_hi:[1,0,0]
	v_pk_fma_f32 v[160:161], v[198:199], v[146:147], v[160:161] op_sel:[0,1,0] neg_lo:[1,0,0] neg_hi:[1,0,0]
	v_pk_fma_f32 v[160:161], v[200:201], v[148:149], v[160:161] op_sel_hi:[1,0,1] neg_lo:[1,0,0] neg_hi:[1,0,0]
	v_pk_fma_f32 v[160:161], v[202:203], v[148:149], v[160:161] op_sel:[0,1,0] neg_lo:[1,0,0] neg_hi:[1,0,0]
	ds_read_b128 v[196:199], v228 offset:16000
	ds_read_b128 v[200:203], v228 offset:16016
	s_waitcnt lgkmcnt(14)
	v_pk_fma_f32 v[160:161], v[204:205], v[150:151], v[160:161] op_sel_hi:[1,0,1] neg_lo:[1,0,0] neg_hi:[1,0,0]
	v_pk_fma_f32 v[160:161], v[206:207], v[150:151], v[160:161] op_sel:[0,1,0] neg_lo:[1,0,0] neg_hi:[1,0,0]
	v_pk_fma_f32 v[160:161], v[208:209], v[152:153], v[160:161] op_sel_hi:[1,0,1] neg_lo:[1,0,0] neg_hi:[1,0,0]
	v_pk_fma_f32 v[160:161], v[210:211], v[152:153], v[160:161] op_sel:[0,1,0] neg_lo:[1,0,0] neg_hi:[1,0,0]
	ds_read_b128 v[204:207], v228 offset:16032
	ds_read_b128 v[208:211], v228 offset:16048
	s_waitcnt lgkmcnt(14)
	v_pk_fma_f32 v[160:161], v[212:213], v[154:155], v[160:161] op_sel_hi:[1,0,1] neg_lo:[1,0,0] neg_hi:[1,0,0]
	v_pk_fma_f32 v[160:161], v[214:215], v[154:155], v[160:161] op_sel:[0,1,0] neg_lo:[1,0,0] neg_hi:[1,0,0]
	v_pk_fma_f32 v[160:161], v[216:217], v[156:157], v[160:161] op_sel_hi:[1,0,1] neg_lo:[1,0,0] neg_hi:[1,0,0]
	v_pk_fma_f32 v[160:161], v[218:219], v[156:157], v[160:161] op_sel:[0,1,0] neg_lo:[1,0,0] neg_hi:[1,0,0]
	ds_read_b128 v[212:215], v228 offset:16064
	ds_read_b128 v[216:219], v228 offset:16080
	s_waitcnt lgkmcnt(14)
	v_pk_fma_f32 v[160:161], v[220:221], v[158:159], v[160:161] op_sel_hi:[1,0,1] neg_lo:[1,0,0] neg_hi:[1,0,0]
	v_pk_fma_f32 v[160:161], v[222:223], v[158:159], v[160:161] op_sel:[0,1,0] neg_lo:[1,0,0] neg_hi:[1,0,0]
	v_fma_f32 v161, -v225, v160, v161
	ds_read_b128 v[220:223], v228 offset:16096
	ds_read_b128 v[224:227], v228 offset:16112
	s_waitcnt lgkmcnt(14)
	v_pk_fma_f32 v[162:163], v[164:165], v[100:101], v[162:163] op_sel_hi:[1,0,1] neg_lo:[1,0,0] neg_hi:[1,0,0]
	v_pk_fma_f32 v[162:163], v[166:167], v[100:101], v[162:163] op_sel:[0,1,0] neg_lo:[1,0,0] neg_hi:[1,0,0]
	v_pk_fma_f32 v[162:163], v[168:169], v[102:103], v[162:163] op_sel_hi:[1,0,1] neg_lo:[1,0,0] neg_hi:[1,0,0]
	v_pk_fma_f32 v[162:163], v[170:171], v[102:103], v[162:163] op_sel:[0,1,0] neg_lo:[1,0,0] neg_hi:[1,0,0]
	ds_read_b128 v[164:167], v228 offset:16128
	ds_read_b128 v[168:171], v228 offset:16144
	s_waitcnt lgkmcnt(14)
	v_pk_fma_f32 v[162:163], v[172:173], v[104:105], v[162:163] op_sel_hi:[1,0,1] neg_lo:[1,0,0] neg_hi:[1,0,0]
	v_pk_fma_f32 v[162:163], v[174:175], v[104:105], v[162:163] op_sel:[0,1,0] neg_lo:[1,0,0] neg_hi:[1,0,0]
	v_pk_fma_f32 v[162:163], v[176:177], v[106:107], v[162:163] op_sel_hi:[1,0,1] neg_lo:[1,0,0] neg_hi:[1,0,0]
	v_pk_fma_f32 v[162:163], v[178:179], v[106:107], v[162:163] op_sel:[0,1,0] neg_lo:[1,0,0] neg_hi:[1,0,0]
	ds_read_b128 v[172:175], v228 offset:16160
	ds_read_b128 v[176:179], v228 offset:16176
	s_waitcnt lgkmcnt(14)
	v_pk_fma_f32 v[162:163], v[180:181], v[108:109], v[162:163] op_sel_hi:[1,0,1] neg_lo:[1,0,0] neg_hi:[1,0,0]
	v_pk_fma_f32 v[162:163], v[182:183], v[108:109], v[162:163] op_sel:[0,1,0] neg_lo:[1,0,0] neg_hi:[1,0,0]
	v_pk_fma_f32 v[162:163], v[184:185], v[110:111], v[162:163] op_sel_hi:[1,0,1] neg_lo:[1,0,0] neg_hi:[1,0,0]
	v_pk_fma_f32 v[162:163], v[186:187], v[110:111], v[162:163] op_sel:[0,1,0] neg_lo:[1,0,0] neg_hi:[1,0,0]
	ds_read_b128 v[180:183], v228 offset:16192
	ds_read_b128 v[184:187], v228 offset:16208
	s_waitcnt lgkmcnt(14)
	v_pk_fma_f32 v[162:163], v[188:189], v[112:113], v[162:163] op_sel_hi:[1,0,1] neg_lo:[1,0,0] neg_hi:[1,0,0]
	v_pk_fma_f32 v[162:163], v[190:191], v[112:113], v[162:163] op_sel:[0,1,0] neg_lo:[1,0,0] neg_hi:[1,0,0]
	v_pk_fma_f32 v[162:163], v[192:193], v[114:115], v[162:163] op_sel_hi:[1,0,1] neg_lo:[1,0,0] neg_hi:[1,0,0]
	v_pk_fma_f32 v[162:163], v[194:195], v[114:115], v[162:163] op_sel:[0,1,0] neg_lo:[1,0,0] neg_hi:[1,0,0]
	ds_read_b128 v[188:191], v228 offset:16224
	ds_read_b128 v[192:195], v228 offset:16240
	s_waitcnt lgkmcnt(14)
	v_pk_fma_f32 v[162:163], v[196:197], v[116:117], v[162:163] op_sel_hi:[1,0,1] neg_lo:[1,0,0] neg_hi:[1,0,0]
	v_pk_fma_f32 v[162:163], v[198:199], v[116:117], v[162:163] op_sel:[0,1,0] neg_lo:[1,0,0] neg_hi:[1,0,0]
	v_pk_fma_f32 v[162:163], v[200:201], v[118:119], v[162:163] op_sel_hi:[1,0,1] neg_lo:[1,0,0] neg_hi:[1,0,0]
	v_pk_fma_f32 v[162:163], v[202:203], v[118:119], v[162:163] op_sel:[0,1,0] neg_lo:[1,0,0] neg_hi:[1,0,0]
	ds_read_b128 v[196:199], v228 offset:16256
	ds_read_b128 v[200:203], v228 offset:16272
	s_waitcnt lgkmcnt(14)
	v_pk_fma_f32 v[162:163], v[204:205], v[120:121], v[162:163] op_sel_hi:[1,0,1] neg_lo:[1,0,0] neg_hi:[1,0,0]
	v_pk_fma_f32 v[162:163], v[206:207], v[120:121], v[162:163] op_sel:[0,1,0] neg_lo:[1,0,0] neg_hi:[1,0,0]
	v_pk_fma_f32 v[162:163], v[208:209], v[122:123], v[162:163] op_sel_hi:[1,0,1] neg_lo:[1,0,0] neg_hi:[1,0,0]
	v_pk_fma_f32 v[162:163], v[210:211], v[122:123], v[162:163] op_sel:[0,1,0] neg_lo:[1,0,0] neg_hi:[1,0,0]
	ds_read_b128 v[204:207], v228 offset:16288
	ds_read_b128 v[208:211], v228 offset:16304
	s_waitcnt lgkmcnt(14)
	v_pk_fma_f32 v[162:163], v[212:213], v[124:125], v[162:163] op_sel_hi:[1,0,1] neg_lo:[1,0,0] neg_hi:[1,0,0]
	v_pk_fma_f32 v[162:163], v[214:215], v[124:125], v[162:163] op_sel:[0,1,0] neg_lo:[1,0,0] neg_hi:[1,0,0]
	v_pk_fma_f32 v[162:163], v[216:217], v[126:127], v[162:163] op_sel_hi:[1,0,1] neg_lo:[1,0,0] neg_hi:[1,0,0]
	v_pk_fma_f32 v[162:163], v[218:219], v[126:127], v[162:163] op_sel:[0,1,0] neg_lo:[1,0,0] neg_hi:[1,0,0]
	ds_read_b128 v[212:215], v228 offset:16320
	ds_read_b128 v[216:219], v228 offset:16336
	s_waitcnt lgkmcnt(14)
	v_pk_fma_f32 v[162:163], v[220:221], v[128:129], v[162:163] op_sel_hi:[1,0,1] neg_lo:[1,0,0] neg_hi:[1,0,0]
	v_pk_fma_f32 v[162:163], v[222:223], v[128:129], v[162:163] op_sel:[0,1,0] neg_lo:[1,0,0] neg_hi:[1,0,0]
	v_pk_fma_f32 v[162:163], v[224:225], v[130:131], v[162:163] op_sel_hi:[1,0,1] neg_lo:[1,0,0] neg_hi:[1,0,0]
	v_pk_fma_f32 v[162:163], v[226:227], v[130:131], v[162:163] op_sel:[0,1,0] neg_lo:[1,0,0] neg_hi:[1,0,0]
	ds_read_b128 v[220:223], v228 offset:16352
	ds_read_b128 v[224:227], v228 offset:16368
	s_waitcnt lgkmcnt(14)
	v_pk_fma_f32 v[162:163], v[164:165], v[132:133], v[162:163] op_sel_hi:[1,0,1] neg_lo:[1,0,0] neg_hi:[1,0,0]
	v_pk_fma_f32 v[162:163], v[166:167], v[132:133], v[162:163] op_sel:[0,1,0] neg_lo:[1,0,0] neg_hi:[1,0,0]
	v_pk_fma_f32 v[162:163], v[168:169], v[134:135], v[162:163] op_sel_hi:[1,0,1] neg_lo:[1,0,0] neg_hi:[1,0,0]
	v_pk_fma_f32 v[162:163], v[170:171], v[134:135], v[162:163] op_sel:[0,1,0] neg_lo:[1,0,0] neg_hi:[1,0,0]
	s_waitcnt lgkmcnt(12)
	v_pk_fma_f32 v[162:163], v[172:173], v[136:137], v[162:163] op_sel_hi:[1,0,1] neg_lo:[1,0,0] neg_hi:[1,0,0]
	v_pk_fma_f32 v[162:163], v[174:175], v[136:137], v[162:163] op_sel:[0,1,0] neg_lo:[1,0,0] neg_hi:[1,0,0]
	v_pk_fma_f32 v[162:163], v[176:177], v[138:139], v[162:163] op_sel_hi:[1,0,1] neg_lo:[1,0,0] neg_hi:[1,0,0]
	v_pk_fma_f32 v[162:163], v[178:179], v[138:139], v[162:163] op_sel:[0,1,0] neg_lo:[1,0,0] neg_hi:[1,0,0]
	s_waitcnt lgkmcnt(10)
	v_pk_fma_f32 v[162:163], v[180:181], v[140:141], v[162:163] op_sel_hi:[1,0,1] neg_lo:[1,0,0] neg_hi:[1,0,0]
	v_pk_fma_f32 v[162:163], v[182:183], v[140:141], v[162:163] op_sel:[0,1,0] neg_lo:[1,0,0] neg_hi:[1,0,0]
	v_pk_fma_f32 v[162:163], v[184:185], v[142:143], v[162:163] op_sel_hi:[1,0,1] neg_lo:[1,0,0] neg_hi:[1,0,0]
	v_pk_fma_f32 v[162:163], v[186:187], v[142:143], v[162:163] op_sel:[0,1,0] neg_lo:[1,0,0] neg_hi:[1,0,0]
	s_waitcnt lgkmcnt(8)
	v_pk_fma_f32 v[162:163], v[188:189], v[144:145], v[162:163] op_sel_hi:[1,0,1] neg_lo:[1,0,0] neg_hi:[1,0,0]
	v_pk_fma_f32 v[162:163], v[190:191], v[144:145], v[162:163] op_sel:[0,1,0] neg_lo:[1,0,0] neg_hi:[1,0,0]
	v_pk_fma_f32 v[162:163], v[192:193], v[146:147], v[162:163] op_sel_hi:[1,0,1] neg_lo:[1,0,0] neg_hi:[1,0,0]
	v_pk_fma_f32 v[162:163], v[194:195], v[146:147], v[162:163] op_sel:[0,1,0] neg_lo:[1,0,0] neg_hi:[1,0,0]
	s_waitcnt lgkmcnt(6)
	v_pk_fma_f32 v[162:163], v[196:197], v[148:149], v[162:163] op_sel_hi:[1,0,1] neg_lo:[1,0,0] neg_hi:[1,0,0]
	v_pk_fma_f32 v[162:163], v[198:199], v[148:149], v[162:163] op_sel:[0,1,0] neg_lo:[1,0,0] neg_hi:[1,0,0]
	v_pk_fma_f32 v[162:163], v[200:201], v[150:151], v[162:163] op_sel_hi:[1,0,1] neg_lo:[1,0,0] neg_hi:[1,0,0]
	v_pk_fma_f32 v[162:163], v[202:203], v[150:151], v[162:163] op_sel:[0,1,0] neg_lo:[1,0,0] neg_hi:[1,0,0]
	s_waitcnt lgkmcnt(4)
	v_pk_fma_f32 v[162:163], v[204:205], v[152:153], v[162:163] op_sel_hi:[1,0,1] neg_lo:[1,0,0] neg_hi:[1,0,0]
	v_pk_fma_f32 v[162:163], v[206:207], v[152:153], v[162:163] op_sel:[0,1,0] neg_lo:[1,0,0] neg_hi:[1,0,0]
	v_pk_fma_f32 v[162:163], v[208:209], v[154:155], v[162:163] op_sel_hi:[1,0,1] neg_lo:[1,0,0] neg_hi:[1,0,0]
	v_pk_fma_f32 v[162:163], v[210:211], v[154:155], v[162:163] op_sel:[0,1,0] neg_lo:[1,0,0] neg_hi:[1,0,0]
	s_waitcnt lgkmcnt(2)
	v_pk_fma_f32 v[162:163], v[212:213], v[156:157], v[162:163] op_sel_hi:[1,0,1] neg_lo:[1,0,0] neg_hi:[1,0,0]
	v_pk_fma_f32 v[162:163], v[214:215], v[156:157], v[162:163] op_sel:[0,1,0] neg_lo:[1,0,0] neg_hi:[1,0,0]
	v_pk_fma_f32 v[162:163], v[216:217], v[158:159], v[162:163] op_sel_hi:[1,0,1] neg_lo:[1,0,0] neg_hi:[1,0,0]
	v_pk_fma_f32 v[162:163], v[218:219], v[158:159], v[162:163] op_sel:[0,1,0] neg_lo:[1,0,0] neg_hi:[1,0,0]
	s_waitcnt lgkmcnt(0)
	v_pk_fma_f32 v[162:163], v[220:221], v[160:161], v[162:163] op_sel_hi:[1,0,1] neg_lo:[1,0,0] neg_hi:[1,0,0]
	v_pk_fma_f32 v[162:163], v[222:223], v[160:161], v[162:163] op_sel:[0,1,0] neg_lo:[1,0,0] neg_hi:[1,0,0]
	v_fma_f32 v163, -v225, v162, v163
	v_cvt_pk_bf16_f32 v35, v102, v103
	v_cvt_pk_bf16_f32 v34, v100, v101
	v_cvt_pk_bf16_f32 v32, v104, v105
	v_cvt_pk_bf16_f32 v33, v106, v107
	v_cvt_pk_bf16_f32 v30, v108, v109
	v_cvt_pk_bf16_f32 v31, v110, v111
	v_cvt_pk_bf16_f32 v28, v112, v113
	v_cvt_pk_bf16_f32 v29, v114, v115
	v_cvt_pk_bf16_f32 v26, v116, v117
	v_cvt_pk_bf16_f32 v27, v118, v119
	v_cvt_pk_bf16_f32 v24, v120, v121
	v_cvt_pk_bf16_f32 v25, v122, v123
	v_cvt_pk_bf16_f32 v18, v124, v125
	v_cvt_pk_bf16_f32 v19, v126, v127
	v_cvt_pk_bf16_f32 v16, v128, v129
	v_cvt_pk_bf16_f32 v17, v130, v131
	v_cvt_pk_bf16_f32 v14, v132, v133
	v_cvt_pk_bf16_f32 v15, v134, v135
	v_cvt_pk_bf16_f32 v12, v136, v137
	v_cvt_pk_bf16_f32 v13, v138, v139
	v_cvt_pk_bf16_f32 v10, v140, v141
	v_cvt_pk_bf16_f32 v11, v142, v143
	v_cvt_pk_bf16_f32 v8, v144, v145
	v_cvt_pk_bf16_f32 v9, v146, v147
	v_cvt_pk_bf16_f32 v6, v148, v149
	v_cvt_pk_bf16_f32 v7, v150, v151
	v_cvt_pk_bf16_f32 v4, v152, v153
	v_cvt_pk_bf16_f32 v5, v154, v155
	v_cvt_pk_bf16_f32 v2, v156, v157
	v_cvt_pk_bf16_f32 v3, v158, v159
	v_cvt_pk_bf16_f32 v0, v160, v161
	v_cvt_pk_bf16_f32 v1, v162, v163
	s_and_saveexec_b64 s[0:1], vcc
	s_xor_b64 s[0:1], exec, s[0:1]
	s_cbranch_execz .LBB0_419
	v_and_b32_e32 v39, 0x7ffffff0, v39
	v_lshlrev_b32_e32 v39, 1, v39
	v_lshlrev_b32_e32 v22, 1, v22
	v_add3_u32 v22, 0, v39, v22
	v_lshlrev_b32_e32 v39, 2, v77
	v_lshlrev_b32_e32 v38, 1, v38
	v_and_b32_e32 v39, 16, v39
	v_add3_u32 v22, v22, v38, v39
	ds_write_b16 v22, v34
	ds_write_b16_d16_hi v22, v34 offset:272
	ds_write_b16 v22, v35 offset:544
	ds_write_b16_d16_hi v22, v35 offset:816
	ds_write_b16 v22, v32 offset:1088
	ds_write_b16_d16_hi v22, v32 offset:1360
	ds_write_b16 v22, v33 offset:1632
	ds_write_b16_d16_hi v22, v33 offset:1904
	ds_write_b16 v22, v30 offset:2176
	ds_write_b16_d16_hi v22, v30 offset:2448
	ds_write_b16 v22, v31 offset:2720
	ds_write_b16_d16_hi v22, v31 offset:2992
	ds_write_b16 v22, v28 offset:3264
	ds_write_b16_d16_hi v22, v28 offset:3536
	ds_write_b16 v22, v29 offset:3808
	ds_write_b16_d16_hi v22, v29 offset:4080
	ds_write_b16 v22, v26 offset:4352
	ds_write_b16_d16_hi v22, v26 offset:4624
	ds_write_b16 v22, v27 offset:4896
	ds_write_b16_d16_hi v22, v27 offset:5168
	ds_write_b16 v22, v24 offset:5440
	ds_write_b16_d16_hi v22, v24 offset:5712
	ds_write_b16 v22, v25 offset:5984
	ds_write_b16_d16_hi v22, v25 offset:6256
	ds_write_b16 v22, v18 offset:6528
	ds_write_b16_d16_hi v22, v18 offset:6800
	ds_write_b16 v22, v19 offset:7072
	ds_write_b16_d16_hi v22, v19 offset:7344
	ds_write_b16 v22, v16 offset:7616
	ds_write_b16_d16_hi v22, v16 offset:7888
	ds_write_b16 v22, v17 offset:8160
	ds_write_b16_d16_hi v22, v17 offset:8432
	ds_write_b16 v22, v14 offset:8704
	ds_write_b16_d16_hi v22, v14 offset:8976
	ds_write_b16 v22, v15 offset:9248
	ds_write_b16_d16_hi v22, v15 offset:9520
	ds_write_b16 v22, v12 offset:9792
	ds_write_b16_d16_hi v22, v12 offset:10064
	ds_write_b16 v22, v13 offset:10336
	ds_write_b16_d16_hi v22, v13 offset:10608
	ds_write_b16 v22, v10 offset:10880
	ds_write_b16_d16_hi v22, v10 offset:11152
	ds_write_b16 v22, v11 offset:11424
	ds_write_b16_d16_hi v22, v11 offset:11696
	ds_write_b16 v22, v8 offset:11968
	ds_write_b16_d16_hi v22, v8 offset:12240
	ds_write_b16 v22, v9 offset:12512
	ds_write_b16_d16_hi v22, v9 offset:12784
	ds_write_b16 v22, v6 offset:13056
	ds_write_b16_d16_hi v22, v6 offset:13328
	ds_write_b16 v22, v7 offset:13600
	ds_write_b16_d16_hi v22, v7 offset:13872
	ds_write_b16 v22, v4 offset:14144
	ds_write_b16_d16_hi v22, v4 offset:14416
	ds_write_b16 v22, v5 offset:14688
	ds_write_b16_d16_hi v22, v5 offset:14960
	ds_write_b16 v22, v2 offset:15232
	ds_write_b16_d16_hi v22, v2 offset:15504
	ds_write_b16 v22, v3 offset:15776
	ds_write_b16_d16_hi v22, v3 offset:16048
	ds_write_b16 v22, v0 offset:16320
	ds_write_b16_d16_hi v22, v0 offset:16592
	ds_write_b16 v22, v1 offset:16864
	ds_write_b16_d16_hi v22, v1 offset:17136

	.amdhsa_kernel _Z14fwd_megakernel4Args
		.amdhsa_group_segment_fixed_size 0
		.amdhsa_private_segment_fixed_size 0
		.amdhsa_kernarg_size 408
		.amdhsa_user_sgpr_count 2
		.amdhsa_user_sgpr_dispatch_ptr 0
		.amdhsa_user_sgpr_queue_ptr 0
		.amdhsa_user_sgpr_kernarg_segment_ptr 1
		.amdhsa_user_sgpr_dispatch_id 0
		.amdhsa_user_sgpr_kernarg_preload_length 0
		.amdhsa_user_sgpr_kernarg_preload_offset 0
		.amdhsa_user_sgpr_private_segment_size 0
		.amdhsa_uses_dynamic_stack 0
		.amdhsa_enable_private_segment 0
		.amdhsa_system_sgpr_workgroup_id_x 1
		.amdhsa_system_sgpr_workgroup_id_y 0
		.amdhsa_system_sgpr_workgroup_id_z 0
		.amdhsa_system_sgpr_workgroup_info 0
		.amdhsa_system_vgpr_workitem_id 2
		.amdhsa_next_free_vgpr 248
		.amdhsa_next_free_sgpr 101
		.amdhsa_accum_offset 248
		.amdhsa_reserve_vcc 1
		.amdhsa_float_round_mode_32 0
		.amdhsa_float_round_mode_16_64 0
		.amdhsa_float_denorm_mode_32 3
		.amdhsa_float_denorm_mode_16_64 3
		.amdhsa_dx10_clamp 1
		.amdhsa_ieee_mode 1
		.amdhsa_fp16_overflow 0
		.amdhsa_tg_split 0
		.amdhsa_exception_fp_ieee_invalid_op 0
		.amdhsa_exception_fp_denorm_src 0
		.amdhsa_exception_fp_ieee_div_zero 0
		.amdhsa_exception_fp_ieee_overflow 0
		.amdhsa_exception_fp_ieee_underflow 0
		.amdhsa_exception_fp_ieee_inexact 0
		.amdhsa_exception_int_div_zero 0
	.end_amdhsa_kernel

amdhsa.kernels:
  - .agpr_count:     0
    .args:
      - .offset:         0
        .size:           152
        .value_kind:     by_value
      - .offset:         152
        .size:           4
        .value_kind:     hidden_block_count_x
      - .offset:         156
        .size:           4
        .value_kind:     hidden_block_count_y
      - .offset:         160
        .size:           4
        .value_kind:     hidden_block_count_z
      - .offset:         164
        .size:           2
        .value_kind:     hidden_group_size_x
      - .offset:         166
        .size:           2
        .value_kind:     hidden_group_size_y
      - .offset:         168
        .size:           2
        .value_kind:     hidden_group_size_z
      - .offset:         170
        .size:           2
        .value_kind:     hidden_remainder_x
      - .offset:         172
        .size:           2
        .value_kind:     hidden_remainder_y
      - .offset:         174
        .size:           2
        .value_kind:     hidden_remainder_z
      - .offset:         192
        .size:           8
        .value_kind:     hidden_global_offset_x
      - .offset:         200
        .size:           8
        .value_kind:     hidden_global_offset_y
      - .offset:         208
        .size:           8
        .value_kind:     hidden_global_offset_z
      - .offset:         216
        .size:           2
        .value_kind:     hidden_grid_dims
      - .offset:         240
        .size:           8
        .value_kind:     hidden_multigrid_sync_arg
      - .offset:         272
        .size:           4
        .value_kind:     hidden_dynamic_lds_size
    .group_segment_fixed_size: 0
    .kernarg_segment_align: 8
    .kernarg_segment_size: 408
    .language:       OpenCL C
    .language_version:
      - 2
      - 0
    .max_flat_workgroup_size: 512
    .name:           _Z14fwd_megakernel4Args
    .private_segment_fixed_size: 0
    .sgpr_count:     107
    .sgpr_spill_count: 4
    .symbol:         _Z14fwd_megakernel4Args.kd
    .uniform_work_group_size: 1
    .uses_dynamic_stack: false
    .vgpr_count:     248
    .vgpr_spill_count: 0
    .wavefront_size: 64
